# speedup vs baseline: 1.1219x; 1.0180x over previous
; __device__ __forceinline__ int tid_opaque() { int t = threadIdx.x; asm volatile("" : "+v"(t)); return t; }
; __device__ __forceinline__ void phase_peer_v(const Params& p, int layer, int xs, int wid0, int wstride, bool last, char* smraw) {
;   const int tid = tid_opaque(), w = tid >> 6, l = tid & 63, g = l >> 3, j = l & 7;
;   const int wid = wid0 + w;
;   const int sl = xs >> 1, par = xs & 1;
;   constexpr int TH = T / 2;
;   float* red = (float*)smraw + w * 2048;
;   const unsigned char* Vq = p.Vq + (size_t)(layer * 4 + sl) * NEXP * 128;
;   const unsigned joff = j * 16;
;   u32x4 ni[4]; f32x4 nc[4];
;   auto load_idx = [&](int tt) {
;     const unsigned o = (unsigned)(2 * tt + par) * 512u + (unsigned)g * 64u;
;     const u32x4* ip = (const u32x4*)((const char*)p.sel_idx + o);
;     const f32x4* cp = (const f32x4*)((const char*)p.coef + o);
; #pragma unroll
;     for (int q4 = 0; q4 < 4; ++q4) { ni[q4] = ip[q4]; nc[q4] = cp[q4]; }
;   };
;   u32x4 qA[8];
;   float acc[32];
;   auto half_fma = [&](const u32x4 (&q)[8], const f32x4& c0, const f32x4& c1) {
; #pragma unroll
;     for (int i = 0; i < 8; ++i) {
;       const float ci = i < 4 ? c0[i & 3] : c1[i & 3];
; #pragma unroll
;       for (int m = 0; m < 4; ++m) {
;         unsigned dw = q[i][m];
;         asm volatile("" : "+v"(dw) : "v"(acc[(8 * m + 31) & 31]));
;         const f32x2 e0 = __builtin_amdgcn_cvt_scalef32_pk_f32_fp4(dw, 1.0f, 0), e1 = __builtin_amdgcn_cvt_scalef32_pk_f32_fp4(dw, 1.0f, 1);
;         const f32x2 e2 = __builtin_amdgcn_cvt_scalef32_pk_f32_fp4(dw, 1.0f, 2), e3 = __builtin_amdgcn_cvt_scalef32_pk_f32_fp4(dw, 1.0f, 3);
;         acc[8 * m + 0] += ci * e0[0]; acc[8 * m + 1] += ci * e0[1]; acc[8 * m + 2] += ci * e1[0]; acc[8 * m + 3] += ci * e1[1];
;         acc[8 * m + 4] += ci * e2[0]; acc[8 * m + 5] += ci * e2[1]; acc[8 * m + 6] += ci * e3[0]; acc[8 * m + 7] += ci * e3[1];
;       }
;     }
;   };
;   int tt = wid;
;   if (tt < TH) load_idx(tt);
;   while (tt < TH) {
;     const int tn = tt + wstride;
;     const int t = 2 * tt + par;
; #pragma unroll
;     for (int i = 0; i < 8; ++i) qA[i] = *(const u32x4*)(Vq + (ni[i >> 2][i & 3] * 128u + joff));
;     float* hq = hrow(p, t) + sl * 256 + 4 * l;
;     f32x4 hv = *(const f32x4*)hq;
;     const f32x4 c0 = nc[0], c1 = nc[1], c2 = nc[2], c3 = nc[3];
.LBB0_782:
	s_or_b64 exec, exec, s[6:7]
	v_mov_b32_e32 v25, v189
	s_barrier
	v_and_b32_e32 v6, 63, v189
	v_lshrrev_b32_e32 v7, 6, v189
	v_lshlrev_b32_e32 v0, 4, v6
	v_and_b32_e32 v1, 7, v6
	v_lshlrev_b32_e32 v1, 4, v1
	v_lshrrev_b32_e32 v8, 3, v6
	v_readfirstlane_b32 s0, v7
	s_lshl_b32 s1, s28, 9
	v_lshl_add_u32 v2, v8, 6, s1
	v_lshlrev_b32_e32 v3, 13, v7
	v_lshl_add_u32 v4, v6, 4, v3
	v_lshl_add_u32 v3, v8, 10, v3
	v_lshl_add_u32 v3, v1, 3, v3
	v_lshlrev_b32_e32 v5, 3, v6
	s_add_u32 s36, s92, s0
	s_movk_i32 s38, 0x4020
	s_cmp_ge_u32 s36, s38
	s_cbranch_scc1 .Lmy_pv0_done
	s_lshl_b32 s0, s14, 21
	s_add_u32 s40, s90, s0
	s_addc_u32 s41, s91, 0
	v_readlane_b32 s42, v254, 6
	v_readlane_b32 s43, v254, 7
	v_readlane_b32 s10, v254, 30
	v_readlane_b32 s11, v254, 31
	v_readlane_b32 s12, v254, 32
	v_readlane_b32 s13, v254, 33
	s_lshl_b32 s39, s14, 10
	s_mov_b32 s49, 0x7fc02
	s_sub_u32 s10, s10, 0x10000
	s_subb_u32 s11, s11, 0
	s_lshl_b32 s0, s36, 10
	v_add_u32_e32 v9, s0, v2
	global_load_dwordx4 v[10:13], v9, s[52:53]
	global_load_dwordx4 v[14:17], v9, s[52:53] offset:16
	global_load_dwordx4 v[18:21], v9, s[52:53] offset:32
	global_load_dwordx4 v[22:25], v9, s[52:53] offset:48
	s_waitcnt vmcnt(0)
	v_lshl_add_u32 v6, v10, 7, v1
	global_load_dwordx4 v[106:109], v6, s[40:41]
	v_lshl_add_u32 v7, v11, 7, v1
	global_load_dwordx4 v[110:113], v7, s[40:41]
	v_lshl_add_u32 v6, v12, 7, v1
	global_load_dwordx4 v[114:117], v6, s[40:41]
	v_lshl_add_u32 v7, v13, 7, v1
	global_load_dwordx4 v[118:121], v7, s[40:41]
	v_lshl_add_u32 v6, v14, 7, v1
	global_load_dwordx4 v[122:125], v6, s[40:41]
	v_lshl_add_u32 v7, v15, 7, v1
	global_load_dwordx4 v[126:129], v7, s[40:41]
	v_lshl_add_u32 v6, v16, 7, v1
	global_load_dwordx4 v[130:133], v6, s[40:41]
	v_lshl_add_u32 v7, v17, 7, v1
	global_load_dwordx4 v[134:137], v7, s[40:41]
	v_lshl_add_u32 v6, v18, 7, v1
	global_load_dwordx4 v[138:141], v6, s[40:41]
	v_lshl_add_u32 v7, v19, 7, v1
	global_load_dwordx4 v[142:145], v7, s[40:41]
	v_lshl_add_u32 v6, v20, 7, v1
	global_load_dwordx4 v[146:149], v6, s[40:41]
	v_lshl_add_u32 v7, v21, 7, v1
	global_load_dwordx4 v[150:153], v7, s[40:41]
	v_lshl_add_u32 v6, v22, 7, v1
	global_load_dwordx4 v[154:157], v6, s[40:41]
	v_lshl_add_u32 v7, v23, 7, v1
	global_load_dwordx4 v[158:161], v7, s[40:41]
	v_lshl_add_u32 v6, v24, 7, v1
	global_load_dwordx4 v[162:165], v6, s[40:41]
	v_lshl_add_u32 v7, v25, 7, v1
	global_load_dwordx4 v[166:169], v7, s[40:41]
	s_lshl_b32 s0, s36, 1
	s_add_u32 s0, s0, s28
	s_mul_hi_u32 s1, s0, s49
	s_mul_i32 s3, s1, 0x2010
	s_sub_u32 s3, s0, s3
	s_lshl_b32 s6, s1, 13
	s_add_u32 s6, s6, s3
	s_lshl_b32 s7, s1, 4
	s_add_u32 s7, s7, s3
	s_cmp_lt_u32 s3, 16
	s_cselect_b32 s6, s7, s6
	s_cselect_b32 s7, s12, s10
	s_cselect_b32 s8, s13, s11
	s_lshl_b32 s6, s6, 12
	s_add_u32 s6, s6, s39
	s_add_u32 s44, s7, s6
	s_addc_u32 s45, s8, 0
	global_load_dwordx4 v[58:61], v0, s[44:45]
	s_lshl_b32 s0, s36, 10
	v_add_u32_e32 v8, s0, v2
	global_load_dwordx4 v[26:29], v8, s[42:43]
	global_load_dwordx4 v[30:33], v8, s[42:43] offset:16
	global_load_dwordx4 v[34:37], v8, s[42:43] offset:32
	global_load_dwordx4 v[38:41], v8, s[42:43] offset:48
	s_add_u32 s51, s36, s33
	s_cmp_ge_u32 s51, s38
	s_cbranch_scc1 .Lmy_pv0_pro1
	s_lshl_b32 s0, s51, 10
	v_add_u32_e32 v9, s0, v2
	global_load_dwordx4 v[10:13], v9, s[52:53]
	global_load_dwordx4 v[14:17], v9, s[52:53] offset:16
	global_load_dwordx4 v[18:21], v9, s[52:53] offset:32
	global_load_dwordx4 v[22:25], v9, s[52:53] offset:48

; __device__ __forceinline__ void phase_peer_v(const Params& p, int layer, int xs, int wid0, int wstride, bool last, char* smraw) {
;     ...
;   auto load_idx = [&](int tt) {
;     const unsigned o = (unsigned)(2 * tt + par) * 512u + (unsigned)g * 64u;
;     const u32x4* ip = (const u32x4*)((const char*)p.sel_idx + o);
;     const f32x4* cp = (const f32x4*)((const char*)p.coef + o);
; #pragma unroll
;     for (int q4 = 0; q4 < 4; ++q4) { ni[q4] = ip[q4]; nc[q4] = cp[q4]; }
;   };
;   u32x4 qA[8];
;   float acc[32];
;   auto half_fma = [&](const u32x4 (&q)[8], const f32x4& c0, const f32x4& c1) {
; #pragma unroll
;     for (int i = 0; i < 8; ++i) {
;       const float ci = i < 4 ? c0[i & 3] : c1[i & 3];
; #pragma unroll
;       for (int m = 0; m < 4; ++m) {
;         unsigned dw = q[i][m];
;         asm volatile("" : "+v"(dw) : "v"(acc[(8 * m + 31) & 31]));
;         const f32x2 e0 = __builtin_amdgcn_cvt_scalef32_pk_f32_fp4(dw, 1.0f, 0), e1 = __builtin_amdgcn_cvt_scalef32_pk_f32_fp4(dw, 1.0f, 1);
;         const f32x2 e2 = __builtin_amdgcn_cvt_scalef32_pk_f32_fp4(dw, 1.0f, 2), e3 = __builtin_amdgcn_cvt_scalef32_pk_f32_fp4(dw, 1.0f, 3);
;         acc[8 * m + 0] += ci * e0[0]; acc[8 * m + 1] += ci * e0[1]; acc[8 * m + 2] += ci * e1[0]; acc[8 * m + 3] += ci * e1[1];
;         acc[8 * m + 4] += ci * e2[0]; acc[8 * m + 5] += ci * e2[1]; acc[8 * m + 6] += ci * e3[0]; acc[8 * m + 7] += ci * e3[1];
;       }
;     }
;   };
;   int tt = wid;
;   if (tt < TH) load_idx(tt);
;   while (tt < TH) {
;     const int tn = tt + wstride;
;     const int t = 2 * tt + par;
; #pragma unroll
;     for (int i = 0; i < 8; ++i) qA[i] = *(const u32x4*)(Vq + (ni[i >> 2][i & 3] * 128u + joff));
;     float* hq = hrow(p, t) + sl * 256 + 4 * l;
;     f32x4 hv = *(const f32x4*)hq;
;     const f32x4 c0 = nc[0], c1 = nc[1], c2 = nc[2], c3 = nc[3];
; #pragma unroll
;     for (int m = 0; m < 32; ++m) acc[m] = 0.f;
;     half_fma(qA, c0, c1);
; #pragma unroll
;     for (int i = 0; i < 8; ++i) qA[i] = *(const u32x4*)(Vq + (ni[2 + (i >> 2)][i & 3] * 128u + joff));
;     if (tn < TH) load_idx(tn);
;     half_fma(qA, c2, c3);
.Lmy_pv0_bodyA:
	s_waitcnt vmcnt(2)
	s_add_u32 s51, s36, s33
	s_cmp_ge_u32 s51, s38
	s_cbranch_scc1 .Lmy_pv0_noissueA
	v_lshl_add_u32 v6, v10, 7, v1
	global_load_dwordx4 v[170:173], v6, s[40:41]
	v_lshl_add_u32 v7, v11, 7, v1
	global_load_dwordx4 v[174:177], v7, s[40:41]
	v_lshl_add_u32 v6, v12, 7, v1
	global_load_dwordx4 v[178:181], v6, s[40:41]
	v_lshl_add_u32 v7, v13, 7, v1
	global_load_dwordx4 v[182:185], v7, s[40:41]
	v_lshl_add_u32 v6, v14, 7, v1
	global_load_dwordx4 v[192:195], v6, s[40:41]
	v_lshl_add_u32 v7, v15, 7, v1
	global_load_dwordx4 v[196:199], v7, s[40:41]
	v_lshl_add_u32 v6, v16, 7, v1
	global_load_dwordx4 v[200:203], v6, s[40:41]
	v_lshl_add_u32 v7, v17, 7, v1
	global_load_dwordx4 v[204:207], v7, s[40:41]
	v_lshl_add_u32 v6, v18, 7, v1
	global_load_dwordx4 v[208:211], v6, s[40:41]
	v_lshl_add_u32 v7, v19, 7, v1
	global_load_dwordx4 v[212:215], v7, s[40:41]
	v_lshl_add_u32 v6, v20, 7, v1
	global_load_dwordx4 v[216:219], v6, s[40:41]
	v_lshl_add_u32 v7, v21, 7, v1
	global_load_dwordx4 v[220:223], v7, s[40:41]
	v_lshl_add_u32 v6, v22, 7, v1
	global_load_dwordx4 v[224:227], v6, s[40:41]
	v_lshl_add_u32 v7, v23, 7, v1
	global_load_dwordx4 v[228:231], v7, s[40:41]
	v_lshl_add_u32 v6, v24, 7, v1
	global_load_dwordx4 v[232:235], v6, s[40:41]
	v_lshl_add_u32 v7, v25, 7, v1
	global_load_dwordx4 v[236:239], v7, s[40:41]
	s_lshl_b32 s0, s51, 1
	s_add_u32 s0, s0, s28
	s_mul_hi_u32 s1, s0, s49
	s_mul_i32 s3, s1, 0x2010
	s_sub_u32 s3, s0, s3
	s_lshl_b32 s6, s1, 13
	s_add_u32 s6, s6, s3
	s_lshl_b32 s7, s1, 4
	s_add_u32 s7, s7, s3
	s_cmp_lt_u32 s3, 16
	s_cselect_b32 s6, s7, s6
	s_cselect_b32 s7, s12, s10
	s_cselect_b32 s8, s13, s11
	s_lshl_b32 s6, s6, 12
	s_add_u32 s6, s6, s39
	s_add_u32 s46, s7, s6
	s_addc_u32 s47, s8, 0
	global_load_dwordx4 v[62:65], v0, s[46:47]
	s_lshl_b32 s0, s51, 10
	v_add_u32_e32 v8, s0, v2
	global_load_dwordx4 v[42:45], v8, s[42:43]
	global_load_dwordx4 v[46:49], v8, s[42:43] offset:16
	global_load_dwordx4 v[50:53], v8, s[42:43] offset:32
	global_load_dwordx4 v[54:57], v8, s[42:43] offset:48
	s_add_u32 s9, s51, s33
	s_cmp_ge_u32 s9, s38
	s_cbranch_scc1 .Lmy_pv0_noissueA
	s_lshl_b32 s0, s9, 10
	v_add_u32_e32 v9, s0, v2
	global_load_dwordx4 v[10:13], v9, s[52:53]
	global_load_dwordx4 v[14:17], v9, s[52:53] offset:16
	global_load_dwordx4 v[18:21], v9, s[52:53] offset:32
	global_load_dwordx4 v[22:25], v9, s[52:53] offset:48
.Lmy_pv0_noissueA:
	v_cvt_scalef32_pk_f32_fp4 v[98:99], v106, 1.0
	v_cvt_scalef32_pk_f32_fp4 v[100:101], v106, 1.0 op_sel:[1,0,0]
	v_cvt_scalef32_pk_f32_fp4 v[102:103], v106, 1.0 op_sel:[0,1,0]
	v_cvt_scalef32_pk_f32_fp4 v[104:105], v106, 1.0 op_sel:[1,1,0]
	v_pk_fma_f32 v[66:67], v[26:27], v[98:99], 0 op_sel_hi:[0,1,0]
	v_pk_fma_f32 v[68:69], v[26:27], v[100:101], 0 op_sel_hi:[0,1,0]
	v_pk_fma_f32 v[70:71], v[26:27], v[102:103], 0 op_sel_hi:[0,1,0]
	v_pk_fma_f32 v[72:73], v[26:27], v[104:105], 0 op_sel_hi:[0,1,0]
	v_cvt_scalef32_pk_f32_fp4 v[98:99], v107, 1.0
	v_cvt_scalef32_pk_f32_fp4 v[100:101], v107, 1.0 op_sel:[1,0,0]
	v_cvt_scalef32_pk_f32_fp4 v[102:103], v107, 1.0 op_sel:[0,1,0]
	v_cvt_scalef32_pk_f32_fp4 v[104:105], v107, 1.0 op_sel:[1,1,0]
	v_pk_fma_f32 v[74:75], v[26:27], v[98:99], 0 op_sel_hi:[0,1,0]
	v_pk_fma_f32 v[76:77], v[26:27], v[100:101], 0 op_sel_hi:[0,1,0]
	v_pk_fma_f32 v[78:79], v[26:27], v[102:103], 0 op_sel_hi:[0,1,0]
	v_pk_fma_f32 v[80:81], v[26:27], v[104:105], 0 op_sel_hi:[0,1,0]
	v_cvt_scalef32_pk_f32_fp4 v[98:99], v108, 1.0
	v_cvt_scalef32_pk_f32_fp4 v[100:101], v108, 1.0 op_sel:[1,0,0]
	v_cvt_scalef32_pk_f32_fp4 v[102:103], v108, 1.0 op_sel:[0,1,0]
	v_cvt_scalef32_pk_f32_fp4 v[104:105], v108, 1.0 op_sel:[1,1,0]
	v_pk_fma_f32 v[82:83], v[26:27], v[98:99], 0 op_sel_hi:[0,1,0]
	v_pk_fma_f32 v[84:85], v[26:27], v[100:101], 0 op_sel_hi:[0,1,0]
	v_pk_fma_f32 v[86:87], v[26:27], v[102:103], 0 op_sel_hi:[0,1,0]
	v_pk_fma_f32 v[88:89], v[26:27], v[104:105], 0 op_sel_hi:[0,1,0]
	v_cvt_scalef32_pk_f32_fp4 v[98:99], v109, 1.0
	v_cvt_scalef32_pk_f32_fp4 v[100:101], v109, 1.0 op_sel:[1,0,0]
	v_cvt_scalef32_pk_f32_fp4 v[102:103], v109, 1.0 op_sel:[0,1,0]
	v_cvt_scalef32_pk_f32_fp4 v[104:105], v109, 1.0 op_sel:[1,1,0]
	v_pk_fma_f32 v[90:91], v[26:27], v[98:99], 0 op_sel_hi:[0,1,0]
	v_pk_fma_f32 v[92:93], v[26:27], v[100:101], 0 op_sel_hi:[0,1,0]
	v_pk_fma_f32 v[94:95], v[26:27], v[102:103], 0 op_sel_hi:[0,1,0]
	v_pk_fma_f32 v[96:97], v[26:27], v[104:105], 0 op_sel_hi:[0,1,0]
	v_cvt_scalef32_pk_f32_fp4 v[98:99], v110, 1.0
	v_cvt_scalef32_pk_f32_fp4 v[100:101], v110, 1.0 op_sel:[1,0,0]
	v_cvt_scalef32_pk_f32_fp4 v[102:103], v110, 1.0 op_sel:[0,1,0]
	v_cvt_scalef32_pk_f32_fp4 v[104:105], v110, 1.0 op_sel:[1,1,0]
	v_pk_fma_f32 v[66:67], v[26:27], v[98:99], v[66:67] op_sel:[1,0,0] op_sel_hi:[1,1,1]
	v_pk_fma_f32 v[68:69], v[26:27], v[100:101], v[68:69] op_sel:[1,0,0] op_sel_hi:[1,1,1]
	v_pk_fma_f32 v[70:71], v[26:27], v[102:103], v[70:71] op_sel:[1,0,0] op_sel_hi:[1,1,1]
	v_pk_fma_f32 v[72:73], v[26:27], v[104:105], v[72:73] op_sel:[1,0,0] op_sel_hi:[1,1,1]
	v_cvt_scalef32_pk_f32_fp4 v[98:99], v111, 1.0
	v_cvt_scalef32_pk_f32_fp4 v[100:101], v111, 1.0 op_sel:[1,0,0]
	v_cvt_scalef32_pk_f32_fp4 v[102:103], v111, 1.0 op_sel:[0,1,0]
	v_cvt_scalef32_pk_f32_fp4 v[104:105], v111, 1.0 op_sel:[1,1,0]
	v_pk_fma_f32 v[74:75], v[26:27], v[98:99], v[74:75] op_sel:[1,0,0] op_sel_hi:[1,1,1]
	v_pk_fma_f32 v[76:77], v[26:27], v[100:101], v[76:77] op_sel:[1,0,0] op_sel_hi:[1,1,1]
	v_pk_fma_f32 v[78:79], v[26:27], v[102:103], v[78:79] op_sel:[1,0,0] op_sel_hi:[1,1,1]
	v_pk_fma_f32 v[80:81], v[26:27], v[104:105], v[80:81] op_sel:[1,0,0] op_sel_hi:[1,1,1]
	v_cvt_scalef32_pk_f32_fp4 v[98:99], v112, 1.0
; __device__ __forceinline__ void phase_peer_v(const Params& p, int layer, int xs, int wid0, int wstride, bool last, char* smraw) {
;     ...
;   auto half_fma = [&](const u32x4 (&q)[8], const f32x4& c0, const f32x4& c1) {
; #pragma unroll
;     for (int i = 0; i < 8; ++i) {
;       const float ci = i < 4 ? c0[i & 3] : c1[i & 3];
; #pragma unroll
;       for (int m = 0; m < 4; ++m) {
;         unsigned dw = q[i][m];
;         asm volatile("" : "+v"(dw) : "v"(acc[(8 * m + 31) & 31]));
;         const f32x2 e0 = __builtin_amdgcn_cvt_scalef32_pk_f32_fp4(dw, 1.0f, 0), e1 = __builtin_amdgcn_cvt_scalef32_pk_f32_fp4(dw, 1.0f, 1);
;         const f32x2 e2 = __builtin_amdgcn_cvt_scalef32_pk_f32_fp4(dw, 1.0f, 2), e3 = __builtin_amdgcn_cvt_scalef32_pk_f32_fp4(dw, 1.0f, 3);
;         acc[8 * m + 0] += ci * e0[0]; acc[8 * m + 1] += ci * e0[1]; acc[8 * m + 2] += ci * e1[0]; acc[8 * m + 3] += ci * e1[1];
;         acc[8 * m + 4] += ci * e2[0]; acc[8 * m + 5] += ci * e2[1]; acc[8 * m + 6] += ci * e3[0]; acc[8 * m + 7] += ci * e3[1];
;       }
;     }
	v_cvt_scalef32_pk_f32_fp4 v[100:101], v112, 1.0 op_sel:[1,0,0]
	v_cvt_scalef32_pk_f32_fp4 v[102:103], v112, 1.0 op_sel:[0,1,0]
	v_cvt_scalef32_pk_f32_fp4 v[104:105], v112, 1.0 op_sel:[1,1,0]
	v_pk_fma_f32 v[82:83], v[26:27], v[98:99], v[82:83] op_sel:[1,0,0] op_sel_hi:[1,1,1]
	v_pk_fma_f32 v[84:85], v[26:27], v[100:101], v[84:85] op_sel:[1,0,0] op_sel_hi:[1,1,1]
	v_pk_fma_f32 v[86:87], v[26:27], v[102:103], v[86:87] op_sel:[1,0,0] op_sel_hi:[1,1,1]
	v_pk_fma_f32 v[88:89], v[26:27], v[104:105], v[88:89] op_sel:[1,0,0] op_sel_hi:[1,1,1]
	v_cvt_scalef32_pk_f32_fp4 v[98:99], v113, 1.0
	v_cvt_scalef32_pk_f32_fp4 v[100:101], v113, 1.0 op_sel:[1,0,0]
	v_cvt_scalef32_pk_f32_fp4 v[102:103], v113, 1.0 op_sel:[0,1,0]
	v_cvt_scalef32_pk_f32_fp4 v[104:105], v113, 1.0 op_sel:[1,1,0]
	v_pk_fma_f32 v[90:91], v[26:27], v[98:99], v[90:91] op_sel:[1,0,0] op_sel_hi:[1,1,1]
	v_pk_fma_f32 v[92:93], v[26:27], v[100:101], v[92:93] op_sel:[1,0,0] op_sel_hi:[1,1,1]
	v_pk_fma_f32 v[94:95], v[26:27], v[102:103], v[94:95] op_sel:[1,0,0] op_sel_hi:[1,1,1]
	v_pk_fma_f32 v[96:97], v[26:27], v[104:105], v[96:97] op_sel:[1,0,0] op_sel_hi:[1,1,1]
	v_cvt_scalef32_pk_f32_fp4 v[98:99], v114, 1.0
	v_cvt_scalef32_pk_f32_fp4 v[100:101], v114, 1.0 op_sel:[1,0,0]
	v_cvt_scalef32_pk_f32_fp4 v[102:103], v114, 1.0 op_sel:[0,1,0]
	v_cvt_scalef32_pk_f32_fp4 v[104:105], v114, 1.0 op_sel:[1,1,0]
	v_pk_fma_f32 v[66:67], v[28:29], v[98:99], v[66:67] op_sel_hi:[0,1,1]
	v_pk_fma_f32 v[68:69], v[28:29], v[100:101], v[68:69] op_sel_hi:[0,1,1]
	v_pk_fma_f32 v[70:71], v[28:29], v[102:103], v[70:71] op_sel_hi:[0,1,1]
	v_pk_fma_f32 v[72:73], v[28:29], v[104:105], v[72:73] op_sel_hi:[0,1,1]
	v_cvt_scalef32_pk_f32_fp4 v[98:99], v115, 1.0
	v_cvt_scalef32_pk_f32_fp4 v[100:101], v115, 1.0 op_sel:[1,0,0]
	v_cvt_scalef32_pk_f32_fp4 v[102:103], v115, 1.0 op_sel:[0,1,0]
	v_cvt_scalef32_pk_f32_fp4 v[104:105], v115, 1.0 op_sel:[1,1,0]
	v_pk_fma_f32 v[74:75], v[28:29], v[98:99], v[74:75] op_sel_hi:[0,1,1]
	v_pk_fma_f32 v[76:77], v[28:29], v[100:101], v[76:77] op_sel_hi:[0,1,1]
	v_pk_fma_f32 v[78:79], v[28:29], v[102:103], v[78:79] op_sel_hi:[0,1,1]
	v_pk_fma_f32 v[80:81], v[28:29], v[104:105], v[80:81] op_sel_hi:[0,1,1]
	v_cvt_scalef32_pk_f32_fp4 v[98:99], v116, 1.0
	v_cvt_scalef32_pk_f32_fp4 v[100:101], v116, 1.0 op_sel:[1,0,0]
	v_cvt_scalef32_pk_f32_fp4 v[102:103], v116, 1.0 op_sel:[0,1,0]
	v_cvt_scalef32_pk_f32_fp4 v[104:105], v116, 1.0 op_sel:[1,1,0]
	v_pk_fma_f32 v[82:83], v[28:29], v[98:99], v[82:83] op_sel_hi:[0,1,1]
	v_pk_fma_f32 v[84:85], v[28:29], v[100:101], v[84:85] op_sel_hi:[0,1,1]
	v_pk_fma_f32 v[86:87], v[28:29], v[102:103], v[86:87] op_sel_hi:[0,1,1]
	v_pk_fma_f32 v[88:89], v[28:29], v[104:105], v[88:89] op_sel_hi:[0,1,1]
	v_cvt_scalef32_pk_f32_fp4 v[98:99], v117, 1.0
	v_cvt_scalef32_pk_f32_fp4 v[100:101], v117, 1.0 op_sel:[1,0,0]
	v_cvt_scalef32_pk_f32_fp4 v[102:103], v117, 1.0 op_sel:[0,1,0]
	v_cvt_scalef32_pk_f32_fp4 v[104:105], v117, 1.0 op_sel:[1,1,0]
	v_pk_fma_f32 v[90:91], v[28:29], v[98:99], v[90:91] op_sel_hi:[0,1,1]
	v_pk_fma_f32 v[92:93], v[28:29], v[100:101], v[92:93] op_sel_hi:[0,1,1]
	v_pk_fma_f32 v[94:95], v[28:29], v[102:103], v[94:95] op_sel_hi:[0,1,1]
	v_pk_fma_f32 v[96:97], v[28:29], v[104:105], v[96:97] op_sel_hi:[0,1,1]
	v_cvt_scalef32_pk_f32_fp4 v[98:99], v118, 1.0
	v_cvt_scalef32_pk_f32_fp4 v[100:101], v118, 1.0 op_sel:[1,0,0]
	v_cvt_scalef32_pk_f32_fp4 v[102:103], v118, 1.0 op_sel:[0,1,0]
	v_cvt_scalef32_pk_f32_fp4 v[104:105], v118, 1.0 op_sel:[1,1,0]
	v_pk_fma_f32 v[66:67], v[28:29], v[98:99], v[66:67] op_sel:[1,0,0] op_sel_hi:[1,1,1]
	v_pk_fma_f32 v[68:69], v[28:29], v[100:101], v[68:69] op_sel:[1,0,0] op_sel_hi:[1,1,1]
	v_pk_fma_f32 v[70:71], v[28:29], v[102:103], v[70:71] op_sel:[1,0,0] op_sel_hi:[1,1,1]
	v_pk_fma_f32 v[72:73], v[28:29], v[104:105], v[72:73] op_sel:[1,0,0] op_sel_hi:[1,1,1]
	v_cvt_scalef32_pk_f32_fp4 v[98:99], v119, 1.0
	v_cvt_scalef32_pk_f32_fp4 v[100:101], v119, 1.0 op_sel:[1,0,0]
	v_cvt_scalef32_pk_f32_fp4 v[102:103], v119, 1.0 op_sel:[0,1,0]
	v_cvt_scalef32_pk_f32_fp4 v[104:105], v119, 1.0 op_sel:[1,1,0]
	v_pk_fma_f32 v[74:75], v[28:29], v[98:99], v[74:75] op_sel:[1,0,0] op_sel_hi:[1,1,1]
	v_pk_fma_f32 v[76:77], v[28:29], v[100:101], v[76:77] op_sel:[1,0,0] op_sel_hi:[1,1,1]
	v_pk_fma_f32 v[78:79], v[28:29], v[102:103], v[78:79] op_sel:[1,0,0] op_sel_hi:[1,1,1]
	v_pk_fma_f32 v[80:81], v[28:29], v[104:105], v[80:81] op_sel:[1,0,0] op_sel_hi:[1,1,1]
	v_cvt_scalef32_pk_f32_fp4 v[98:99], v120, 1.0
	v_cvt_scalef32_pk_f32_fp4 v[100:101], v120, 1.0 op_sel:[1,0,0]
	v_cvt_scalef32_pk_f32_fp4 v[102:103], v120, 1.0 op_sel:[0,1,0]
	v_cvt_scalef32_pk_f32_fp4 v[104:105], v120, 1.0 op_sel:[1,1,0]
	v_pk_fma_f32 v[82:83], v[28:29], v[98:99], v[82:83] op_sel:[1,0,0] op_sel_hi:[1,1,1]
	v_pk_fma_f32 v[84:85], v[28:29], v[100:101], v[84:85] op_sel:[1,0,0] op_sel_hi:[1,1,1]
	v_pk_fma_f32 v[86:87], v[28:29], v[102:103], v[86:87] op_sel:[1,0,0] op_sel_hi:[1,1,1]
	v_pk_fma_f32 v[88:89], v[28:29], v[104:105], v[88:89] op_sel:[1,0,0] op_sel_hi:[1,1,1]
	v_cvt_scalef32_pk_f32_fp4 v[98:99], v121, 1.0
	v_cvt_scalef32_pk_f32_fp4 v[100:101], v121, 1.0 op_sel:[1,0,0]
	v_cvt_scalef32_pk_f32_fp4 v[102:103], v121, 1.0 op_sel:[0,1,0]
	v_cvt_scalef32_pk_f32_fp4 v[104:105], v121, 1.0 op_sel:[1,1,0]
	v_pk_fma_f32 v[90:91], v[28:29], v[98:99], v[90:91] op_sel:[1,0,0] op_sel_hi:[1,1,1]
	v_pk_fma_f32 v[92:93], v[28:29], v[100:101], v[92:93] op_sel:[1,0,0] op_sel_hi:[1,1,1]
	v_pk_fma_f32 v[94:95], v[28:29], v[102:103], v[94:95] op_sel:[1,0,0] op_sel_hi:[1,1,1]
	v_pk_fma_f32 v[96:97], v[28:29], v[104:105], v[96:97] op_sel:[1,0,0] op_sel_hi:[1,1,1]
	v_cvt_scalef32_pk_f32_fp4 v[98:99], v122, 1.0
; __device__ __forceinline__ void phase_peer_v(const Params& p, int layer, int xs, int wid0, int wstride, bool last, char* smraw) {
;     ...
;   auto half_fma = [&](const u32x4 (&q)[8], const f32x4& c0, const f32x4& c1) {
; #pragma unroll
;     for (int i = 0; i < 8; ++i) {
;       const float ci = i < 4 ? c0[i & 3] : c1[i & 3];
; #pragma unroll
;       for (int m = 0; m < 4; ++m) {
;         unsigned dw = q[i][m];
;         asm volatile("" : "+v"(dw) : "v"(acc[(8 * m + 31) & 31]));
;         const f32x2 e0 = __builtin_amdgcn_cvt_scalef32_pk_f32_fp4(dw, 1.0f, 0), e1 = __builtin_amdgcn_cvt_scalef32_pk_f32_fp4(dw, 1.0f, 1);
;         const f32x2 e2 = __builtin_amdgcn_cvt_scalef32_pk_f32_fp4(dw, 1.0f, 2), e3 = __builtin_amdgcn_cvt_scalef32_pk_f32_fp4(dw, 1.0f, 3);
;         acc[8 * m + 0] += ci * e0[0]; acc[8 * m + 1] += ci * e0[1]; acc[8 * m + 2] += ci * e1[0]; acc[8 * m + 3] += ci * e1[1];
;         acc[8 * m + 4] += ci * e2[0]; acc[8 * m + 5] += ci * e2[1]; acc[8 * m + 6] += ci * e3[0]; acc[8 * m + 7] += ci * e3[1];
;       }
;     }
	v_cvt_scalef32_pk_f32_fp4 v[100:101], v122, 1.0 op_sel:[1,0,0]
	v_cvt_scalef32_pk_f32_fp4 v[102:103], v122, 1.0 op_sel:[0,1,0]
	v_cvt_scalef32_pk_f32_fp4 v[104:105], v122, 1.0 op_sel:[1,1,0]
	v_pk_fma_f32 v[66:67], v[30:31], v[98:99], v[66:67] op_sel_hi:[0,1,1]
	v_pk_fma_f32 v[68:69], v[30:31], v[100:101], v[68:69] op_sel_hi:[0,1,1]
	v_pk_fma_f32 v[70:71], v[30:31], v[102:103], v[70:71] op_sel_hi:[0,1,1]
	v_pk_fma_f32 v[72:73], v[30:31], v[104:105], v[72:73] op_sel_hi:[0,1,1]
	v_cvt_scalef32_pk_f32_fp4 v[98:99], v123, 1.0
	v_cvt_scalef32_pk_f32_fp4 v[100:101], v123, 1.0 op_sel:[1,0,0]
	v_cvt_scalef32_pk_f32_fp4 v[102:103], v123, 1.0 op_sel:[0,1,0]
	v_cvt_scalef32_pk_f32_fp4 v[104:105], v123, 1.0 op_sel:[1,1,0]
	v_pk_fma_f32 v[74:75], v[30:31], v[98:99], v[74:75] op_sel_hi:[0,1,1]
	v_pk_fma_f32 v[76:77], v[30:31], v[100:101], v[76:77] op_sel_hi:[0,1,1]
	v_pk_fma_f32 v[78:79], v[30:31], v[102:103], v[78:79] op_sel_hi:[0,1,1]
	v_pk_fma_f32 v[80:81], v[30:31], v[104:105], v[80:81] op_sel_hi:[0,1,1]
	v_cvt_scalef32_pk_f32_fp4 v[98:99], v124, 1.0
	v_cvt_scalef32_pk_f32_fp4 v[100:101], v124, 1.0 op_sel:[1,0,0]
	v_cvt_scalef32_pk_f32_fp4 v[102:103], v124, 1.0 op_sel:[0,1,0]
	v_cvt_scalef32_pk_f32_fp4 v[104:105], v124, 1.0 op_sel:[1,1,0]
	v_pk_fma_f32 v[82:83], v[30:31], v[98:99], v[82:83] op_sel_hi:[0,1,1]
	v_pk_fma_f32 v[84:85], v[30:31], v[100:101], v[84:85] op_sel_hi:[0,1,1]
	v_pk_fma_f32 v[86:87], v[30:31], v[102:103], v[86:87] op_sel_hi:[0,1,1]
	v_pk_fma_f32 v[88:89], v[30:31], v[104:105], v[88:89] op_sel_hi:[0,1,1]
	v_cvt_scalef32_pk_f32_fp4 v[98:99], v125, 1.0
	v_cvt_scalef32_pk_f32_fp4 v[100:101], v125, 1.0 op_sel:[1,0,0]
	v_cvt_scalef32_pk_f32_fp4 v[102:103], v125, 1.0 op_sel:[0,1,0]
	v_cvt_scalef32_pk_f32_fp4 v[104:105], v125, 1.0 op_sel:[1,1,0]
	v_pk_fma_f32 v[90:91], v[30:31], v[98:99], v[90:91] op_sel_hi:[0,1,1]
	v_pk_fma_f32 v[92:93], v[30:31], v[100:101], v[92:93] op_sel_hi:[0,1,1]
	v_pk_fma_f32 v[94:95], v[30:31], v[102:103], v[94:95] op_sel_hi:[0,1,1]
	v_pk_fma_f32 v[96:97], v[30:31], v[104:105], v[96:97] op_sel_hi:[0,1,1]
	v_cvt_scalef32_pk_f32_fp4 v[98:99], v126, 1.0
	v_cvt_scalef32_pk_f32_fp4 v[100:101], v126, 1.0 op_sel:[1,0,0]
	v_cvt_scalef32_pk_f32_fp4 v[102:103], v126, 1.0 op_sel:[0,1,0]
	v_cvt_scalef32_pk_f32_fp4 v[104:105], v126, 1.0 op_sel:[1,1,0]
	v_pk_fma_f32 v[66:67], v[30:31], v[98:99], v[66:67] op_sel:[1,0,0] op_sel_hi:[1,1,1]
	v_pk_fma_f32 v[68:69], v[30:31], v[100:101], v[68:69] op_sel:[1,0,0] op_sel_hi:[1,1,1]
	v_pk_fma_f32 v[70:71], v[30:31], v[102:103], v[70:71] op_sel:[1,0,0] op_sel_hi:[1,1,1]
	v_pk_fma_f32 v[72:73], v[30:31], v[104:105], v[72:73] op_sel:[1,0,0] op_sel_hi:[1,1,1]
	v_cvt_scalef32_pk_f32_fp4 v[98:99], v127, 1.0
	v_cvt_scalef32_pk_f32_fp4 v[100:101], v127, 1.0 op_sel:[1,0,0]
	v_cvt_scalef32_pk_f32_fp4 v[102:103], v127, 1.0 op_sel:[0,1,0]
	v_cvt_scalef32_pk_f32_fp4 v[104:105], v127, 1.0 op_sel:[1,1,0]
	v_pk_fma_f32 v[74:75], v[30:31], v[98:99], v[74:75] op_sel:[1,0,0] op_sel_hi:[1,1,1]
	v_pk_fma_f32 v[76:77], v[30:31], v[100:101], v[76:77] op_sel:[1,0,0] op_sel_hi:[1,1,1]
	v_pk_fma_f32 v[78:79], v[30:31], v[102:103], v[78:79] op_sel:[1,0,0] op_sel_hi:[1,1,1]
	v_pk_fma_f32 v[80:81], v[30:31], v[104:105], v[80:81] op_sel:[1,0,0] op_sel_hi:[1,1,1]
	v_cvt_scalef32_pk_f32_fp4 v[98:99], v128, 1.0
	v_cvt_scalef32_pk_f32_fp4 v[100:101], v128, 1.0 op_sel:[1,0,0]
	v_cvt_scalef32_pk_f32_fp4 v[102:103], v128, 1.0 op_sel:[0,1,0]
	v_cvt_scalef32_pk_f32_fp4 v[104:105], v128, 1.0 op_sel:[1,1,0]
	v_pk_fma_f32 v[82:83], v[30:31], v[98:99], v[82:83] op_sel:[1,0,0] op_sel_hi:[1,1,1]
	v_pk_fma_f32 v[84:85], v[30:31], v[100:101], v[84:85] op_sel:[1,0,0] op_sel_hi:[1,1,1]
	v_pk_fma_f32 v[86:87], v[30:31], v[102:103], v[86:87] op_sel:[1,0,0] op_sel_hi:[1,1,1]
	v_pk_fma_f32 v[88:89], v[30:31], v[104:105], v[88:89] op_sel:[1,0,0] op_sel_hi:[1,1,1]
	v_cvt_scalef32_pk_f32_fp4 v[98:99], v129, 1.0
	v_cvt_scalef32_pk_f32_fp4 v[100:101], v129, 1.0 op_sel:[1,0,0]
	v_cvt_scalef32_pk_f32_fp4 v[102:103], v129, 1.0 op_sel:[0,1,0]
	v_cvt_scalef32_pk_f32_fp4 v[104:105], v129, 1.0 op_sel:[1,1,0]
	v_pk_fma_f32 v[90:91], v[30:31], v[98:99], v[90:91] op_sel:[1,0,0] op_sel_hi:[1,1,1]
	v_pk_fma_f32 v[92:93], v[30:31], v[100:101], v[92:93] op_sel:[1,0,0] op_sel_hi:[1,1,1]
	v_pk_fma_f32 v[94:95], v[30:31], v[102:103], v[94:95] op_sel:[1,0,0] op_sel_hi:[1,1,1]
	v_pk_fma_f32 v[96:97], v[30:31], v[104:105], v[96:97] op_sel:[1,0,0] op_sel_hi:[1,1,1]
	v_cvt_scalef32_pk_f32_fp4 v[98:99], v130, 1.0
	v_cvt_scalef32_pk_f32_fp4 v[100:101], v130, 1.0 op_sel:[1,0,0]
	v_cvt_scalef32_pk_f32_fp4 v[102:103], v130, 1.0 op_sel:[0,1,0]
	v_cvt_scalef32_pk_f32_fp4 v[104:105], v130, 1.0 op_sel:[1,1,0]
	v_pk_fma_f32 v[66:67], v[32:33], v[98:99], v[66:67] op_sel_hi:[0,1,1]
	v_pk_fma_f32 v[68:69], v[32:33], v[100:101], v[68:69] op_sel_hi:[0,1,1]
	v_pk_fma_f32 v[70:71], v[32:33], v[102:103], v[70:71] op_sel_hi:[0,1,1]
	v_pk_fma_f32 v[72:73], v[32:33], v[104:105], v[72:73] op_sel_hi:[0,1,1]
	v_cvt_scalef32_pk_f32_fp4 v[98:99], v131, 1.0
	v_cvt_scalef32_pk_f32_fp4 v[100:101], v131, 1.0 op_sel:[1,0,0]
	v_cvt_scalef32_pk_f32_fp4 v[102:103], v131, 1.0 op_sel:[0,1,0]
	v_cvt_scalef32_pk_f32_fp4 v[104:105], v131, 1.0 op_sel:[1,1,0]
	v_pk_fma_f32 v[74:75], v[32:33], v[98:99], v[74:75] op_sel_hi:[0,1,1]
	v_pk_fma_f32 v[76:77], v[32:33], v[100:101], v[76:77] op_sel_hi:[0,1,1]
	v_pk_fma_f32 v[78:79], v[32:33], v[102:103], v[78:79] op_sel_hi:[0,1,1]
	v_pk_fma_f32 v[80:81], v[32:33], v[104:105], v[80:81] op_sel_hi:[0,1,1]
	v_cvt_scalef32_pk_f32_fp4 v[98:99], v132, 1.0
	v_cvt_scalef32_pk_f32_fp4 v[100:101], v132, 1.0 op_sel:[1,0,0]
	v_cvt_scalef32_pk_f32_fp4 v[102:103], v132, 1.0 op_sel:[0,1,0]
; __device__ __forceinline__ void phase_peer_v(const Params& p, int layer, int xs, int wid0, int wstride, bool last, char* smraw) {
;     ...
;   auto half_fma = [&](const u32x4 (&q)[8], const f32x4& c0, const f32x4& c1) {
; #pragma unroll
;     for (int i = 0; i < 8; ++i) {
;       const float ci = i < 4 ? c0[i & 3] : c1[i & 3];
; #pragma unroll
;       for (int m = 0; m < 4; ++m) {
;         unsigned dw = q[i][m];
;         asm volatile("" : "+v"(dw) : "v"(acc[(8 * m + 31) & 31]));
;         const f32x2 e0 = __builtin_amdgcn_cvt_scalef32_pk_f32_fp4(dw, 1.0f, 0), e1 = __builtin_amdgcn_cvt_scalef32_pk_f32_fp4(dw, 1.0f, 1);
;         const f32x2 e2 = __builtin_amdgcn_cvt_scalef32_pk_f32_fp4(dw, 1.0f, 2), e3 = __builtin_amdgcn_cvt_scalef32_pk_f32_fp4(dw, 1.0f, 3);
;         acc[8 * m + 0] += ci * e0[0]; acc[8 * m + 1] += ci * e0[1]; acc[8 * m + 2] += ci * e1[0]; acc[8 * m + 3] += ci * e1[1];
;         acc[8 * m + 4] += ci * e2[0]; acc[8 * m + 5] += ci * e2[1]; acc[8 * m + 6] += ci * e3[0]; acc[8 * m + 7] += ci * e3[1];
;       }
;     }
	v_cvt_scalef32_pk_f32_fp4 v[104:105], v132, 1.0 op_sel:[1,1,0]
	v_pk_fma_f32 v[82:83], v[32:33], v[98:99], v[82:83] op_sel_hi:[0,1,1]
	v_pk_fma_f32 v[84:85], v[32:33], v[100:101], v[84:85] op_sel_hi:[0,1,1]
	v_pk_fma_f32 v[86:87], v[32:33], v[102:103], v[86:87] op_sel_hi:[0,1,1]
	v_pk_fma_f32 v[88:89], v[32:33], v[104:105], v[88:89] op_sel_hi:[0,1,1]
	v_cvt_scalef32_pk_f32_fp4 v[98:99], v133, 1.0
	v_cvt_scalef32_pk_f32_fp4 v[100:101], v133, 1.0 op_sel:[1,0,0]
	v_cvt_scalef32_pk_f32_fp4 v[102:103], v133, 1.0 op_sel:[0,1,0]
	v_cvt_scalef32_pk_f32_fp4 v[104:105], v133, 1.0 op_sel:[1,1,0]
	v_pk_fma_f32 v[90:91], v[32:33], v[98:99], v[90:91] op_sel_hi:[0,1,1]
	v_pk_fma_f32 v[92:93], v[32:33], v[100:101], v[92:93] op_sel_hi:[0,1,1]
	v_pk_fma_f32 v[94:95], v[32:33], v[102:103], v[94:95] op_sel_hi:[0,1,1]
	v_pk_fma_f32 v[96:97], v[32:33], v[104:105], v[96:97] op_sel_hi:[0,1,1]
	v_cvt_scalef32_pk_f32_fp4 v[98:99], v134, 1.0
	v_cvt_scalef32_pk_f32_fp4 v[100:101], v134, 1.0 op_sel:[1,0,0]
	v_cvt_scalef32_pk_f32_fp4 v[102:103], v134, 1.0 op_sel:[0,1,0]
	v_cvt_scalef32_pk_f32_fp4 v[104:105], v134, 1.0 op_sel:[1,1,0]
	v_pk_fma_f32 v[66:67], v[32:33], v[98:99], v[66:67] op_sel:[1,0,0] op_sel_hi:[1,1,1]
	v_pk_fma_f32 v[68:69], v[32:33], v[100:101], v[68:69] op_sel:[1,0,0] op_sel_hi:[1,1,1]
	v_pk_fma_f32 v[70:71], v[32:33], v[102:103], v[70:71] op_sel:[1,0,0] op_sel_hi:[1,1,1]
	v_pk_fma_f32 v[72:73], v[32:33], v[104:105], v[72:73] op_sel:[1,0,0] op_sel_hi:[1,1,1]
	v_cvt_scalef32_pk_f32_fp4 v[98:99], v135, 1.0
	v_cvt_scalef32_pk_f32_fp4 v[100:101], v135, 1.0 op_sel:[1,0,0]
	v_cvt_scalef32_pk_f32_fp4 v[102:103], v135, 1.0 op_sel:[0,1,0]
	v_cvt_scalef32_pk_f32_fp4 v[104:105], v135, 1.0 op_sel:[1,1,0]
	v_pk_fma_f32 v[74:75], v[32:33], v[98:99], v[74:75] op_sel:[1,0,0] op_sel_hi:[1,1,1]
	v_pk_fma_f32 v[76:77], v[32:33], v[100:101], v[76:77] op_sel:[1,0,0] op_sel_hi:[1,1,1]
	v_pk_fma_f32 v[78:79], v[32:33], v[102:103], v[78:79] op_sel:[1,0,0] op_sel_hi:[1,1,1]
	v_pk_fma_f32 v[80:81], v[32:33], v[104:105], v[80:81] op_sel:[1,0,0] op_sel_hi:[1,1,1]
	v_cvt_scalef32_pk_f32_fp4 v[98:99], v136, 1.0
	v_cvt_scalef32_pk_f32_fp4 v[100:101], v136, 1.0 op_sel:[1,0,0]
	v_cvt_scalef32_pk_f32_fp4 v[102:103], v136, 1.0 op_sel:[0,1,0]
	v_cvt_scalef32_pk_f32_fp4 v[104:105], v136, 1.0 op_sel:[1,1,0]
	v_pk_fma_f32 v[82:83], v[32:33], v[98:99], v[82:83] op_sel:[1,0,0] op_sel_hi:[1,1,1]
	v_pk_fma_f32 v[84:85], v[32:33], v[100:101], v[84:85] op_sel:[1,0,0] op_sel_hi:[1,1,1]
	v_pk_fma_f32 v[86:87], v[32:33], v[102:103], v[86:87] op_sel:[1,0,0] op_sel_hi:[1,1,1]
	v_pk_fma_f32 v[88:89], v[32:33], v[104:105], v[88:89] op_sel:[1,0,0] op_sel_hi:[1,1,1]
	v_cvt_scalef32_pk_f32_fp4 v[98:99], v137, 1.0
	v_cvt_scalef32_pk_f32_fp4 v[100:101], v137, 1.0 op_sel:[1,0,0]
	v_cvt_scalef32_pk_f32_fp4 v[102:103], v137, 1.0 op_sel:[0,1,0]
	v_cvt_scalef32_pk_f32_fp4 v[104:105], v137, 1.0 op_sel:[1,1,0]
	v_pk_fma_f32 v[90:91], v[32:33], v[98:99], v[90:91] op_sel:[1,0,0] op_sel_hi:[1,1,1]
	v_pk_fma_f32 v[92:93], v[32:33], v[100:101], v[92:93] op_sel:[1,0,0] op_sel_hi:[1,1,1]
	v_pk_fma_f32 v[94:95], v[32:33], v[102:103], v[94:95] op_sel:[1,0,0] op_sel_hi:[1,1,1]
	v_pk_fma_f32 v[96:97], v[32:33], v[104:105], v[96:97] op_sel:[1,0,0] op_sel_hi:[1,1,1]
	v_cvt_scalef32_pk_f32_fp4 v[98:99], v138, 1.0
	v_cvt_scalef32_pk_f32_fp4 v[100:101], v138, 1.0 op_sel:[1,0,0]
	v_cvt_scalef32_pk_f32_fp4 v[102:103], v138, 1.0 op_sel:[0,1,0]
	v_cvt_scalef32_pk_f32_fp4 v[104:105], v138, 1.0 op_sel:[1,1,0]
	v_pk_fma_f32 v[66:67], v[34:35], v[98:99], v[66:67] op_sel_hi:[0,1,1]
	v_pk_fma_f32 v[68:69], v[34:35], v[100:101], v[68:69] op_sel_hi:[0,1,1]
	v_pk_fma_f32 v[70:71], v[34:35], v[102:103], v[70:71] op_sel_hi:[0,1,1]
	v_pk_fma_f32 v[72:73], v[34:35], v[104:105], v[72:73] op_sel_hi:[0,1,1]
	v_cvt_scalef32_pk_f32_fp4 v[98:99], v139, 1.0
	v_cvt_scalef32_pk_f32_fp4 v[100:101], v139, 1.0 op_sel:[1,0,0]
	v_cvt_scalef32_pk_f32_fp4 v[102:103], v139, 1.0 op_sel:[0,1,0]
	v_cvt_scalef32_pk_f32_fp4 v[104:105], v139, 1.0 op_sel:[1,1,0]
	v_pk_fma_f32 v[74:75], v[34:35], v[98:99], v[74:75] op_sel_hi:[0,1,1]
	v_pk_fma_f32 v[76:77], v[34:35], v[100:101], v[76:77] op_sel_hi:[0,1,1]
	v_pk_fma_f32 v[78:79], v[34:35], v[102:103], v[78:79] op_sel_hi:[0,1,1]
	v_pk_fma_f32 v[80:81], v[34:35], v[104:105], v[80:81] op_sel_hi:[0,1,1]
	v_cvt_scalef32_pk_f32_fp4 v[98:99], v140, 1.0
	v_cvt_scalef32_pk_f32_fp4 v[100:101], v140, 1.0 op_sel:[1,0,0]
	v_cvt_scalef32_pk_f32_fp4 v[102:103], v140, 1.0 op_sel:[0,1,0]
	v_cvt_scalef32_pk_f32_fp4 v[104:105], v140, 1.0 op_sel:[1,1,0]
	v_pk_fma_f32 v[82:83], v[34:35], v[98:99], v[82:83] op_sel_hi:[0,1,1]
	v_pk_fma_f32 v[84:85], v[34:35], v[100:101], v[84:85] op_sel_hi:[0,1,1]
	v_pk_fma_f32 v[86:87], v[34:35], v[102:103], v[86:87] op_sel_hi:[0,1,1]
	v_pk_fma_f32 v[88:89], v[34:35], v[104:105], v[88:89] op_sel_hi:[0,1,1]
	v_cvt_scalef32_pk_f32_fp4 v[98:99], v141, 1.0
	v_cvt_scalef32_pk_f32_fp4 v[100:101], v141, 1.0 op_sel:[1,0,0]
	v_cvt_scalef32_pk_f32_fp4 v[102:103], v141, 1.0 op_sel:[0,1,0]
	v_cvt_scalef32_pk_f32_fp4 v[104:105], v141, 1.0 op_sel:[1,1,0]
	v_pk_fma_f32 v[90:91], v[34:35], v[98:99], v[90:91] op_sel_hi:[0,1,1]
	v_pk_fma_f32 v[92:93], v[34:35], v[100:101], v[92:93] op_sel_hi:[0,1,1]
	v_pk_fma_f32 v[94:95], v[34:35], v[102:103], v[94:95] op_sel_hi:[0,1,1]
	v_pk_fma_f32 v[96:97], v[34:35], v[104:105], v[96:97] op_sel_hi:[0,1,1]
	v_cvt_scalef32_pk_f32_fp4 v[98:99], v142, 1.0
	v_cvt_scalef32_pk_f32_fp4 v[100:101], v142, 1.0 op_sel:[1,0,0]
	v_cvt_scalef32_pk_f32_fp4 v[102:103], v142, 1.0 op_sel:[0,1,0]
	v_cvt_scalef32_pk_f32_fp4 v[104:105], v142, 1.0 op_sel:[1,1,0]
	v_pk_fma_f32 v[66:67], v[34:35], v[98:99], v[66:67] op_sel:[1,0,0] op_sel_hi:[1,1,1]
; __device__ __forceinline__ void phase_peer_v(const Params& p, int layer, int xs, int wid0, int wstride, bool last, char* smraw) {
;     ...
;   auto half_fma = [&](const u32x4 (&q)[8], const f32x4& c0, const f32x4& c1) {
; #pragma unroll
;     for (int i = 0; i < 8; ++i) {
;       const float ci = i < 4 ? c0[i & 3] : c1[i & 3];
; #pragma unroll
;       for (int m = 0; m < 4; ++m) {
;         unsigned dw = q[i][m];
;         asm volatile("" : "+v"(dw) : "v"(acc[(8 * m + 31) & 31]));
;         const f32x2 e0 = __builtin_amdgcn_cvt_scalef32_pk_f32_fp4(dw, 1.0f, 0), e1 = __builtin_amdgcn_cvt_scalef32_pk_f32_fp4(dw, 1.0f, 1);
;         const f32x2 e2 = __builtin_amdgcn_cvt_scalef32_pk_f32_fp4(dw, 1.0f, 2), e3 = __builtin_amdgcn_cvt_scalef32_pk_f32_fp4(dw, 1.0f, 3);
;         acc[8 * m + 0] += ci * e0[0]; acc[8 * m + 1] += ci * e0[1]; acc[8 * m + 2] += ci * e1[0]; acc[8 * m + 3] += ci * e1[1];
;         acc[8 * m + 4] += ci * e2[0]; acc[8 * m + 5] += ci * e2[1]; acc[8 * m + 6] += ci * e3[0]; acc[8 * m + 7] += ci * e3[1];
;       }
;     }
	v_pk_fma_f32 v[68:69], v[34:35], v[100:101], v[68:69] op_sel:[1,0,0] op_sel_hi:[1,1,1]
	v_pk_fma_f32 v[70:71], v[34:35], v[102:103], v[70:71] op_sel:[1,0,0] op_sel_hi:[1,1,1]
	v_pk_fma_f32 v[72:73], v[34:35], v[104:105], v[72:73] op_sel:[1,0,0] op_sel_hi:[1,1,1]
	v_cvt_scalef32_pk_f32_fp4 v[98:99], v143, 1.0
	v_cvt_scalef32_pk_f32_fp4 v[100:101], v143, 1.0 op_sel:[1,0,0]
	v_cvt_scalef32_pk_f32_fp4 v[102:103], v143, 1.0 op_sel:[0,1,0]
	v_cvt_scalef32_pk_f32_fp4 v[104:105], v143, 1.0 op_sel:[1,1,0]
	v_pk_fma_f32 v[74:75], v[34:35], v[98:99], v[74:75] op_sel:[1,0,0] op_sel_hi:[1,1,1]
	v_pk_fma_f32 v[76:77], v[34:35], v[100:101], v[76:77] op_sel:[1,0,0] op_sel_hi:[1,1,1]
	v_pk_fma_f32 v[78:79], v[34:35], v[102:103], v[78:79] op_sel:[1,0,0] op_sel_hi:[1,1,1]
	v_pk_fma_f32 v[80:81], v[34:35], v[104:105], v[80:81] op_sel:[1,0,0] op_sel_hi:[1,1,1]
	v_cvt_scalef32_pk_f32_fp4 v[98:99], v144, 1.0
	v_cvt_scalef32_pk_f32_fp4 v[100:101], v144, 1.0 op_sel:[1,0,0]
	v_cvt_scalef32_pk_f32_fp4 v[102:103], v144, 1.0 op_sel:[0,1,0]
	v_cvt_scalef32_pk_f32_fp4 v[104:105], v144, 1.0 op_sel:[1,1,0]
	v_pk_fma_f32 v[82:83], v[34:35], v[98:99], v[82:83] op_sel:[1,0,0] op_sel_hi:[1,1,1]
	v_pk_fma_f32 v[84:85], v[34:35], v[100:101], v[84:85] op_sel:[1,0,0] op_sel_hi:[1,1,1]
	v_pk_fma_f32 v[86:87], v[34:35], v[102:103], v[86:87] op_sel:[1,0,0] op_sel_hi:[1,1,1]
	v_pk_fma_f32 v[88:89], v[34:35], v[104:105], v[88:89] op_sel:[1,0,0] op_sel_hi:[1,1,1]
	v_cvt_scalef32_pk_f32_fp4 v[98:99], v145, 1.0
	v_cvt_scalef32_pk_f32_fp4 v[100:101], v145, 1.0 op_sel:[1,0,0]
	v_cvt_scalef32_pk_f32_fp4 v[102:103], v145, 1.0 op_sel:[0,1,0]
	v_cvt_scalef32_pk_f32_fp4 v[104:105], v145, 1.0 op_sel:[1,1,0]
	v_pk_fma_f32 v[90:91], v[34:35], v[98:99], v[90:91] op_sel:[1,0,0] op_sel_hi:[1,1,1]
	v_pk_fma_f32 v[92:93], v[34:35], v[100:101], v[92:93] op_sel:[1,0,0] op_sel_hi:[1,1,1]
	v_pk_fma_f32 v[94:95], v[34:35], v[102:103], v[94:95] op_sel:[1,0,0] op_sel_hi:[1,1,1]
	v_pk_fma_f32 v[96:97], v[34:35], v[104:105], v[96:97] op_sel:[1,0,0] op_sel_hi:[1,1,1]
	v_cvt_scalef32_pk_f32_fp4 v[98:99], v146, 1.0
	v_cvt_scalef32_pk_f32_fp4 v[100:101], v146, 1.0 op_sel:[1,0,0]
	v_cvt_scalef32_pk_f32_fp4 v[102:103], v146, 1.0 op_sel:[0,1,0]
	v_cvt_scalef32_pk_f32_fp4 v[104:105], v146, 1.0 op_sel:[1,1,0]
	v_pk_fma_f32 v[66:67], v[36:37], v[98:99], v[66:67] op_sel_hi:[0,1,1]
	v_pk_fma_f32 v[68:69], v[36:37], v[100:101], v[68:69] op_sel_hi:[0,1,1]
	v_pk_fma_f32 v[70:71], v[36:37], v[102:103], v[70:71] op_sel_hi:[0,1,1]
	v_pk_fma_f32 v[72:73], v[36:37], v[104:105], v[72:73] op_sel_hi:[0,1,1]
	v_cvt_scalef32_pk_f32_fp4 v[98:99], v147, 1.0
	v_cvt_scalef32_pk_f32_fp4 v[100:101], v147, 1.0 op_sel:[1,0,0]
	v_cvt_scalef32_pk_f32_fp4 v[102:103], v147, 1.0 op_sel:[0,1,0]
	v_cvt_scalef32_pk_f32_fp4 v[104:105], v147, 1.0 op_sel:[1,1,0]
	v_pk_fma_f32 v[74:75], v[36:37], v[98:99], v[74:75] op_sel_hi:[0,1,1]
	v_pk_fma_f32 v[76:77], v[36:37], v[100:101], v[76:77] op_sel_hi:[0,1,1]
	v_pk_fma_f32 v[78:79], v[36:37], v[102:103], v[78:79] op_sel_hi:[0,1,1]
	v_pk_fma_f32 v[80:81], v[36:37], v[104:105], v[80:81] op_sel_hi:[0,1,1]
	v_cvt_scalef32_pk_f32_fp4 v[98:99], v148, 1.0
	v_cvt_scalef32_pk_f32_fp4 v[100:101], v148, 1.0 op_sel:[1,0,0]
	v_cvt_scalef32_pk_f32_fp4 v[102:103], v148, 1.0 op_sel:[0,1,0]
	v_cvt_scalef32_pk_f32_fp4 v[104:105], v148, 1.0 op_sel:[1,1,0]
	v_pk_fma_f32 v[82:83], v[36:37], v[98:99], v[82:83] op_sel_hi:[0,1,1]
	v_pk_fma_f32 v[84:85], v[36:37], v[100:101], v[84:85] op_sel_hi:[0,1,1]
	v_pk_fma_f32 v[86:87], v[36:37], v[102:103], v[86:87] op_sel_hi:[0,1,1]
	v_pk_fma_f32 v[88:89], v[36:37], v[104:105], v[88:89] op_sel_hi:[0,1,1]
	v_cvt_scalef32_pk_f32_fp4 v[98:99], v149, 1.0
	v_cvt_scalef32_pk_f32_fp4 v[100:101], v149, 1.0 op_sel:[1,0,0]
	v_cvt_scalef32_pk_f32_fp4 v[102:103], v149, 1.0 op_sel:[0,1,0]
	v_cvt_scalef32_pk_f32_fp4 v[104:105], v149, 1.0 op_sel:[1,1,0]
	v_pk_fma_f32 v[90:91], v[36:37], v[98:99], v[90:91] op_sel_hi:[0,1,1]
	v_pk_fma_f32 v[92:93], v[36:37], v[100:101], v[92:93] op_sel_hi:[0,1,1]
	v_pk_fma_f32 v[94:95], v[36:37], v[102:103], v[94:95] op_sel_hi:[0,1,1]
	v_pk_fma_f32 v[96:97], v[36:37], v[104:105], v[96:97] op_sel_hi:[0,1,1]
	v_cvt_scalef32_pk_f32_fp4 v[98:99], v150, 1.0
	v_cvt_scalef32_pk_f32_fp4 v[100:101], v150, 1.0 op_sel:[1,0,0]
	v_cvt_scalef32_pk_f32_fp4 v[102:103], v150, 1.0 op_sel:[0,1,0]
	v_cvt_scalef32_pk_f32_fp4 v[104:105], v150, 1.0 op_sel:[1,1,0]
	v_pk_fma_f32 v[66:67], v[36:37], v[98:99], v[66:67] op_sel:[1,0,0] op_sel_hi:[1,1,1]
	v_pk_fma_f32 v[68:69], v[36:37], v[100:101], v[68:69] op_sel:[1,0,0] op_sel_hi:[1,1,1]
	v_pk_fma_f32 v[70:71], v[36:37], v[102:103], v[70:71] op_sel:[1,0,0] op_sel_hi:[1,1,1]
	v_pk_fma_f32 v[72:73], v[36:37], v[104:105], v[72:73] op_sel:[1,0,0] op_sel_hi:[1,1,1]
	v_cvt_scalef32_pk_f32_fp4 v[98:99], v151, 1.0
	v_cvt_scalef32_pk_f32_fp4 v[100:101], v151, 1.0 op_sel:[1,0,0]
	v_cvt_scalef32_pk_f32_fp4 v[102:103], v151, 1.0 op_sel:[0,1,0]
	v_cvt_scalef32_pk_f32_fp4 v[104:105], v151, 1.0 op_sel:[1,1,0]
	v_pk_fma_f32 v[74:75], v[36:37], v[98:99], v[74:75] op_sel:[1,0,0] op_sel_hi:[1,1,1]
	v_pk_fma_f32 v[76:77], v[36:37], v[100:101], v[76:77] op_sel:[1,0,0] op_sel_hi:[1,1,1]
	v_pk_fma_f32 v[78:79], v[36:37], v[102:103], v[78:79] op_sel:[1,0,0] op_sel_hi:[1,1,1]
	v_pk_fma_f32 v[80:81], v[36:37], v[104:105], v[80:81] op_sel:[1,0,0] op_sel_hi:[1,1,1]
	v_cvt_scalef32_pk_f32_fp4 v[98:99], v152, 1.0
	v_cvt_scalef32_pk_f32_fp4 v[100:101], v152, 1.0 op_sel:[1,0,0]
	v_cvt_scalef32_pk_f32_fp4 v[102:103], v152, 1.0 op_sel:[0,1,0]
	v_cvt_scalef32_pk_f32_fp4 v[104:105], v152, 1.0 op_sel:[1,1,0]
	v_pk_fma_f32 v[82:83], v[36:37], v[98:99], v[82:83] op_sel:[1,0,0] op_sel_hi:[1,1,1]
; __device__ __forceinline__ void phase_peer_v(const Params& p, int layer, int xs, int wid0, int wstride, bool last, char* smraw) {
;     ...
;   auto half_fma = [&](const u32x4 (&q)[8], const f32x4& c0, const f32x4& c1) {
; #pragma unroll
;     for (int i = 0; i < 8; ++i) {
;       const float ci = i < 4 ? c0[i & 3] : c1[i & 3];
; #pragma unroll
;       for (int m = 0; m < 4; ++m) {
;         unsigned dw = q[i][m];
;         asm volatile("" : "+v"(dw) : "v"(acc[(8 * m + 31) & 31]));
;         const f32x2 e0 = __builtin_amdgcn_cvt_scalef32_pk_f32_fp4(dw, 1.0f, 0), e1 = __builtin_amdgcn_cvt_scalef32_pk_f32_fp4(dw, 1.0f, 1);
;         const f32x2 e2 = __builtin_amdgcn_cvt_scalef32_pk_f32_fp4(dw, 1.0f, 2), e3 = __builtin_amdgcn_cvt_scalef32_pk_f32_fp4(dw, 1.0f, 3);
;         acc[8 * m + 0] += ci * e0[0]; acc[8 * m + 1] += ci * e0[1]; acc[8 * m + 2] += ci * e1[0]; acc[8 * m + 3] += ci * e1[1];
;         acc[8 * m + 4] += ci * e2[0]; acc[8 * m + 5] += ci * e2[1]; acc[8 * m + 6] += ci * e3[0]; acc[8 * m + 7] += ci * e3[1];
;       }
;     }
	v_pk_fma_f32 v[84:85], v[36:37], v[100:101], v[84:85] op_sel:[1,0,0] op_sel_hi:[1,1,1]
	v_pk_fma_f32 v[86:87], v[36:37], v[102:103], v[86:87] op_sel:[1,0,0] op_sel_hi:[1,1,1]
	v_pk_fma_f32 v[88:89], v[36:37], v[104:105], v[88:89] op_sel:[1,0,0] op_sel_hi:[1,1,1]
	v_cvt_scalef32_pk_f32_fp4 v[98:99], v153, 1.0
	v_cvt_scalef32_pk_f32_fp4 v[100:101], v153, 1.0 op_sel:[1,0,0]
	v_cvt_scalef32_pk_f32_fp4 v[102:103], v153, 1.0 op_sel:[0,1,0]
	v_cvt_scalef32_pk_f32_fp4 v[104:105], v153, 1.0 op_sel:[1,1,0]
	v_pk_fma_f32 v[90:91], v[36:37], v[98:99], v[90:91] op_sel:[1,0,0] op_sel_hi:[1,1,1]
	v_pk_fma_f32 v[92:93], v[36:37], v[100:101], v[92:93] op_sel:[1,0,0] op_sel_hi:[1,1,1]
	v_pk_fma_f32 v[94:95], v[36:37], v[102:103], v[94:95] op_sel:[1,0,0] op_sel_hi:[1,1,1]
	v_pk_fma_f32 v[96:97], v[36:37], v[104:105], v[96:97] op_sel:[1,0,0] op_sel_hi:[1,1,1]
	v_cvt_scalef32_pk_f32_fp4 v[98:99], v154, 1.0
	v_cvt_scalef32_pk_f32_fp4 v[100:101], v154, 1.0 op_sel:[1,0,0]
	v_cvt_scalef32_pk_f32_fp4 v[102:103], v154, 1.0 op_sel:[0,1,0]
	v_cvt_scalef32_pk_f32_fp4 v[104:105], v154, 1.0 op_sel:[1,1,0]
	v_pk_fma_f32 v[66:67], v[38:39], v[98:99], v[66:67] op_sel_hi:[0,1,1]
	v_pk_fma_f32 v[68:69], v[38:39], v[100:101], v[68:69] op_sel_hi:[0,1,1]
	v_pk_fma_f32 v[70:71], v[38:39], v[102:103], v[70:71] op_sel_hi:[0,1,1]
	v_pk_fma_f32 v[72:73], v[38:39], v[104:105], v[72:73] op_sel_hi:[0,1,1]
	v_cvt_scalef32_pk_f32_fp4 v[98:99], v155, 1.0
	v_cvt_scalef32_pk_f32_fp4 v[100:101], v155, 1.0 op_sel:[1,0,0]
	v_cvt_scalef32_pk_f32_fp4 v[102:103], v155, 1.0 op_sel:[0,1,0]
	v_cvt_scalef32_pk_f32_fp4 v[104:105], v155, 1.0 op_sel:[1,1,0]
	v_pk_fma_f32 v[74:75], v[38:39], v[98:99], v[74:75] op_sel_hi:[0,1,1]
	v_pk_fma_f32 v[76:77], v[38:39], v[100:101], v[76:77] op_sel_hi:[0,1,1]
	v_pk_fma_f32 v[78:79], v[38:39], v[102:103], v[78:79] op_sel_hi:[0,1,1]
	v_pk_fma_f32 v[80:81], v[38:39], v[104:105], v[80:81] op_sel_hi:[0,1,1]
	v_cvt_scalef32_pk_f32_fp4 v[98:99], v156, 1.0
	v_cvt_scalef32_pk_f32_fp4 v[100:101], v156, 1.0 op_sel:[1,0,0]
	v_cvt_scalef32_pk_f32_fp4 v[102:103], v156, 1.0 op_sel:[0,1,0]
	v_cvt_scalef32_pk_f32_fp4 v[104:105], v156, 1.0 op_sel:[1,1,0]
	v_pk_fma_f32 v[82:83], v[38:39], v[98:99], v[82:83] op_sel_hi:[0,1,1]
	v_pk_fma_f32 v[84:85], v[38:39], v[100:101], v[84:85] op_sel_hi:[0,1,1]
	v_pk_fma_f32 v[86:87], v[38:39], v[102:103], v[86:87] op_sel_hi:[0,1,1]
	v_pk_fma_f32 v[88:89], v[38:39], v[104:105], v[88:89] op_sel_hi:[0,1,1]
	v_cvt_scalef32_pk_f32_fp4 v[98:99], v157, 1.0
	v_cvt_scalef32_pk_f32_fp4 v[100:101], v157, 1.0 op_sel:[1,0,0]
	v_cvt_scalef32_pk_f32_fp4 v[102:103], v157, 1.0 op_sel:[0,1,0]
	v_cvt_scalef32_pk_f32_fp4 v[104:105], v157, 1.0 op_sel:[1,1,0]
	v_pk_fma_f32 v[90:91], v[38:39], v[98:99], v[90:91] op_sel_hi:[0,1,1]
	v_pk_fma_f32 v[92:93], v[38:39], v[100:101], v[92:93] op_sel_hi:[0,1,1]
	v_pk_fma_f32 v[94:95], v[38:39], v[102:103], v[94:95] op_sel_hi:[0,1,1]
	v_pk_fma_f32 v[96:97], v[38:39], v[104:105], v[96:97] op_sel_hi:[0,1,1]
	v_cvt_scalef32_pk_f32_fp4 v[98:99], v158, 1.0
	v_cvt_scalef32_pk_f32_fp4 v[100:101], v158, 1.0 op_sel:[1,0,0]
	v_cvt_scalef32_pk_f32_fp4 v[102:103], v158, 1.0 op_sel:[0,1,0]
	v_cvt_scalef32_pk_f32_fp4 v[104:105], v158, 1.0 op_sel:[1,1,0]
	v_pk_fma_f32 v[66:67], v[38:39], v[98:99], v[66:67] op_sel:[1,0,0] op_sel_hi:[1,1,1]
	v_pk_fma_f32 v[68:69], v[38:39], v[100:101], v[68:69] op_sel:[1,0,0] op_sel_hi:[1,1,1]
	v_pk_fma_f32 v[70:71], v[38:39], v[102:103], v[70:71] op_sel:[1,0,0] op_sel_hi:[1,1,1]
	v_pk_fma_f32 v[72:73], v[38:39], v[104:105], v[72:73] op_sel:[1,0,0] op_sel_hi:[1,1,1]
	v_cvt_scalef32_pk_f32_fp4 v[98:99], v159, 1.0
	v_cvt_scalef32_pk_f32_fp4 v[100:101], v159, 1.0 op_sel:[1,0,0]
	v_cvt_scalef32_pk_f32_fp4 v[102:103], v159, 1.0 op_sel:[0,1,0]
	v_cvt_scalef32_pk_f32_fp4 v[104:105], v159, 1.0 op_sel:[1,1,0]
	v_pk_fma_f32 v[74:75], v[38:39], v[98:99], v[74:75] op_sel:[1,0,0] op_sel_hi:[1,1,1]
	v_pk_fma_f32 v[76:77], v[38:39], v[100:101], v[76:77] op_sel:[1,0,0] op_sel_hi:[1,1,1]
	v_pk_fma_f32 v[78:79], v[38:39], v[102:103], v[78:79] op_sel:[1,0,0] op_sel_hi:[1,1,1]
	v_pk_fma_f32 v[80:81], v[38:39], v[104:105], v[80:81] op_sel:[1,0,0] op_sel_hi:[1,1,1]
	v_cvt_scalef32_pk_f32_fp4 v[98:99], v160, 1.0
	v_cvt_scalef32_pk_f32_fp4 v[100:101], v160, 1.0 op_sel:[1,0,0]
	v_cvt_scalef32_pk_f32_fp4 v[102:103], v160, 1.0 op_sel:[0,1,0]
	v_cvt_scalef32_pk_f32_fp4 v[104:105], v160, 1.0 op_sel:[1,1,0]
	v_pk_fma_f32 v[82:83], v[38:39], v[98:99], v[82:83] op_sel:[1,0,0] op_sel_hi:[1,1,1]
	v_pk_fma_f32 v[84:85], v[38:39], v[100:101], v[84:85] op_sel:[1,0,0] op_sel_hi:[1,1,1]
	v_pk_fma_f32 v[86:87], v[38:39], v[102:103], v[86:87] op_sel:[1,0,0] op_sel_hi:[1,1,1]
	v_pk_fma_f32 v[88:89], v[38:39], v[104:105], v[88:89] op_sel:[1,0,0] op_sel_hi:[1,1,1]
	v_cvt_scalef32_pk_f32_fp4 v[98:99], v161, 1.0
	v_cvt_scalef32_pk_f32_fp4 v[100:101], v161, 1.0 op_sel:[1,0,0]
	v_cvt_scalef32_pk_f32_fp4 v[102:103], v161, 1.0 op_sel:[0,1,0]
	v_cvt_scalef32_pk_f32_fp4 v[104:105], v161, 1.0 op_sel:[1,1,0]
	v_pk_fma_f32 v[90:91], v[38:39], v[98:99], v[90:91] op_sel:[1,0,0] op_sel_hi:[1,1,1]
	v_pk_fma_f32 v[92:93], v[38:39], v[100:101], v[92:93] op_sel:[1,0,0] op_sel_hi:[1,1,1]
	v_pk_fma_f32 v[94:95], v[38:39], v[102:103], v[94:95] op_sel:[1,0,0] op_sel_hi:[1,1,1]
	v_pk_fma_f32 v[96:97], v[38:39], v[104:105], v[96:97] op_sel:[1,0,0] op_sel_hi:[1,1,1]
	v_cvt_scalef32_pk_f32_fp4 v[98:99], v162, 1.0
	v_cvt_scalef32_pk_f32_fp4 v[100:101], v162, 1.0 op_sel:[1,0,0]
	v_cvt_scalef32_pk_f32_fp4 v[102:103], v162, 1.0 op_sel:[0,1,0]
	v_cvt_scalef32_pk_f32_fp4 v[104:105], v162, 1.0 op_sel:[1,1,0]
	v_pk_fma_f32 v[66:67], v[40:41], v[98:99], v[66:67] op_sel_hi:[0,1,1]
; __device__ __forceinline__ void phase_peer_v(const Params& p, int layer, int xs, int wid0, int wstride, bool last, char* smraw) {
;     ...
;   auto half_fma = [&](const u32x4 (&q)[8], const f32x4& c0, const f32x4& c1) {
; #pragma unroll
;     for (int i = 0; i < 8; ++i) {
;       const float ci = i < 4 ? c0[i & 3] : c1[i & 3];
; #pragma unroll
;       for (int m = 0; m < 4; ++m) {
;         unsigned dw = q[i][m];
;         asm volatile("" : "+v"(dw) : "v"(acc[(8 * m + 31) & 31]));
;         const f32x2 e0 = __builtin_amdgcn_cvt_scalef32_pk_f32_fp4(dw, 1.0f, 0), e1 = __builtin_amdgcn_cvt_scalef32_pk_f32_fp4(dw, 1.0f, 1);
;         const f32x2 e2 = __builtin_amdgcn_cvt_scalef32_pk_f32_fp4(dw, 1.0f, 2), e3 = __builtin_amdgcn_cvt_scalef32_pk_f32_fp4(dw, 1.0f, 3);
;         acc[8 * m + 0] += ci * e0[0]; acc[8 * m + 1] += ci * e0[1]; acc[8 * m + 2] += ci * e1[0]; acc[8 * m + 3] += ci * e1[1];
;         acc[8 * m + 4] += ci * e2[0]; acc[8 * m + 5] += ci * e2[1]; acc[8 * m + 6] += ci * e3[0]; acc[8 * m + 7] += ci * e3[1];
;       }
;     ...
;     for (int q4 = 0; q4 < 8; ++q4) *(f32x4*)(red + g * 256 + j * 32 + q4 * 4) = f32x4{acc[q4 * 4], acc[q4 * 4 + 1], acc[q4 * 4 + 2], acc[q4 * 4 + 3]};
;     __builtin_amdgcn_fence(__ATOMIC_RELEASE, "wavefront");
;     __builtin_amdgcn_wave_barrier();
;     __builtin_amdgcn_fence(__ATOMIC_ACQUIRE, "wavefront");
;     f32x4 r = {0.f, 0.f, 0.f, 0.f};
; #pragma unroll
;     for (int gg = 0; gg < 8; ++gg) { f32x4 v = *(const f32x4*)(red + gg * 256 + 4 * l); r += v; }
;     asm volatile("" ::: "memory");
;     __builtin_amdgcn_wave_barrier();
;     {
;       hv += r;
;       *(f32x4*)hq = hv;
;       if (!last) { u32x2 o; o[0] = cvtpk(hv[0], hv[1]); o[1] = cvtpk(hv[2], hv[3]); *(u32x2*)((char*)p.hb + ((unsigned)t * 2048u + (unsigned)(sl * 512 + l * 8))) = o; }
;     }
;     tt = tn;
	v_pk_fma_f32 v[68:69], v[40:41], v[100:101], v[68:69] op_sel_hi:[0,1,1]
	v_pk_fma_f32 v[70:71], v[40:41], v[102:103], v[70:71] op_sel_hi:[0,1,1]
	v_pk_fma_f32 v[72:73], v[40:41], v[104:105], v[72:73] op_sel_hi:[0,1,1]
	v_cvt_scalef32_pk_f32_fp4 v[98:99], v163, 1.0
	v_cvt_scalef32_pk_f32_fp4 v[100:101], v163, 1.0 op_sel:[1,0,0]
	v_cvt_scalef32_pk_f32_fp4 v[102:103], v163, 1.0 op_sel:[0,1,0]
	v_cvt_scalef32_pk_f32_fp4 v[104:105], v163, 1.0 op_sel:[1,1,0]
	v_pk_fma_f32 v[74:75], v[40:41], v[98:99], v[74:75] op_sel_hi:[0,1,1]
	v_pk_fma_f32 v[76:77], v[40:41], v[100:101], v[76:77] op_sel_hi:[0,1,1]
	v_pk_fma_f32 v[78:79], v[40:41], v[102:103], v[78:79] op_sel_hi:[0,1,1]
	v_pk_fma_f32 v[80:81], v[40:41], v[104:105], v[80:81] op_sel_hi:[0,1,1]
	v_cvt_scalef32_pk_f32_fp4 v[98:99], v164, 1.0
	v_cvt_scalef32_pk_f32_fp4 v[100:101], v164, 1.0 op_sel:[1,0,0]
	v_cvt_scalef32_pk_f32_fp4 v[102:103], v164, 1.0 op_sel:[0,1,0]
	v_cvt_scalef32_pk_f32_fp4 v[104:105], v164, 1.0 op_sel:[1,1,0]
	v_pk_fma_f32 v[82:83], v[40:41], v[98:99], v[82:83] op_sel_hi:[0,1,1]
	v_pk_fma_f32 v[84:85], v[40:41], v[100:101], v[84:85] op_sel_hi:[0,1,1]
	v_pk_fma_f32 v[86:87], v[40:41], v[102:103], v[86:87] op_sel_hi:[0,1,1]
	v_pk_fma_f32 v[88:89], v[40:41], v[104:105], v[88:89] op_sel_hi:[0,1,1]
	v_cvt_scalef32_pk_f32_fp4 v[98:99], v165, 1.0
	v_cvt_scalef32_pk_f32_fp4 v[100:101], v165, 1.0 op_sel:[1,0,0]
	v_cvt_scalef32_pk_f32_fp4 v[102:103], v165, 1.0 op_sel:[0,1,0]
	v_cvt_scalef32_pk_f32_fp4 v[104:105], v165, 1.0 op_sel:[1,1,0]
	v_pk_fma_f32 v[90:91], v[40:41], v[98:99], v[90:91] op_sel_hi:[0,1,1]
	v_pk_fma_f32 v[92:93], v[40:41], v[100:101], v[92:93] op_sel_hi:[0,1,1]
	v_pk_fma_f32 v[94:95], v[40:41], v[102:103], v[94:95] op_sel_hi:[0,1,1]
	v_pk_fma_f32 v[96:97], v[40:41], v[104:105], v[96:97] op_sel_hi:[0,1,1]
	v_cvt_scalef32_pk_f32_fp4 v[98:99], v166, 1.0
	v_cvt_scalef32_pk_f32_fp4 v[100:101], v166, 1.0 op_sel:[1,0,0]
	v_cvt_scalef32_pk_f32_fp4 v[102:103], v166, 1.0 op_sel:[0,1,0]
	v_cvt_scalef32_pk_f32_fp4 v[104:105], v166, 1.0 op_sel:[1,1,0]
	v_pk_fma_f32 v[66:67], v[40:41], v[98:99], v[66:67] op_sel:[1,0,0] op_sel_hi:[1,1,1]
	v_pk_fma_f32 v[68:69], v[40:41], v[100:101], v[68:69] op_sel:[1,0,0] op_sel_hi:[1,1,1]
	v_pk_fma_f32 v[70:71], v[40:41], v[102:103], v[70:71] op_sel:[1,0,0] op_sel_hi:[1,1,1]
	v_pk_fma_f32 v[72:73], v[40:41], v[104:105], v[72:73] op_sel:[1,0,0] op_sel_hi:[1,1,1]
	v_cvt_scalef32_pk_f32_fp4 v[98:99], v167, 1.0
	v_cvt_scalef32_pk_f32_fp4 v[100:101], v167, 1.0 op_sel:[1,0,0]
	v_cvt_scalef32_pk_f32_fp4 v[102:103], v167, 1.0 op_sel:[0,1,0]
	v_cvt_scalef32_pk_f32_fp4 v[104:105], v167, 1.0 op_sel:[1,1,0]
	v_pk_fma_f32 v[74:75], v[40:41], v[98:99], v[74:75] op_sel:[1,0,0] op_sel_hi:[1,1,1]
	v_pk_fma_f32 v[76:77], v[40:41], v[100:101], v[76:77] op_sel:[1,0,0] op_sel_hi:[1,1,1]
	v_pk_fma_f32 v[78:79], v[40:41], v[102:103], v[78:79] op_sel:[1,0,0] op_sel_hi:[1,1,1]
	v_pk_fma_f32 v[80:81], v[40:41], v[104:105], v[80:81] op_sel:[1,0,0] op_sel_hi:[1,1,1]
	v_cvt_scalef32_pk_f32_fp4 v[98:99], v168, 1.0
	v_cvt_scalef32_pk_f32_fp4 v[100:101], v168, 1.0 op_sel:[1,0,0]
	v_cvt_scalef32_pk_f32_fp4 v[102:103], v168, 1.0 op_sel:[0,1,0]
	v_cvt_scalef32_pk_f32_fp4 v[104:105], v168, 1.0 op_sel:[1,1,0]
	v_pk_fma_f32 v[82:83], v[40:41], v[98:99], v[82:83] op_sel:[1,0,0] op_sel_hi:[1,1,1]
	v_pk_fma_f32 v[84:85], v[40:41], v[100:101], v[84:85] op_sel:[1,0,0] op_sel_hi:[1,1,1]
	v_pk_fma_f32 v[86:87], v[40:41], v[102:103], v[86:87] op_sel:[1,0,0] op_sel_hi:[1,1,1]
	v_pk_fma_f32 v[88:89], v[40:41], v[104:105], v[88:89] op_sel:[1,0,0] op_sel_hi:[1,1,1]
	v_cvt_scalef32_pk_f32_fp4 v[98:99], v169, 1.0
	v_cvt_scalef32_pk_f32_fp4 v[100:101], v169, 1.0 op_sel:[1,0,0]
	v_cvt_scalef32_pk_f32_fp4 v[102:103], v169, 1.0 op_sel:[0,1,0]
	v_cvt_scalef32_pk_f32_fp4 v[104:105], v169, 1.0 op_sel:[1,1,0]
	v_pk_fma_f32 v[90:91], v[40:41], v[98:99], v[90:91] op_sel:[1,0,0] op_sel_hi:[1,1,1]
	v_pk_fma_f32 v[92:93], v[40:41], v[100:101], v[92:93] op_sel:[1,0,0] op_sel_hi:[1,1,1]
	v_pk_fma_f32 v[94:95], v[40:41], v[102:103], v[94:95] op_sel:[1,0,0] op_sel_hi:[1,1,1]
	v_pk_fma_f32 v[96:97], v[40:41], v[104:105], v[96:97] op_sel:[1,0,0] op_sel_hi:[1,1,1]
	ds_write_b128 v3, v[66:69]
	ds_write_b128 v3, v[70:73] offset:16
	ds_write_b128 v3, v[74:77] offset:32
	ds_write_b128 v3, v[78:81] offset:48
	ds_write_b128 v3, v[82:85] offset:64
	ds_write_b128 v3, v[86:89] offset:80
	ds_write_b128 v3, v[90:93] offset:96
	ds_write_b128 v3, v[94:97] offset:112
	s_waitcnt lgkmcnt(0)
	ds_read_b128 v[66:69], v4
	ds_read_b128 v[70:73], v4 offset:1024
	ds_read_b128 v[74:77], v4 offset:2048
	ds_read_b128 v[78:81], v4 offset:3072
	ds_read_b128 v[82:85], v4 offset:4096
	ds_read_b128 v[86:89], v4 offset:5120
	ds_read_b128 v[90:93], v4 offset:6144
	ds_read_b128 v[94:97], v4 offset:7168
	s_waitcnt lgkmcnt(6)
	v_pk_add_f32 v[66:67], v[66:67], v[70:71]
	v_pk_add_f32 v[68:69], v[68:69], v[72:73]
	s_waitcnt lgkmcnt(5)
	v_pk_add_f32 v[66:67], v[66:67], v[74:75]
	v_pk_add_f32 v[68:69], v[68:69], v[76:77]
	s_waitcnt lgkmcnt(4)
	v_pk_add_f32 v[66:67], v[66:67], v[78:79]
	v_pk_add_f32 v[68:69], v[68:69], v[80:81]
	s_waitcnt lgkmcnt(3)
	v_pk_add_f32 v[66:67], v[66:67], v[82:83]
	v_pk_add_f32 v[68:69], v[68:69], v[84:85]
	s_waitcnt lgkmcnt(2)
	v_pk_add_f32 v[66:67], v[66:67], v[86:87]
	v_pk_add_f32 v[68:69], v[68:69], v[88:89]
	s_waitcnt lgkmcnt(1)
	v_pk_add_f32 v[66:67], v[66:67], v[90:91]
	v_pk_add_f32 v[68:69], v[68:69], v[92:93]
	s_waitcnt lgkmcnt(0)
	v_pk_add_f32 v[66:67], v[66:67], v[94:95]
	v_pk_add_f32 v[68:69], v[68:69], v[96:97]
	v_pk_add_f32 v[58:59], v[58:59], v[66:67]
	v_pk_add_f32 v[60:61], v[60:61], v[68:69]
	global_store_dwordx4 v0, v[58:61], s[44:45]
	v_cvt_pk_bf16_f32 v98, v58, v59
	v_cvt_pk_bf16_f32 v99, v60, v61
	s_lshl_b32 s0, s36, 1
	s_add_u32 s0, s0, s28
	s_lshl_b32 s0, s0, 11
	s_lshl_b32 s1, s14, 9
	s_add_u32 s0, s0, s1
	v_add_u32_e32 v6, s0, v5
	global_store_dwordx2 v6, v[98:99], s[76:77]
	s_mov_b32 s36, s51
	s_cmp_lt_u32 s36, s38
	s_cbranch_scc0 .Lmy_pv0_done
; __device__ __forceinline__ void phase_peer_v(const Params& p, int layer, int xs, int wid0, int wstride, bool last, char* smraw) {
;     ...
;   while (tt < TH) {
;     const int tn = tt + wstride;
;     const int t = 2 * tt + par;
; #pragma unroll
;     for (int i = 0; i < 8; ++i) qA[i] = *(const u32x4*)(Vq + (ni[i >> 2][i & 3] * 128u + joff));
;     float* hq = hrow(p, t) + sl * 256 + 4 * l;
;     f32x4 hv = *(const f32x4*)hq;
;     const f32x4 c0 = nc[0], c1 = nc[1], c2 = nc[2], c3 = nc[3];
; #pragma unroll
;     for (int m = 0; m < 32; ++m) acc[m] = 0.f;
;     half_fma(qA, c0, c1);
; #pragma unroll
;     for (int i = 0; i < 8; ++i) qA[i] = *(const u32x4*)(Vq + (ni[2 + (i >> 2)][i & 3] * 128u + joff));
;     if (tn < TH) load_idx(tn);
.Lmy_pv0_bodyB:
	s_waitcnt vmcnt(2)
	s_add_u32 s51, s36, s33
	s_cmp_ge_u32 s51, s38
	s_cbranch_scc1 .Lmy_pv0_noissueB
	v_lshl_add_u32 v6, v10, 7, v1
	global_load_dwordx4 v[106:109], v6, s[40:41]
	v_lshl_add_u32 v7, v11, 7, v1
	global_load_dwordx4 v[110:113], v7, s[40:41]
	v_lshl_add_u32 v6, v12, 7, v1
	global_load_dwordx4 v[114:117], v6, s[40:41]
	v_lshl_add_u32 v7, v13, 7, v1
	global_load_dwordx4 v[118:121], v7, s[40:41]
	v_lshl_add_u32 v6, v14, 7, v1
	global_load_dwordx4 v[122:125], v6, s[40:41]
	v_lshl_add_u32 v7, v15, 7, v1
	global_load_dwordx4 v[126:129], v7, s[40:41]
	v_lshl_add_u32 v6, v16, 7, v1
	global_load_dwordx4 v[130:133], v6, s[40:41]
	v_lshl_add_u32 v7, v17, 7, v1
	global_load_dwordx4 v[134:137], v7, s[40:41]
	v_lshl_add_u32 v6, v18, 7, v1
	global_load_dwordx4 v[138:141], v6, s[40:41]
	v_lshl_add_u32 v7, v19, 7, v1
	global_load_dwordx4 v[142:145], v7, s[40:41]
	v_lshl_add_u32 v6, v20, 7, v1
	global_load_dwordx4 v[146:149], v6, s[40:41]
	v_lshl_add_u32 v7, v21, 7, v1
	global_load_dwordx4 v[150:153], v7, s[40:41]
	v_lshl_add_u32 v6, v22, 7, v1
	global_load_dwordx4 v[154:157], v6, s[40:41]
	v_lshl_add_u32 v7, v23, 7, v1
	global_load_dwordx4 v[158:161], v7, s[40:41]
	v_lshl_add_u32 v6, v24, 7, v1
	global_load_dwordx4 v[162:165], v6, s[40:41]
	v_lshl_add_u32 v7, v25, 7, v1
	global_load_dwordx4 v[166:169], v7, s[40:41]
	s_lshl_b32 s0, s51, 1
	s_add_u32 s0, s0, s28
	s_mul_hi_u32 s1, s0, s49
	s_mul_i32 s3, s1, 0x2010
	s_sub_u32 s3, s0, s3
	s_lshl_b32 s6, s1, 13
	s_add_u32 s6, s6, s3
	s_lshl_b32 s7, s1, 4
	s_add_u32 s7, s7, s3
	s_cmp_lt_u32 s3, 16
	s_cselect_b32 s6, s7, s6
	s_cselect_b32 s7, s12, s10
	s_cselect_b32 s8, s13, s11
	s_lshl_b32 s6, s6, 12
	s_add_u32 s6, s6, s39
	s_add_u32 s44, s7, s6
	s_addc_u32 s45, s8, 0
	global_load_dwordx4 v[58:61], v0, s[44:45]
	s_lshl_b32 s0, s51, 10
	v_add_u32_e32 v8, s0, v2
	global_load_dwordx4 v[26:29], v8, s[42:43]
	global_load_dwordx4 v[30:33], v8, s[42:43] offset:16
	global_load_dwordx4 v[34:37], v8, s[42:43] offset:32
	global_load_dwordx4 v[38:41], v8, s[42:43] offset:48
	s_add_u32 s9, s51, s33
	s_cmp_ge_u32 s9, s38
	s_cbranch_scc1 .Lmy_pv0_noissueB
	s_lshl_b32 s0, s9, 10
	v_add_u32_e32 v9, s0, v2
	global_load_dwordx4 v[10:13], v9, s[52:53]
	global_load_dwordx4 v[14:17], v9, s[52:53] offset:16
	global_load_dwordx4 v[18:21], v9, s[52:53] offset:32
	global_load_dwordx4 v[22:25], v9, s[52:53] offset:48
.Lmy_pv0_noissueB:
	v_cvt_scalef32_pk_f32_fp4 v[98:99], v170, 1.0
	v_cvt_scalef32_pk_f32_fp4 v[100:101], v170, 1.0 op_sel:[1,0,0]
	v_cvt_scalef32_pk_f32_fp4 v[102:103], v170, 1.0 op_sel:[0,1,0]
	v_cvt_scalef32_pk_f32_fp4 v[104:105], v170, 1.0 op_sel:[1,1,0]
	v_pk_fma_f32 v[66:67], v[42:43], v[98:99], 0 op_sel_hi:[0,1,0]
	v_pk_fma_f32 v[68:69], v[42:43], v[100:101], 0 op_sel_hi:[0,1,0]
	v_pk_fma_f32 v[70:71], v[42:43], v[102:103], 0 op_sel_hi:[0,1,0]
	v_pk_fma_f32 v[72:73], v[42:43], v[104:105], 0 op_sel_hi:[0,1,0]
	v_cvt_scalef32_pk_f32_fp4 v[98:99], v171, 1.0
	v_cvt_scalef32_pk_f32_fp4 v[100:101], v171, 1.0 op_sel:[1,0,0]
	v_cvt_scalef32_pk_f32_fp4 v[102:103], v171, 1.0 op_sel:[0,1,0]
	v_cvt_scalef32_pk_f32_fp4 v[104:105], v171, 1.0 op_sel:[1,1,0]
	v_pk_fma_f32 v[74:75], v[42:43], v[98:99], 0 op_sel_hi:[0,1,0]
	v_pk_fma_f32 v[76:77], v[42:43], v[100:101], 0 op_sel_hi:[0,1,0]
	v_pk_fma_f32 v[78:79], v[42:43], v[102:103], 0 op_sel_hi:[0,1,0]
	v_pk_fma_f32 v[80:81], v[42:43], v[104:105], 0 op_sel_hi:[0,1,0]
	v_cvt_scalef32_pk_f32_fp4 v[98:99], v172, 1.0
	v_cvt_scalef32_pk_f32_fp4 v[100:101], v172, 1.0 op_sel:[1,0,0]
	v_cvt_scalef32_pk_f32_fp4 v[102:103], v172, 1.0 op_sel:[0,1,0]
	v_cvt_scalef32_pk_f32_fp4 v[104:105], v172, 1.0 op_sel:[1,1,0]
	v_pk_fma_f32 v[82:83], v[42:43], v[98:99], 0 op_sel_hi:[0,1,0]
	v_pk_fma_f32 v[84:85], v[42:43], v[100:101], 0 op_sel_hi:[0,1,0]
	v_pk_fma_f32 v[86:87], v[42:43], v[102:103], 0 op_sel_hi:[0,1,0]
	v_pk_fma_f32 v[88:89], v[42:43], v[104:105], 0 op_sel_hi:[0,1,0]
	v_cvt_scalef32_pk_f32_fp4 v[98:99], v173, 1.0
	v_cvt_scalef32_pk_f32_fp4 v[100:101], v173, 1.0 op_sel:[1,0,0]
	v_cvt_scalef32_pk_f32_fp4 v[102:103], v173, 1.0 op_sel:[0,1,0]
	v_cvt_scalef32_pk_f32_fp4 v[104:105], v173, 1.0 op_sel:[1,1,0]
	v_pk_fma_f32 v[90:91], v[42:43], v[98:99], 0 op_sel_hi:[0,1,0]
	v_pk_fma_f32 v[92:93], v[42:43], v[100:101], 0 op_sel_hi:[0,1,0]
	v_pk_fma_f32 v[94:95], v[42:43], v[102:103], 0 op_sel_hi:[0,1,0]
	v_pk_fma_f32 v[96:97], v[42:43], v[104:105], 0 op_sel_hi:[0,1,0]
	v_cvt_scalef32_pk_f32_fp4 v[98:99], v174, 1.0
	v_cvt_scalef32_pk_f32_fp4 v[100:101], v174, 1.0 op_sel:[1,0,0]
	v_cvt_scalef32_pk_f32_fp4 v[102:103], v174, 1.0 op_sel:[0,1,0]
	v_cvt_scalef32_pk_f32_fp4 v[104:105], v174, 1.0 op_sel:[1,1,0]
	v_pk_fma_f32 v[66:67], v[42:43], v[98:99], v[66:67] op_sel:[1,0,0] op_sel_hi:[1,1,1]
	v_pk_fma_f32 v[68:69], v[42:43], v[100:101], v[68:69] op_sel:[1,0,0] op_sel_hi:[1,1,1]
	v_pk_fma_f32 v[70:71], v[42:43], v[102:103], v[70:71] op_sel:[1,0,0] op_sel_hi:[1,1,1]
	v_pk_fma_f32 v[72:73], v[42:43], v[104:105], v[72:73] op_sel:[1,0,0] op_sel_hi:[1,1,1]
	v_cvt_scalef32_pk_f32_fp4 v[98:99], v175, 1.0
	v_cvt_scalef32_pk_f32_fp4 v[100:101], v175, 1.0 op_sel:[1,0,0]
	v_cvt_scalef32_pk_f32_fp4 v[102:103], v175, 1.0 op_sel:[0,1,0]
	v_cvt_scalef32_pk_f32_fp4 v[104:105], v175, 1.0 op_sel:[1,1,0]
	v_pk_fma_f32 v[74:75], v[42:43], v[98:99], v[74:75] op_sel:[1,0,0] op_sel_hi:[1,1,1]
	v_pk_fma_f32 v[76:77], v[42:43], v[100:101], v[76:77] op_sel:[1,0,0] op_sel_hi:[1,1,1]
	v_pk_fma_f32 v[78:79], v[42:43], v[102:103], v[78:79] op_sel:[1,0,0] op_sel_hi:[1,1,1]
	v_pk_fma_f32 v[80:81], v[42:43], v[104:105], v[80:81] op_sel:[1,0,0] op_sel_hi:[1,1,1]
	v_cvt_scalef32_pk_f32_fp4 v[98:99], v176, 1.0
; __device__ __forceinline__ void phase_peer_v(const Params& p, int layer, int xs, int wid0, int wstride, bool last, char* smraw) {
;     ...
;   auto half_fma = [&](const u32x4 (&q)[8], const f32x4& c0, const f32x4& c1) {
; #pragma unroll
;     for (int i = 0; i < 8; ++i) {
;       const float ci = i < 4 ? c0[i & 3] : c1[i & 3];
; #pragma unroll
;       for (int m = 0; m < 4; ++m) {
;         unsigned dw = q[i][m];
;         asm volatile("" : "+v"(dw) : "v"(acc[(8 * m + 31) & 31]));
;         const f32x2 e0 = __builtin_amdgcn_cvt_scalef32_pk_f32_fp4(dw, 1.0f, 0), e1 = __builtin_amdgcn_cvt_scalef32_pk_f32_fp4(dw, 1.0f, 1);
;         const f32x2 e2 = __builtin_amdgcn_cvt_scalef32_pk_f32_fp4(dw, 1.0f, 2), e3 = __builtin_amdgcn_cvt_scalef32_pk_f32_fp4(dw, 1.0f, 3);
;         acc[8 * m + 0] += ci * e0[0]; acc[8 * m + 1] += ci * e0[1]; acc[8 * m + 2] += ci * e1[0]; acc[8 * m + 3] += ci * e1[1];
;         acc[8 * m + 4] += ci * e2[0]; acc[8 * m + 5] += ci * e2[1]; acc[8 * m + 6] += ci * e3[0]; acc[8 * m + 7] += ci * e3[1];
;       }
;     }
	v_cvt_scalef32_pk_f32_fp4 v[100:101], v176, 1.0 op_sel:[1,0,0]
	v_cvt_scalef32_pk_f32_fp4 v[102:103], v176, 1.0 op_sel:[0,1,0]
	v_cvt_scalef32_pk_f32_fp4 v[104:105], v176, 1.0 op_sel:[1,1,0]
	v_pk_fma_f32 v[82:83], v[42:43], v[98:99], v[82:83] op_sel:[1,0,0] op_sel_hi:[1,1,1]
	v_pk_fma_f32 v[84:85], v[42:43], v[100:101], v[84:85] op_sel:[1,0,0] op_sel_hi:[1,1,1]
	v_pk_fma_f32 v[86:87], v[42:43], v[102:103], v[86:87] op_sel:[1,0,0] op_sel_hi:[1,1,1]
	v_pk_fma_f32 v[88:89], v[42:43], v[104:105], v[88:89] op_sel:[1,0,0] op_sel_hi:[1,1,1]
	v_cvt_scalef32_pk_f32_fp4 v[98:99], v177, 1.0
	v_cvt_scalef32_pk_f32_fp4 v[100:101], v177, 1.0 op_sel:[1,0,0]
	v_cvt_scalef32_pk_f32_fp4 v[102:103], v177, 1.0 op_sel:[0,1,0]
	v_cvt_scalef32_pk_f32_fp4 v[104:105], v177, 1.0 op_sel:[1,1,0]
	v_pk_fma_f32 v[90:91], v[42:43], v[98:99], v[90:91] op_sel:[1,0,0] op_sel_hi:[1,1,1]
	v_pk_fma_f32 v[92:93], v[42:43], v[100:101], v[92:93] op_sel:[1,0,0] op_sel_hi:[1,1,1]
	v_pk_fma_f32 v[94:95], v[42:43], v[102:103], v[94:95] op_sel:[1,0,0] op_sel_hi:[1,1,1]
	v_pk_fma_f32 v[96:97], v[42:43], v[104:105], v[96:97] op_sel:[1,0,0] op_sel_hi:[1,1,1]
	v_cvt_scalef32_pk_f32_fp4 v[98:99], v178, 1.0
	v_cvt_scalef32_pk_f32_fp4 v[100:101], v178, 1.0 op_sel:[1,0,0]
	v_cvt_scalef32_pk_f32_fp4 v[102:103], v178, 1.0 op_sel:[0,1,0]
	v_cvt_scalef32_pk_f32_fp4 v[104:105], v178, 1.0 op_sel:[1,1,0]
	v_pk_fma_f32 v[66:67], v[44:45], v[98:99], v[66:67] op_sel_hi:[0,1,1]
	v_pk_fma_f32 v[68:69], v[44:45], v[100:101], v[68:69] op_sel_hi:[0,1,1]
	v_pk_fma_f32 v[70:71], v[44:45], v[102:103], v[70:71] op_sel_hi:[0,1,1]
	v_pk_fma_f32 v[72:73], v[44:45], v[104:105], v[72:73] op_sel_hi:[0,1,1]
	v_cvt_scalef32_pk_f32_fp4 v[98:99], v179, 1.0
	v_cvt_scalef32_pk_f32_fp4 v[100:101], v179, 1.0 op_sel:[1,0,0]
	v_cvt_scalef32_pk_f32_fp4 v[102:103], v179, 1.0 op_sel:[0,1,0]
	v_cvt_scalef32_pk_f32_fp4 v[104:105], v179, 1.0 op_sel:[1,1,0]
	v_pk_fma_f32 v[74:75], v[44:45], v[98:99], v[74:75] op_sel_hi:[0,1,1]
	v_pk_fma_f32 v[76:77], v[44:45], v[100:101], v[76:77] op_sel_hi:[0,1,1]
	v_pk_fma_f32 v[78:79], v[44:45], v[102:103], v[78:79] op_sel_hi:[0,1,1]
	v_pk_fma_f32 v[80:81], v[44:45], v[104:105], v[80:81] op_sel_hi:[0,1,1]
	v_cvt_scalef32_pk_f32_fp4 v[98:99], v180, 1.0
	v_cvt_scalef32_pk_f32_fp4 v[100:101], v180, 1.0 op_sel:[1,0,0]
	v_cvt_scalef32_pk_f32_fp4 v[102:103], v180, 1.0 op_sel:[0,1,0]
	v_cvt_scalef32_pk_f32_fp4 v[104:105], v180, 1.0 op_sel:[1,1,0]
	v_pk_fma_f32 v[82:83], v[44:45], v[98:99], v[82:83] op_sel_hi:[0,1,1]
	v_pk_fma_f32 v[84:85], v[44:45], v[100:101], v[84:85] op_sel_hi:[0,1,1]
	v_pk_fma_f32 v[86:87], v[44:45], v[102:103], v[86:87] op_sel_hi:[0,1,1]
	v_pk_fma_f32 v[88:89], v[44:45], v[104:105], v[88:89] op_sel_hi:[0,1,1]
	v_cvt_scalef32_pk_f32_fp4 v[98:99], v181, 1.0
	v_cvt_scalef32_pk_f32_fp4 v[100:101], v181, 1.0 op_sel:[1,0,0]
	v_cvt_scalef32_pk_f32_fp4 v[102:103], v181, 1.0 op_sel:[0,1,0]
	v_cvt_scalef32_pk_f32_fp4 v[104:105], v181, 1.0 op_sel:[1,1,0]
	v_pk_fma_f32 v[90:91], v[44:45], v[98:99], v[90:91] op_sel_hi:[0,1,1]
	v_pk_fma_f32 v[92:93], v[44:45], v[100:101], v[92:93] op_sel_hi:[0,1,1]
	v_pk_fma_f32 v[94:95], v[44:45], v[102:103], v[94:95] op_sel_hi:[0,1,1]
	v_pk_fma_f32 v[96:97], v[44:45], v[104:105], v[96:97] op_sel_hi:[0,1,1]
	v_cvt_scalef32_pk_f32_fp4 v[98:99], v182, 1.0
	v_cvt_scalef32_pk_f32_fp4 v[100:101], v182, 1.0 op_sel:[1,0,0]
	v_cvt_scalef32_pk_f32_fp4 v[102:103], v182, 1.0 op_sel:[0,1,0]
	v_cvt_scalef32_pk_f32_fp4 v[104:105], v182, 1.0 op_sel:[1,1,0]
	v_pk_fma_f32 v[66:67], v[44:45], v[98:99], v[66:67] op_sel:[1,0,0] op_sel_hi:[1,1,1]
	v_pk_fma_f32 v[68:69], v[44:45], v[100:101], v[68:69] op_sel:[1,0,0] op_sel_hi:[1,1,1]
	v_pk_fma_f32 v[70:71], v[44:45], v[102:103], v[70:71] op_sel:[1,0,0] op_sel_hi:[1,1,1]
	v_pk_fma_f32 v[72:73], v[44:45], v[104:105], v[72:73] op_sel:[1,0,0] op_sel_hi:[1,1,1]
	v_cvt_scalef32_pk_f32_fp4 v[98:99], v183, 1.0
	v_cvt_scalef32_pk_f32_fp4 v[100:101], v183, 1.0 op_sel:[1,0,0]
	v_cvt_scalef32_pk_f32_fp4 v[102:103], v183, 1.0 op_sel:[0,1,0]
	v_cvt_scalef32_pk_f32_fp4 v[104:105], v183, 1.0 op_sel:[1,1,0]
	v_pk_fma_f32 v[74:75], v[44:45], v[98:99], v[74:75] op_sel:[1,0,0] op_sel_hi:[1,1,1]
	v_pk_fma_f32 v[76:77], v[44:45], v[100:101], v[76:77] op_sel:[1,0,0] op_sel_hi:[1,1,1]
	v_pk_fma_f32 v[78:79], v[44:45], v[102:103], v[78:79] op_sel:[1,0,0] op_sel_hi:[1,1,1]
	v_pk_fma_f32 v[80:81], v[44:45], v[104:105], v[80:81] op_sel:[1,0,0] op_sel_hi:[1,1,1]
	v_cvt_scalef32_pk_f32_fp4 v[98:99], v184, 1.0
	v_cvt_scalef32_pk_f32_fp4 v[100:101], v184, 1.0 op_sel:[1,0,0]
	v_cvt_scalef32_pk_f32_fp4 v[102:103], v184, 1.0 op_sel:[0,1,0]
	v_cvt_scalef32_pk_f32_fp4 v[104:105], v184, 1.0 op_sel:[1,1,0]
	v_pk_fma_f32 v[82:83], v[44:45], v[98:99], v[82:83] op_sel:[1,0,0] op_sel_hi:[1,1,1]
	v_pk_fma_f32 v[84:85], v[44:45], v[100:101], v[84:85] op_sel:[1,0,0] op_sel_hi:[1,1,1]
	v_pk_fma_f32 v[86:87], v[44:45], v[102:103], v[86:87] op_sel:[1,0,0] op_sel_hi:[1,1,1]
	v_pk_fma_f32 v[88:89], v[44:45], v[104:105], v[88:89] op_sel:[1,0,0] op_sel_hi:[1,1,1]
	v_cvt_scalef32_pk_f32_fp4 v[98:99], v185, 1.0
	v_cvt_scalef32_pk_f32_fp4 v[100:101], v185, 1.0 op_sel:[1,0,0]
	v_cvt_scalef32_pk_f32_fp4 v[102:103], v185, 1.0 op_sel:[0,1,0]
	v_cvt_scalef32_pk_f32_fp4 v[104:105], v185, 1.0 op_sel:[1,1,0]
	v_pk_fma_f32 v[90:91], v[44:45], v[98:99], v[90:91] op_sel:[1,0,0] op_sel_hi:[1,1,1]
	v_pk_fma_f32 v[92:93], v[44:45], v[100:101], v[92:93] op_sel:[1,0,0] op_sel_hi:[1,1,1]
	v_pk_fma_f32 v[94:95], v[44:45], v[102:103], v[94:95] op_sel:[1,0,0] op_sel_hi:[1,1,1]
	v_pk_fma_f32 v[96:97], v[44:45], v[104:105], v[96:97] op_sel:[1,0,0] op_sel_hi:[1,1,1]
	v_cvt_scalef32_pk_f32_fp4 v[98:99], v192, 1.0
; __device__ __forceinline__ void phase_peer_v(const Params& p, int layer, int xs, int wid0, int wstride, bool last, char* smraw) {
;     ...
;   auto half_fma = [&](const u32x4 (&q)[8], const f32x4& c0, const f32x4& c1) {
; #pragma unroll
;     for (int i = 0; i < 8; ++i) {
;       const float ci = i < 4 ? c0[i & 3] : c1[i & 3];
; #pragma unroll
;       for (int m = 0; m < 4; ++m) {
;         unsigned dw = q[i][m];
;         asm volatile("" : "+v"(dw) : "v"(acc[(8 * m + 31) & 31]));
;         const f32x2 e0 = __builtin_amdgcn_cvt_scalef32_pk_f32_fp4(dw, 1.0f, 0), e1 = __builtin_amdgcn_cvt_scalef32_pk_f32_fp4(dw, 1.0f, 1);
;         const f32x2 e2 = __builtin_amdgcn_cvt_scalef32_pk_f32_fp4(dw, 1.0f, 2), e3 = __builtin_amdgcn_cvt_scalef32_pk_f32_fp4(dw, 1.0f, 3);
;         acc[8 * m + 0] += ci * e0[0]; acc[8 * m + 1] += ci * e0[1]; acc[8 * m + 2] += ci * e1[0]; acc[8 * m + 3] += ci * e1[1];
;         acc[8 * m + 4] += ci * e2[0]; acc[8 * m + 5] += ci * e2[1]; acc[8 * m + 6] += ci * e3[0]; acc[8 * m + 7] += ci * e3[1];
;       }
;     }
	v_cvt_scalef32_pk_f32_fp4 v[100:101], v192, 1.0 op_sel:[1,0,0]
	v_cvt_scalef32_pk_f32_fp4 v[102:103], v192, 1.0 op_sel:[0,1,0]
	v_cvt_scalef32_pk_f32_fp4 v[104:105], v192, 1.0 op_sel:[1,1,0]
	v_pk_fma_f32 v[66:67], v[46:47], v[98:99], v[66:67] op_sel_hi:[0,1,1]
	v_pk_fma_f32 v[68:69], v[46:47], v[100:101], v[68:69] op_sel_hi:[0,1,1]
	v_pk_fma_f32 v[70:71], v[46:47], v[102:103], v[70:71] op_sel_hi:[0,1,1]
	v_pk_fma_f32 v[72:73], v[46:47], v[104:105], v[72:73] op_sel_hi:[0,1,1]
	v_cvt_scalef32_pk_f32_fp4 v[98:99], v193, 1.0
	v_cvt_scalef32_pk_f32_fp4 v[100:101], v193, 1.0 op_sel:[1,0,0]
	v_cvt_scalef32_pk_f32_fp4 v[102:103], v193, 1.0 op_sel:[0,1,0]
	v_cvt_scalef32_pk_f32_fp4 v[104:105], v193, 1.0 op_sel:[1,1,0]
	v_pk_fma_f32 v[74:75], v[46:47], v[98:99], v[74:75] op_sel_hi:[0,1,1]
	v_pk_fma_f32 v[76:77], v[46:47], v[100:101], v[76:77] op_sel_hi:[0,1,1]
	v_pk_fma_f32 v[78:79], v[46:47], v[102:103], v[78:79] op_sel_hi:[0,1,1]
	v_pk_fma_f32 v[80:81], v[46:47], v[104:105], v[80:81] op_sel_hi:[0,1,1]
	v_cvt_scalef32_pk_f32_fp4 v[98:99], v194, 1.0
	v_cvt_scalef32_pk_f32_fp4 v[100:101], v194, 1.0 op_sel:[1,0,0]
	v_cvt_scalef32_pk_f32_fp4 v[102:103], v194, 1.0 op_sel:[0,1,0]
	v_cvt_scalef32_pk_f32_fp4 v[104:105], v194, 1.0 op_sel:[1,1,0]
	v_pk_fma_f32 v[82:83], v[46:47], v[98:99], v[82:83] op_sel_hi:[0,1,1]
	v_pk_fma_f32 v[84:85], v[46:47], v[100:101], v[84:85] op_sel_hi:[0,1,1]
	v_pk_fma_f32 v[86:87], v[46:47], v[102:103], v[86:87] op_sel_hi:[0,1,1]
	v_pk_fma_f32 v[88:89], v[46:47], v[104:105], v[88:89] op_sel_hi:[0,1,1]
	v_cvt_scalef32_pk_f32_fp4 v[98:99], v195, 1.0
	v_cvt_scalef32_pk_f32_fp4 v[100:101], v195, 1.0 op_sel:[1,0,0]
	v_cvt_scalef32_pk_f32_fp4 v[102:103], v195, 1.0 op_sel:[0,1,0]
	v_cvt_scalef32_pk_f32_fp4 v[104:105], v195, 1.0 op_sel:[1,1,0]
	v_pk_fma_f32 v[90:91], v[46:47], v[98:99], v[90:91] op_sel_hi:[0,1,1]
	v_pk_fma_f32 v[92:93], v[46:47], v[100:101], v[92:93] op_sel_hi:[0,1,1]
	v_pk_fma_f32 v[94:95], v[46:47], v[102:103], v[94:95] op_sel_hi:[0,1,1]
	v_pk_fma_f32 v[96:97], v[46:47], v[104:105], v[96:97] op_sel_hi:[0,1,1]
	v_cvt_scalef32_pk_f32_fp4 v[98:99], v196, 1.0
	v_cvt_scalef32_pk_f32_fp4 v[100:101], v196, 1.0 op_sel:[1,0,0]
	v_cvt_scalef32_pk_f32_fp4 v[102:103], v196, 1.0 op_sel:[0,1,0]
	v_cvt_scalef32_pk_f32_fp4 v[104:105], v196, 1.0 op_sel:[1,1,0]
	v_pk_fma_f32 v[66:67], v[46:47], v[98:99], v[66:67] op_sel:[1,0,0] op_sel_hi:[1,1,1]
	v_pk_fma_f32 v[68:69], v[46:47], v[100:101], v[68:69] op_sel:[1,0,0] op_sel_hi:[1,1,1]
	v_pk_fma_f32 v[70:71], v[46:47], v[102:103], v[70:71] op_sel:[1,0,0] op_sel_hi:[1,1,1]
	v_pk_fma_f32 v[72:73], v[46:47], v[104:105], v[72:73] op_sel:[1,0,0] op_sel_hi:[1,1,1]
	v_cvt_scalef32_pk_f32_fp4 v[98:99], v197, 1.0
	v_cvt_scalef32_pk_f32_fp4 v[100:101], v197, 1.0 op_sel:[1,0,0]
	v_cvt_scalef32_pk_f32_fp4 v[102:103], v197, 1.0 op_sel:[0,1,0]
	v_cvt_scalef32_pk_f32_fp4 v[104:105], v197, 1.0 op_sel:[1,1,0]
	v_pk_fma_f32 v[74:75], v[46:47], v[98:99], v[74:75] op_sel:[1,0,0] op_sel_hi:[1,1,1]
	v_pk_fma_f32 v[76:77], v[46:47], v[100:101], v[76:77] op_sel:[1,0,0] op_sel_hi:[1,1,1]
	v_pk_fma_f32 v[78:79], v[46:47], v[102:103], v[78:79] op_sel:[1,0,0] op_sel_hi:[1,1,1]
	v_pk_fma_f32 v[80:81], v[46:47], v[104:105], v[80:81] op_sel:[1,0,0] op_sel_hi:[1,1,1]
	v_cvt_scalef32_pk_f32_fp4 v[98:99], v198, 1.0
	v_cvt_scalef32_pk_f32_fp4 v[100:101], v198, 1.0 op_sel:[1,0,0]
	v_cvt_scalef32_pk_f32_fp4 v[102:103], v198, 1.0 op_sel:[0,1,0]
	v_cvt_scalef32_pk_f32_fp4 v[104:105], v198, 1.0 op_sel:[1,1,0]
	v_pk_fma_f32 v[82:83], v[46:47], v[98:99], v[82:83] op_sel:[1,0,0] op_sel_hi:[1,1,1]
	v_pk_fma_f32 v[84:85], v[46:47], v[100:101], v[84:85] op_sel:[1,0,0] op_sel_hi:[1,1,1]
	v_pk_fma_f32 v[86:87], v[46:47], v[102:103], v[86:87] op_sel:[1,0,0] op_sel_hi:[1,1,1]
	v_pk_fma_f32 v[88:89], v[46:47], v[104:105], v[88:89] op_sel:[1,0,0] op_sel_hi:[1,1,1]
	v_cvt_scalef32_pk_f32_fp4 v[98:99], v199, 1.0
	v_cvt_scalef32_pk_f32_fp4 v[100:101], v199, 1.0 op_sel:[1,0,0]
	v_cvt_scalef32_pk_f32_fp4 v[102:103], v199, 1.0 op_sel:[0,1,0]
	v_cvt_scalef32_pk_f32_fp4 v[104:105], v199, 1.0 op_sel:[1,1,0]
	v_pk_fma_f32 v[90:91], v[46:47], v[98:99], v[90:91] op_sel:[1,0,0] op_sel_hi:[1,1,1]
	v_pk_fma_f32 v[92:93], v[46:47], v[100:101], v[92:93] op_sel:[1,0,0] op_sel_hi:[1,1,1]
	v_pk_fma_f32 v[94:95], v[46:47], v[102:103], v[94:95] op_sel:[1,0,0] op_sel_hi:[1,1,1]
	v_pk_fma_f32 v[96:97], v[46:47], v[104:105], v[96:97] op_sel:[1,0,0] op_sel_hi:[1,1,1]
	v_cvt_scalef32_pk_f32_fp4 v[98:99], v200, 1.0
	v_cvt_scalef32_pk_f32_fp4 v[100:101], v200, 1.0 op_sel:[1,0,0]
	v_cvt_scalef32_pk_f32_fp4 v[102:103], v200, 1.0 op_sel:[0,1,0]
	v_cvt_scalef32_pk_f32_fp4 v[104:105], v200, 1.0 op_sel:[1,1,0]
	v_pk_fma_f32 v[66:67], v[48:49], v[98:99], v[66:67] op_sel_hi:[0,1,1]
	v_pk_fma_f32 v[68:69], v[48:49], v[100:101], v[68:69] op_sel_hi:[0,1,1]
	v_pk_fma_f32 v[70:71], v[48:49], v[102:103], v[70:71] op_sel_hi:[0,1,1]
	v_pk_fma_f32 v[72:73], v[48:49], v[104:105], v[72:73] op_sel_hi:[0,1,1]
	v_cvt_scalef32_pk_f32_fp4 v[98:99], v201, 1.0
	v_cvt_scalef32_pk_f32_fp4 v[100:101], v201, 1.0 op_sel:[1,0,0]
	v_cvt_scalef32_pk_f32_fp4 v[102:103], v201, 1.0 op_sel:[0,1,0]
	v_cvt_scalef32_pk_f32_fp4 v[104:105], v201, 1.0 op_sel:[1,1,0]
	v_pk_fma_f32 v[74:75], v[48:49], v[98:99], v[74:75] op_sel_hi:[0,1,1]
	v_pk_fma_f32 v[76:77], v[48:49], v[100:101], v[76:77] op_sel_hi:[0,1,1]
	v_pk_fma_f32 v[78:79], v[48:49], v[102:103], v[78:79] op_sel_hi:[0,1,1]
	v_pk_fma_f32 v[80:81], v[48:49], v[104:105], v[80:81] op_sel_hi:[0,1,1]
	v_cvt_scalef32_pk_f32_fp4 v[98:99], v202, 1.0
	v_cvt_scalef32_pk_f32_fp4 v[100:101], v202, 1.0 op_sel:[1,0,0]
	v_cvt_scalef32_pk_f32_fp4 v[102:103], v202, 1.0 op_sel:[0,1,0]
; __device__ __forceinline__ void phase_peer_v(const Params& p, int layer, int xs, int wid0, int wstride, bool last, char* smraw) {
;     ...
;   auto half_fma = [&](const u32x4 (&q)[8], const f32x4& c0, const f32x4& c1) {
; #pragma unroll
;     for (int i = 0; i < 8; ++i) {
;       const float ci = i < 4 ? c0[i & 3] : c1[i & 3];
; #pragma unroll
;       for (int m = 0; m < 4; ++m) {
;         unsigned dw = q[i][m];
;         asm volatile("" : "+v"(dw) : "v"(acc[(8 * m + 31) & 31]));
;         const f32x2 e0 = __builtin_amdgcn_cvt_scalef32_pk_f32_fp4(dw, 1.0f, 0), e1 = __builtin_amdgcn_cvt_scalef32_pk_f32_fp4(dw, 1.0f, 1);
;         const f32x2 e2 = __builtin_amdgcn_cvt_scalef32_pk_f32_fp4(dw, 1.0f, 2), e3 = __builtin_amdgcn_cvt_scalef32_pk_f32_fp4(dw, 1.0f, 3);
;         acc[8 * m + 0] += ci * e0[0]; acc[8 * m + 1] += ci * e0[1]; acc[8 * m + 2] += ci * e1[0]; acc[8 * m + 3] += ci * e1[1];
;         acc[8 * m + 4] += ci * e2[0]; acc[8 * m + 5] += ci * e2[1]; acc[8 * m + 6] += ci * e3[0]; acc[8 * m + 7] += ci * e3[1];
;       }
;     }
	v_cvt_scalef32_pk_f32_fp4 v[104:105], v202, 1.0 op_sel:[1,1,0]
	v_pk_fma_f32 v[82:83], v[48:49], v[98:99], v[82:83] op_sel_hi:[0,1,1]
	v_pk_fma_f32 v[84:85], v[48:49], v[100:101], v[84:85] op_sel_hi:[0,1,1]
	v_pk_fma_f32 v[86:87], v[48:49], v[102:103], v[86:87] op_sel_hi:[0,1,1]
	v_pk_fma_f32 v[88:89], v[48:49], v[104:105], v[88:89] op_sel_hi:[0,1,1]
	v_cvt_scalef32_pk_f32_fp4 v[98:99], v203, 1.0
	v_cvt_scalef32_pk_f32_fp4 v[100:101], v203, 1.0 op_sel:[1,0,0]
	v_cvt_scalef32_pk_f32_fp4 v[102:103], v203, 1.0 op_sel:[0,1,0]
	v_cvt_scalef32_pk_f32_fp4 v[104:105], v203, 1.0 op_sel:[1,1,0]
	v_pk_fma_f32 v[90:91], v[48:49], v[98:99], v[90:91] op_sel_hi:[0,1,1]
	v_pk_fma_f32 v[92:93], v[48:49], v[100:101], v[92:93] op_sel_hi:[0,1,1]
	v_pk_fma_f32 v[94:95], v[48:49], v[102:103], v[94:95] op_sel_hi:[0,1,1]
	v_pk_fma_f32 v[96:97], v[48:49], v[104:105], v[96:97] op_sel_hi:[0,1,1]
	v_cvt_scalef32_pk_f32_fp4 v[98:99], v204, 1.0
	v_cvt_scalef32_pk_f32_fp4 v[100:101], v204, 1.0 op_sel:[1,0,0]
	v_cvt_scalef32_pk_f32_fp4 v[102:103], v204, 1.0 op_sel:[0,1,0]
	v_cvt_scalef32_pk_f32_fp4 v[104:105], v204, 1.0 op_sel:[1,1,0]
	v_pk_fma_f32 v[66:67], v[48:49], v[98:99], v[66:67] op_sel:[1,0,0] op_sel_hi:[1,1,1]
	v_pk_fma_f32 v[68:69], v[48:49], v[100:101], v[68:69] op_sel:[1,0,0] op_sel_hi:[1,1,1]
	v_pk_fma_f32 v[70:71], v[48:49], v[102:103], v[70:71] op_sel:[1,0,0] op_sel_hi:[1,1,1]
	v_pk_fma_f32 v[72:73], v[48:49], v[104:105], v[72:73] op_sel:[1,0,0] op_sel_hi:[1,1,1]
	v_cvt_scalef32_pk_f32_fp4 v[98:99], v205, 1.0
	v_cvt_scalef32_pk_f32_fp4 v[100:101], v205, 1.0 op_sel:[1,0,0]
	v_cvt_scalef32_pk_f32_fp4 v[102:103], v205, 1.0 op_sel:[0,1,0]
	v_cvt_scalef32_pk_f32_fp4 v[104:105], v205, 1.0 op_sel:[1,1,0]
	v_pk_fma_f32 v[74:75], v[48:49], v[98:99], v[74:75] op_sel:[1,0,0] op_sel_hi:[1,1,1]
	v_pk_fma_f32 v[76:77], v[48:49], v[100:101], v[76:77] op_sel:[1,0,0] op_sel_hi:[1,1,1]
	v_pk_fma_f32 v[78:79], v[48:49], v[102:103], v[78:79] op_sel:[1,0,0] op_sel_hi:[1,1,1]
	v_pk_fma_f32 v[80:81], v[48:49], v[104:105], v[80:81] op_sel:[1,0,0] op_sel_hi:[1,1,1]
	v_cvt_scalef32_pk_f32_fp4 v[98:99], v206, 1.0
	v_cvt_scalef32_pk_f32_fp4 v[100:101], v206, 1.0 op_sel:[1,0,0]
	v_cvt_scalef32_pk_f32_fp4 v[102:103], v206, 1.0 op_sel:[0,1,0]
	v_cvt_scalef32_pk_f32_fp4 v[104:105], v206, 1.0 op_sel:[1,1,0]
	v_pk_fma_f32 v[82:83], v[48:49], v[98:99], v[82:83] op_sel:[1,0,0] op_sel_hi:[1,1,1]
	v_pk_fma_f32 v[84:85], v[48:49], v[100:101], v[84:85] op_sel:[1,0,0] op_sel_hi:[1,1,1]
	v_pk_fma_f32 v[86:87], v[48:49], v[102:103], v[86:87] op_sel:[1,0,0] op_sel_hi:[1,1,1]
	v_pk_fma_f32 v[88:89], v[48:49], v[104:105], v[88:89] op_sel:[1,0,0] op_sel_hi:[1,1,1]
	v_cvt_scalef32_pk_f32_fp4 v[98:99], v207, 1.0
	v_cvt_scalef32_pk_f32_fp4 v[100:101], v207, 1.0 op_sel:[1,0,0]
	v_cvt_scalef32_pk_f32_fp4 v[102:103], v207, 1.0 op_sel:[0,1,0]
	v_cvt_scalef32_pk_f32_fp4 v[104:105], v207, 1.0 op_sel:[1,1,0]
	v_pk_fma_f32 v[90:91], v[48:49], v[98:99], v[90:91] op_sel:[1,0,0] op_sel_hi:[1,1,1]
	v_pk_fma_f32 v[92:93], v[48:49], v[100:101], v[92:93] op_sel:[1,0,0] op_sel_hi:[1,1,1]
	v_pk_fma_f32 v[94:95], v[48:49], v[102:103], v[94:95] op_sel:[1,0,0] op_sel_hi:[1,1,1]
	v_pk_fma_f32 v[96:97], v[48:49], v[104:105], v[96:97] op_sel:[1,0,0] op_sel_hi:[1,1,1]
	v_cvt_scalef32_pk_f32_fp4 v[98:99], v208, 1.0
	v_cvt_scalef32_pk_f32_fp4 v[100:101], v208, 1.0 op_sel:[1,0,0]
	v_cvt_scalef32_pk_f32_fp4 v[102:103], v208, 1.0 op_sel:[0,1,0]
	v_cvt_scalef32_pk_f32_fp4 v[104:105], v208, 1.0 op_sel:[1,1,0]
	v_pk_fma_f32 v[66:67], v[50:51], v[98:99], v[66:67] op_sel_hi:[0,1,1]
	v_pk_fma_f32 v[68:69], v[50:51], v[100:101], v[68:69] op_sel_hi:[0,1,1]
	v_pk_fma_f32 v[70:71], v[50:51], v[102:103], v[70:71] op_sel_hi:[0,1,1]
	v_pk_fma_f32 v[72:73], v[50:51], v[104:105], v[72:73] op_sel_hi:[0,1,1]
	v_cvt_scalef32_pk_f32_fp4 v[98:99], v209, 1.0
	v_cvt_scalef32_pk_f32_fp4 v[100:101], v209, 1.0 op_sel:[1,0,0]
	v_cvt_scalef32_pk_f32_fp4 v[102:103], v209, 1.0 op_sel:[0,1,0]
	v_cvt_scalef32_pk_f32_fp4 v[104:105], v209, 1.0 op_sel:[1,1,0]
	v_pk_fma_f32 v[74:75], v[50:51], v[98:99], v[74:75] op_sel_hi:[0,1,1]
	v_pk_fma_f32 v[76:77], v[50:51], v[100:101], v[76:77] op_sel_hi:[0,1,1]
	v_pk_fma_f32 v[78:79], v[50:51], v[102:103], v[78:79] op_sel_hi:[0,1,1]
	v_pk_fma_f32 v[80:81], v[50:51], v[104:105], v[80:81] op_sel_hi:[0,1,1]
	v_cvt_scalef32_pk_f32_fp4 v[98:99], v210, 1.0
	v_cvt_scalef32_pk_f32_fp4 v[100:101], v210, 1.0 op_sel:[1,0,0]
	v_cvt_scalef32_pk_f32_fp4 v[102:103], v210, 1.0 op_sel:[0,1,0]
	v_cvt_scalef32_pk_f32_fp4 v[104:105], v210, 1.0 op_sel:[1,1,0]
	v_pk_fma_f32 v[82:83], v[50:51], v[98:99], v[82:83] op_sel_hi:[0,1,1]
	v_pk_fma_f32 v[84:85], v[50:51], v[100:101], v[84:85] op_sel_hi:[0,1,1]
	v_pk_fma_f32 v[86:87], v[50:51], v[102:103], v[86:87] op_sel_hi:[0,1,1]
	v_pk_fma_f32 v[88:89], v[50:51], v[104:105], v[88:89] op_sel_hi:[0,1,1]
	v_cvt_scalef32_pk_f32_fp4 v[98:99], v211, 1.0
	v_cvt_scalef32_pk_f32_fp4 v[100:101], v211, 1.0 op_sel:[1,0,0]
	v_cvt_scalef32_pk_f32_fp4 v[102:103], v211, 1.0 op_sel:[0,1,0]
	v_cvt_scalef32_pk_f32_fp4 v[104:105], v211, 1.0 op_sel:[1,1,0]
	v_pk_fma_f32 v[90:91], v[50:51], v[98:99], v[90:91] op_sel_hi:[0,1,1]
	v_pk_fma_f32 v[92:93], v[50:51], v[100:101], v[92:93] op_sel_hi:[0,1,1]
	v_pk_fma_f32 v[94:95], v[50:51], v[102:103], v[94:95] op_sel_hi:[0,1,1]
	v_pk_fma_f32 v[96:97], v[50:51], v[104:105], v[96:97] op_sel_hi:[0,1,1]
	v_cvt_scalef32_pk_f32_fp4 v[98:99], v212, 1.0
	v_cvt_scalef32_pk_f32_fp4 v[100:101], v212, 1.0 op_sel:[1,0,0]
	v_cvt_scalef32_pk_f32_fp4 v[102:103], v212, 1.0 op_sel:[0,1,0]
	v_cvt_scalef32_pk_f32_fp4 v[104:105], v212, 1.0 op_sel:[1,1,0]
	v_pk_fma_f32 v[66:67], v[50:51], v[98:99], v[66:67] op_sel:[1,0,0] op_sel_hi:[1,1,1]
; __device__ __forceinline__ void phase_peer_v(const Params& p, int layer, int xs, int wid0, int wstride, bool last, char* smraw) {
;     ...
;   auto half_fma = [&](const u32x4 (&q)[8], const f32x4& c0, const f32x4& c1) {
; #pragma unroll
;     for (int i = 0; i < 8; ++i) {
;       const float ci = i < 4 ? c0[i & 3] : c1[i & 3];
; #pragma unroll
;       for (int m = 0; m < 4; ++m) {
;         unsigned dw = q[i][m];
;         asm volatile("" : "+v"(dw) : "v"(acc[(8 * m + 31) & 31]));
;         const f32x2 e0 = __builtin_amdgcn_cvt_scalef32_pk_f32_fp4(dw, 1.0f, 0), e1 = __builtin_amdgcn_cvt_scalef32_pk_f32_fp4(dw, 1.0f, 1);
;         const f32x2 e2 = __builtin_amdgcn_cvt_scalef32_pk_f32_fp4(dw, 1.0f, 2), e3 = __builtin_amdgcn_cvt_scalef32_pk_f32_fp4(dw, 1.0f, 3);
;         acc[8 * m + 0] += ci * e0[0]; acc[8 * m + 1] += ci * e0[1]; acc[8 * m + 2] += ci * e1[0]; acc[8 * m + 3] += ci * e1[1];
;         acc[8 * m + 4] += ci * e2[0]; acc[8 * m + 5] += ci * e2[1]; acc[8 * m + 6] += ci * e3[0]; acc[8 * m + 7] += ci * e3[1];
;       }
;     }
	v_pk_fma_f32 v[68:69], v[50:51], v[100:101], v[68:69] op_sel:[1,0,0] op_sel_hi:[1,1,1]
	v_pk_fma_f32 v[70:71], v[50:51], v[102:103], v[70:71] op_sel:[1,0,0] op_sel_hi:[1,1,1]
	v_pk_fma_f32 v[72:73], v[50:51], v[104:105], v[72:73] op_sel:[1,0,0] op_sel_hi:[1,1,1]
	v_cvt_scalef32_pk_f32_fp4 v[98:99], v213, 1.0
	v_cvt_scalef32_pk_f32_fp4 v[100:101], v213, 1.0 op_sel:[1,0,0]
	v_cvt_scalef32_pk_f32_fp4 v[102:103], v213, 1.0 op_sel:[0,1,0]
	v_cvt_scalef32_pk_f32_fp4 v[104:105], v213, 1.0 op_sel:[1,1,0]
	v_pk_fma_f32 v[74:75], v[50:51], v[98:99], v[74:75] op_sel:[1,0,0] op_sel_hi:[1,1,1]
	v_pk_fma_f32 v[76:77], v[50:51], v[100:101], v[76:77] op_sel:[1,0,0] op_sel_hi:[1,1,1]
	v_pk_fma_f32 v[78:79], v[50:51], v[102:103], v[78:79] op_sel:[1,0,0] op_sel_hi:[1,1,1]
	v_pk_fma_f32 v[80:81], v[50:51], v[104:105], v[80:81] op_sel:[1,0,0] op_sel_hi:[1,1,1]
	v_cvt_scalef32_pk_f32_fp4 v[98:99], v214, 1.0
	v_cvt_scalef32_pk_f32_fp4 v[100:101], v214, 1.0 op_sel:[1,0,0]
	v_cvt_scalef32_pk_f32_fp4 v[102:103], v214, 1.0 op_sel:[0,1,0]
	v_cvt_scalef32_pk_f32_fp4 v[104:105], v214, 1.0 op_sel:[1,1,0]
	v_pk_fma_f32 v[82:83], v[50:51], v[98:99], v[82:83] op_sel:[1,0,0] op_sel_hi:[1,1,1]
	v_pk_fma_f32 v[84:85], v[50:51], v[100:101], v[84:85] op_sel:[1,0,0] op_sel_hi:[1,1,1]
	v_pk_fma_f32 v[86:87], v[50:51], v[102:103], v[86:87] op_sel:[1,0,0] op_sel_hi:[1,1,1]
	v_pk_fma_f32 v[88:89], v[50:51], v[104:105], v[88:89] op_sel:[1,0,0] op_sel_hi:[1,1,1]
	v_cvt_scalef32_pk_f32_fp4 v[98:99], v215, 1.0
	v_cvt_scalef32_pk_f32_fp4 v[100:101], v215, 1.0 op_sel:[1,0,0]
	v_cvt_scalef32_pk_f32_fp4 v[102:103], v215, 1.0 op_sel:[0,1,0]
	v_cvt_scalef32_pk_f32_fp4 v[104:105], v215, 1.0 op_sel:[1,1,0]
	v_pk_fma_f32 v[90:91], v[50:51], v[98:99], v[90:91] op_sel:[1,0,0] op_sel_hi:[1,1,1]
	v_pk_fma_f32 v[92:93], v[50:51], v[100:101], v[92:93] op_sel:[1,0,0] op_sel_hi:[1,1,1]
	v_pk_fma_f32 v[94:95], v[50:51], v[102:103], v[94:95] op_sel:[1,0,0] op_sel_hi:[1,1,1]
	v_pk_fma_f32 v[96:97], v[50:51], v[104:105], v[96:97] op_sel:[1,0,0] op_sel_hi:[1,1,1]
	v_cvt_scalef32_pk_f32_fp4 v[98:99], v216, 1.0
	v_cvt_scalef32_pk_f32_fp4 v[100:101], v216, 1.0 op_sel:[1,0,0]
	v_cvt_scalef32_pk_f32_fp4 v[102:103], v216, 1.0 op_sel:[0,1,0]
	v_cvt_scalef32_pk_f32_fp4 v[104:105], v216, 1.0 op_sel:[1,1,0]
	v_pk_fma_f32 v[66:67], v[52:53], v[98:99], v[66:67] op_sel_hi:[0,1,1]
	v_pk_fma_f32 v[68:69], v[52:53], v[100:101], v[68:69] op_sel_hi:[0,1,1]
	v_pk_fma_f32 v[70:71], v[52:53], v[102:103], v[70:71] op_sel_hi:[0,1,1]
	v_pk_fma_f32 v[72:73], v[52:53], v[104:105], v[72:73] op_sel_hi:[0,1,1]
	v_cvt_scalef32_pk_f32_fp4 v[98:99], v217, 1.0
	v_cvt_scalef32_pk_f32_fp4 v[100:101], v217, 1.0 op_sel:[1,0,0]
	v_cvt_scalef32_pk_f32_fp4 v[102:103], v217, 1.0 op_sel:[0,1,0]
	v_cvt_scalef32_pk_f32_fp4 v[104:105], v217, 1.0 op_sel:[1,1,0]
	v_pk_fma_f32 v[74:75], v[52:53], v[98:99], v[74:75] op_sel_hi:[0,1,1]
	v_pk_fma_f32 v[76:77], v[52:53], v[100:101], v[76:77] op_sel_hi:[0,1,1]
	v_pk_fma_f32 v[78:79], v[52:53], v[102:103], v[78:79] op_sel_hi:[0,1,1]
	v_pk_fma_f32 v[80:81], v[52:53], v[104:105], v[80:81] op_sel_hi:[0,1,1]
	v_cvt_scalef32_pk_f32_fp4 v[98:99], v218, 1.0
	v_cvt_scalef32_pk_f32_fp4 v[100:101], v218, 1.0 op_sel:[1,0,0]
	v_cvt_scalef32_pk_f32_fp4 v[102:103], v218, 1.0 op_sel:[0,1,0]
	v_cvt_scalef32_pk_f32_fp4 v[104:105], v218, 1.0 op_sel:[1,1,0]
	v_pk_fma_f32 v[82:83], v[52:53], v[98:99], v[82:83] op_sel_hi:[0,1,1]
	v_pk_fma_f32 v[84:85], v[52:53], v[100:101], v[84:85] op_sel_hi:[0,1,1]
	v_pk_fma_f32 v[86:87], v[52:53], v[102:103], v[86:87] op_sel_hi:[0,1,1]
	v_pk_fma_f32 v[88:89], v[52:53], v[104:105], v[88:89] op_sel_hi:[0,1,1]
	v_cvt_scalef32_pk_f32_fp4 v[98:99], v219, 1.0
	v_cvt_scalef32_pk_f32_fp4 v[100:101], v219, 1.0 op_sel:[1,0,0]
	v_cvt_scalef32_pk_f32_fp4 v[102:103], v219, 1.0 op_sel:[0,1,0]
	v_cvt_scalef32_pk_f32_fp4 v[104:105], v219, 1.0 op_sel:[1,1,0]
	v_pk_fma_f32 v[90:91], v[52:53], v[98:99], v[90:91] op_sel_hi:[0,1,1]
	v_pk_fma_f32 v[92:93], v[52:53], v[100:101], v[92:93] op_sel_hi:[0,1,1]
	v_pk_fma_f32 v[94:95], v[52:53], v[102:103], v[94:95] op_sel_hi:[0,1,1]
	v_pk_fma_f32 v[96:97], v[52:53], v[104:105], v[96:97] op_sel_hi:[0,1,1]
	v_cvt_scalef32_pk_f32_fp4 v[98:99], v220, 1.0
	v_cvt_scalef32_pk_f32_fp4 v[100:101], v220, 1.0 op_sel:[1,0,0]
	v_cvt_scalef32_pk_f32_fp4 v[102:103], v220, 1.0 op_sel:[0,1,0]
	v_cvt_scalef32_pk_f32_fp4 v[104:105], v220, 1.0 op_sel:[1,1,0]
	v_pk_fma_f32 v[66:67], v[52:53], v[98:99], v[66:67] op_sel:[1,0,0] op_sel_hi:[1,1,1]
	v_pk_fma_f32 v[68:69], v[52:53], v[100:101], v[68:69] op_sel:[1,0,0] op_sel_hi:[1,1,1]
	v_pk_fma_f32 v[70:71], v[52:53], v[102:103], v[70:71] op_sel:[1,0,0] op_sel_hi:[1,1,1]
	v_pk_fma_f32 v[72:73], v[52:53], v[104:105], v[72:73] op_sel:[1,0,0] op_sel_hi:[1,1,1]
	v_cvt_scalef32_pk_f32_fp4 v[98:99], v221, 1.0
	v_cvt_scalef32_pk_f32_fp4 v[100:101], v221, 1.0 op_sel:[1,0,0]
	v_cvt_scalef32_pk_f32_fp4 v[102:103], v221, 1.0 op_sel:[0,1,0]
	v_cvt_scalef32_pk_f32_fp4 v[104:105], v221, 1.0 op_sel:[1,1,0]
	v_pk_fma_f32 v[74:75], v[52:53], v[98:99], v[74:75] op_sel:[1,0,0] op_sel_hi:[1,1,1]
	v_pk_fma_f32 v[76:77], v[52:53], v[100:101], v[76:77] op_sel:[1,0,0] op_sel_hi:[1,1,1]
	v_pk_fma_f32 v[78:79], v[52:53], v[102:103], v[78:79] op_sel:[1,0,0] op_sel_hi:[1,1,1]
	v_pk_fma_f32 v[80:81], v[52:53], v[104:105], v[80:81] op_sel:[1,0,0] op_sel_hi:[1,1,1]
	v_cvt_scalef32_pk_f32_fp4 v[98:99], v222, 1.0
	v_cvt_scalef32_pk_f32_fp4 v[100:101], v222, 1.0 op_sel:[1,0,0]
	v_cvt_scalef32_pk_f32_fp4 v[102:103], v222, 1.0 op_sel:[0,1,0]
	v_cvt_scalef32_pk_f32_fp4 v[104:105], v222, 1.0 op_sel:[1,1,0]
	v_pk_fma_f32 v[82:83], v[52:53], v[98:99], v[82:83] op_sel:[1,0,0] op_sel_hi:[1,1,1]
; __device__ __forceinline__ void phase_peer_v(const Params& p, int layer, int xs, int wid0, int wstride, bool last, char* smraw) {
;     ...
;   auto half_fma = [&](const u32x4 (&q)[8], const f32x4& c0, const f32x4& c1) {
; #pragma unroll
;     for (int i = 0; i < 8; ++i) {
;       const float ci = i < 4 ? c0[i & 3] : c1[i & 3];
; #pragma unroll
;       for (int m = 0; m < 4; ++m) {
;         unsigned dw = q[i][m];
;         asm volatile("" : "+v"(dw) : "v"(acc[(8 * m + 31) & 31]));
;         const f32x2 e0 = __builtin_amdgcn_cvt_scalef32_pk_f32_fp4(dw, 1.0f, 0), e1 = __builtin_amdgcn_cvt_scalef32_pk_f32_fp4(dw, 1.0f, 1);
;         const f32x2 e2 = __builtin_amdgcn_cvt_scalef32_pk_f32_fp4(dw, 1.0f, 2), e3 = __builtin_amdgcn_cvt_scalef32_pk_f32_fp4(dw, 1.0f, 3);
;         acc[8 * m + 0] += ci * e0[0]; acc[8 * m + 1] += ci * e0[1]; acc[8 * m + 2] += ci * e1[0]; acc[8 * m + 3] += ci * e1[1];
;         acc[8 * m + 4] += ci * e2[0]; acc[8 * m + 5] += ci * e2[1]; acc[8 * m + 6] += ci * e3[0]; acc[8 * m + 7] += ci * e3[1];
;       }
;     }
	v_pk_fma_f32 v[84:85], v[52:53], v[100:101], v[84:85] op_sel:[1,0,0] op_sel_hi:[1,1,1]
	v_pk_fma_f32 v[86:87], v[52:53], v[102:103], v[86:87] op_sel:[1,0,0] op_sel_hi:[1,1,1]
	v_pk_fma_f32 v[88:89], v[52:53], v[104:105], v[88:89] op_sel:[1,0,0] op_sel_hi:[1,1,1]
	v_cvt_scalef32_pk_f32_fp4 v[98:99], v223, 1.0
	v_cvt_scalef32_pk_f32_fp4 v[100:101], v223, 1.0 op_sel:[1,0,0]
	v_cvt_scalef32_pk_f32_fp4 v[102:103], v223, 1.0 op_sel:[0,1,0]
	v_cvt_scalef32_pk_f32_fp4 v[104:105], v223, 1.0 op_sel:[1,1,0]
	v_pk_fma_f32 v[90:91], v[52:53], v[98:99], v[90:91] op_sel:[1,0,0] op_sel_hi:[1,1,1]
	v_pk_fma_f32 v[92:93], v[52:53], v[100:101], v[92:93] op_sel:[1,0,0] op_sel_hi:[1,1,1]
	v_pk_fma_f32 v[94:95], v[52:53], v[102:103], v[94:95] op_sel:[1,0,0] op_sel_hi:[1,1,1]
	v_pk_fma_f32 v[96:97], v[52:53], v[104:105], v[96:97] op_sel:[1,0,0] op_sel_hi:[1,1,1]
	v_cvt_scalef32_pk_f32_fp4 v[98:99], v224, 1.0
	v_cvt_scalef32_pk_f32_fp4 v[100:101], v224, 1.0 op_sel:[1,0,0]
	v_cvt_scalef32_pk_f32_fp4 v[102:103], v224, 1.0 op_sel:[0,1,0]
	v_cvt_scalef32_pk_f32_fp4 v[104:105], v224, 1.0 op_sel:[1,1,0]
	v_pk_fma_f32 v[66:67], v[54:55], v[98:99], v[66:67] op_sel_hi:[0,1,1]
	v_pk_fma_f32 v[68:69], v[54:55], v[100:101], v[68:69] op_sel_hi:[0,1,1]
	v_pk_fma_f32 v[70:71], v[54:55], v[102:103], v[70:71] op_sel_hi:[0,1,1]
	v_pk_fma_f32 v[72:73], v[54:55], v[104:105], v[72:73] op_sel_hi:[0,1,1]
	v_cvt_scalef32_pk_f32_fp4 v[98:99], v225, 1.0
	v_cvt_scalef32_pk_f32_fp4 v[100:101], v225, 1.0 op_sel:[1,0,0]
	v_cvt_scalef32_pk_f32_fp4 v[102:103], v225, 1.0 op_sel:[0,1,0]
	v_cvt_scalef32_pk_f32_fp4 v[104:105], v225, 1.0 op_sel:[1,1,0]
	v_pk_fma_f32 v[74:75], v[54:55], v[98:99], v[74:75] op_sel_hi:[0,1,1]
	v_pk_fma_f32 v[76:77], v[54:55], v[100:101], v[76:77] op_sel_hi:[0,1,1]
	v_pk_fma_f32 v[78:79], v[54:55], v[102:103], v[78:79] op_sel_hi:[0,1,1]
	v_pk_fma_f32 v[80:81], v[54:55], v[104:105], v[80:81] op_sel_hi:[0,1,1]
	v_cvt_scalef32_pk_f32_fp4 v[98:99], v226, 1.0
	v_cvt_scalef32_pk_f32_fp4 v[100:101], v226, 1.0 op_sel:[1,0,0]
	v_cvt_scalef32_pk_f32_fp4 v[102:103], v226, 1.0 op_sel:[0,1,0]
	v_cvt_scalef32_pk_f32_fp4 v[104:105], v226, 1.0 op_sel:[1,1,0]
	v_pk_fma_f32 v[82:83], v[54:55], v[98:99], v[82:83] op_sel_hi:[0,1,1]
	v_pk_fma_f32 v[84:85], v[54:55], v[100:101], v[84:85] op_sel_hi:[0,1,1]
	v_pk_fma_f32 v[86:87], v[54:55], v[102:103], v[86:87] op_sel_hi:[0,1,1]
	v_pk_fma_f32 v[88:89], v[54:55], v[104:105], v[88:89] op_sel_hi:[0,1,1]
	v_cvt_scalef32_pk_f32_fp4 v[98:99], v227, 1.0
	v_cvt_scalef32_pk_f32_fp4 v[100:101], v227, 1.0 op_sel:[1,0,0]
	v_cvt_scalef32_pk_f32_fp4 v[102:103], v227, 1.0 op_sel:[0,1,0]
	v_cvt_scalef32_pk_f32_fp4 v[104:105], v227, 1.0 op_sel:[1,1,0]
	v_pk_fma_f32 v[90:91], v[54:55], v[98:99], v[90:91] op_sel_hi:[0,1,1]
	v_pk_fma_f32 v[92:93], v[54:55], v[100:101], v[92:93] op_sel_hi:[0,1,1]
	v_pk_fma_f32 v[94:95], v[54:55], v[102:103], v[94:95] op_sel_hi:[0,1,1]
	v_pk_fma_f32 v[96:97], v[54:55], v[104:105], v[96:97] op_sel_hi:[0,1,1]
	v_cvt_scalef32_pk_f32_fp4 v[98:99], v228, 1.0
	v_cvt_scalef32_pk_f32_fp4 v[100:101], v228, 1.0 op_sel:[1,0,0]
	v_cvt_scalef32_pk_f32_fp4 v[102:103], v228, 1.0 op_sel:[0,1,0]
	v_cvt_scalef32_pk_f32_fp4 v[104:105], v228, 1.0 op_sel:[1,1,0]
	v_pk_fma_f32 v[66:67], v[54:55], v[98:99], v[66:67] op_sel:[1,0,0] op_sel_hi:[1,1,1]
	v_pk_fma_f32 v[68:69], v[54:55], v[100:101], v[68:69] op_sel:[1,0,0] op_sel_hi:[1,1,1]
	v_pk_fma_f32 v[70:71], v[54:55], v[102:103], v[70:71] op_sel:[1,0,0] op_sel_hi:[1,1,1]
	v_pk_fma_f32 v[72:73], v[54:55], v[104:105], v[72:73] op_sel:[1,0,0] op_sel_hi:[1,1,1]
	v_cvt_scalef32_pk_f32_fp4 v[98:99], v229, 1.0
	v_cvt_scalef32_pk_f32_fp4 v[100:101], v229, 1.0 op_sel:[1,0,0]
	v_cvt_scalef32_pk_f32_fp4 v[102:103], v229, 1.0 op_sel:[0,1,0]
	v_cvt_scalef32_pk_f32_fp4 v[104:105], v229, 1.0 op_sel:[1,1,0]
	v_pk_fma_f32 v[74:75], v[54:55], v[98:99], v[74:75] op_sel:[1,0,0] op_sel_hi:[1,1,1]
	v_pk_fma_f32 v[76:77], v[54:55], v[100:101], v[76:77] op_sel:[1,0,0] op_sel_hi:[1,1,1]
	v_pk_fma_f32 v[78:79], v[54:55], v[102:103], v[78:79] op_sel:[1,0,0] op_sel_hi:[1,1,1]
	v_pk_fma_f32 v[80:81], v[54:55], v[104:105], v[80:81] op_sel:[1,0,0] op_sel_hi:[1,1,1]
	v_cvt_scalef32_pk_f32_fp4 v[98:99], v230, 1.0
	v_cvt_scalef32_pk_f32_fp4 v[100:101], v230, 1.0 op_sel:[1,0,0]
	v_cvt_scalef32_pk_f32_fp4 v[102:103], v230, 1.0 op_sel:[0,1,0]
	v_cvt_scalef32_pk_f32_fp4 v[104:105], v230, 1.0 op_sel:[1,1,0]
	v_pk_fma_f32 v[82:83], v[54:55], v[98:99], v[82:83] op_sel:[1,0,0] op_sel_hi:[1,1,1]
	v_pk_fma_f32 v[84:85], v[54:55], v[100:101], v[84:85] op_sel:[1,0,0] op_sel_hi:[1,1,1]
	v_pk_fma_f32 v[86:87], v[54:55], v[102:103], v[86:87] op_sel:[1,0,0] op_sel_hi:[1,1,1]
	v_pk_fma_f32 v[88:89], v[54:55], v[104:105], v[88:89] op_sel:[1,0,0] op_sel_hi:[1,1,1]
	v_cvt_scalef32_pk_f32_fp4 v[98:99], v231, 1.0
	v_cvt_scalef32_pk_f32_fp4 v[100:101], v231, 1.0 op_sel:[1,0,0]
	v_cvt_scalef32_pk_f32_fp4 v[102:103], v231, 1.0 op_sel:[0,1,0]
	v_cvt_scalef32_pk_f32_fp4 v[104:105], v231, 1.0 op_sel:[1,1,0]
	v_pk_fma_f32 v[90:91], v[54:55], v[98:99], v[90:91] op_sel:[1,0,0] op_sel_hi:[1,1,1]
	v_pk_fma_f32 v[92:93], v[54:55], v[100:101], v[92:93] op_sel:[1,0,0] op_sel_hi:[1,1,1]
	v_pk_fma_f32 v[94:95], v[54:55], v[102:103], v[94:95] op_sel:[1,0,0] op_sel_hi:[1,1,1]
	v_pk_fma_f32 v[96:97], v[54:55], v[104:105], v[96:97] op_sel:[1,0,0] op_sel_hi:[1,1,1]
	v_cvt_scalef32_pk_f32_fp4 v[98:99], v232, 1.0
	v_cvt_scalef32_pk_f32_fp4 v[100:101], v232, 1.0 op_sel:[1,0,0]
	v_cvt_scalef32_pk_f32_fp4 v[102:103], v232, 1.0 op_sel:[0,1,0]
	v_cvt_scalef32_pk_f32_fp4 v[104:105], v232, 1.0 op_sel:[1,1,0]
	v_pk_fma_f32 v[66:67], v[56:57], v[98:99], v[66:67] op_sel_hi:[0,1,1]
; __device__ __forceinline__ void phase_peer_v(const Params& p, int layer, int xs, int wid0, int wstride, bool last, char* smraw) {
;     ...
;   auto half_fma = [&](const u32x4 (&q)[8], const f32x4& c0, const f32x4& c1) {
; #pragma unroll
;     for (int i = 0; i < 8; ++i) {
;       const float ci = i < 4 ? c0[i & 3] : c1[i & 3];
; #pragma unroll
;       for (int m = 0; m < 4; ++m) {
;         unsigned dw = q[i][m];
;         asm volatile("" : "+v"(dw) : "v"(acc[(8 * m + 31) & 31]));
;         const f32x2 e0 = __builtin_amdgcn_cvt_scalef32_pk_f32_fp4(dw, 1.0f, 0), e1 = __builtin_amdgcn_cvt_scalef32_pk_f32_fp4(dw, 1.0f, 1);
;         const f32x2 e2 = __builtin_amdgcn_cvt_scalef32_pk_f32_fp4(dw, 1.0f, 2), e3 = __builtin_amdgcn_cvt_scalef32_pk_f32_fp4(dw, 1.0f, 3);
;         acc[8 * m + 0] += ci * e0[0]; acc[8 * m + 1] += ci * e0[1]; acc[8 * m + 2] += ci * e1[0]; acc[8 * m + 3] += ci * e1[1];
;         acc[8 * m + 4] += ci * e2[0]; acc[8 * m + 5] += ci * e2[1]; acc[8 * m + 6] += ci * e3[0]; acc[8 * m + 7] += ci * e3[1];
;       }
;     ...
;     for (int q4 = 0; q4 < 8; ++q4) *(f32x4*)(red + g * 256 + j * 32 + q4 * 4) = f32x4{acc[q4 * 4], acc[q4 * 4 + 1], acc[q4 * 4 + 2], acc[q4 * 4 + 3]};
;     __builtin_amdgcn_fence(__ATOMIC_RELEASE, "wavefront");
;     __builtin_amdgcn_wave_barrier();
;     __builtin_amdgcn_fence(__ATOMIC_ACQUIRE, "wavefront");
;     f32x4 r = {0.f, 0.f, 0.f, 0.f};
; #pragma unroll
;     for (int gg = 0; gg < 8; ++gg) { f32x4 v = *(const f32x4*)(red + gg * 256 + 4 * l); r += v; }
;     asm volatile("" ::: "memory");
;     __builtin_amdgcn_wave_barrier();
;     {
;       hv += r;
;       *(f32x4*)hq = hv;
;       if (!last) { u32x2 o; o[0] = cvtpk(hv[0], hv[1]); o[1] = cvtpk(hv[2], hv[3]); *(u32x2*)((char*)p.hb + ((unsigned)t * 2048u + (unsigned)(sl * 512 + l * 8))) = o; }
;     }
;     tt = tn;
	v_pk_fma_f32 v[68:69], v[56:57], v[100:101], v[68:69] op_sel_hi:[0,1,1]
	v_pk_fma_f32 v[70:71], v[56:57], v[102:103], v[70:71] op_sel_hi:[0,1,1]
	v_pk_fma_f32 v[72:73], v[56:57], v[104:105], v[72:73] op_sel_hi:[0,1,1]
	v_cvt_scalef32_pk_f32_fp4 v[98:99], v233, 1.0
	v_cvt_scalef32_pk_f32_fp4 v[100:101], v233, 1.0 op_sel:[1,0,0]
	v_cvt_scalef32_pk_f32_fp4 v[102:103], v233, 1.0 op_sel:[0,1,0]
	v_cvt_scalef32_pk_f32_fp4 v[104:105], v233, 1.0 op_sel:[1,1,0]
	v_pk_fma_f32 v[74:75], v[56:57], v[98:99], v[74:75] op_sel_hi:[0,1,1]
	v_pk_fma_f32 v[76:77], v[56:57], v[100:101], v[76:77] op_sel_hi:[0,1,1]
	v_pk_fma_f32 v[78:79], v[56:57], v[102:103], v[78:79] op_sel_hi:[0,1,1]
	v_pk_fma_f32 v[80:81], v[56:57], v[104:105], v[80:81] op_sel_hi:[0,1,1]
	v_cvt_scalef32_pk_f32_fp4 v[98:99], v234, 1.0
	v_cvt_scalef32_pk_f32_fp4 v[100:101], v234, 1.0 op_sel:[1,0,0]
	v_cvt_scalef32_pk_f32_fp4 v[102:103], v234, 1.0 op_sel:[0,1,0]
	v_cvt_scalef32_pk_f32_fp4 v[104:105], v234, 1.0 op_sel:[1,1,0]
	v_pk_fma_f32 v[82:83], v[56:57], v[98:99], v[82:83] op_sel_hi:[0,1,1]
	v_pk_fma_f32 v[84:85], v[56:57], v[100:101], v[84:85] op_sel_hi:[0,1,1]
	v_pk_fma_f32 v[86:87], v[56:57], v[102:103], v[86:87] op_sel_hi:[0,1,1]
	v_pk_fma_f32 v[88:89], v[56:57], v[104:105], v[88:89] op_sel_hi:[0,1,1]
	v_cvt_scalef32_pk_f32_fp4 v[98:99], v235, 1.0
	v_cvt_scalef32_pk_f32_fp4 v[100:101], v235, 1.0 op_sel:[1,0,0]
	v_cvt_scalef32_pk_f32_fp4 v[102:103], v235, 1.0 op_sel:[0,1,0]
	v_cvt_scalef32_pk_f32_fp4 v[104:105], v235, 1.0 op_sel:[1,1,0]
	v_pk_fma_f32 v[90:91], v[56:57], v[98:99], v[90:91] op_sel_hi:[0,1,1]
	v_pk_fma_f32 v[92:93], v[56:57], v[100:101], v[92:93] op_sel_hi:[0,1,1]
	v_pk_fma_f32 v[94:95], v[56:57], v[102:103], v[94:95] op_sel_hi:[0,1,1]
	v_pk_fma_f32 v[96:97], v[56:57], v[104:105], v[96:97] op_sel_hi:[0,1,1]
	v_cvt_scalef32_pk_f32_fp4 v[98:99], v236, 1.0
	v_cvt_scalef32_pk_f32_fp4 v[100:101], v236, 1.0 op_sel:[1,0,0]
	v_cvt_scalef32_pk_f32_fp4 v[102:103], v236, 1.0 op_sel:[0,1,0]
	v_cvt_scalef32_pk_f32_fp4 v[104:105], v236, 1.0 op_sel:[1,1,0]
	v_pk_fma_f32 v[66:67], v[56:57], v[98:99], v[66:67] op_sel:[1,0,0] op_sel_hi:[1,1,1]
	v_pk_fma_f32 v[68:69], v[56:57], v[100:101], v[68:69] op_sel:[1,0,0] op_sel_hi:[1,1,1]
	v_pk_fma_f32 v[70:71], v[56:57], v[102:103], v[70:71] op_sel:[1,0,0] op_sel_hi:[1,1,1]
	v_pk_fma_f32 v[72:73], v[56:57], v[104:105], v[72:73] op_sel:[1,0,0] op_sel_hi:[1,1,1]
	v_cvt_scalef32_pk_f32_fp4 v[98:99], v237, 1.0
	v_cvt_scalef32_pk_f32_fp4 v[100:101], v237, 1.0 op_sel:[1,0,0]
	v_cvt_scalef32_pk_f32_fp4 v[102:103], v237, 1.0 op_sel:[0,1,0]
	v_cvt_scalef32_pk_f32_fp4 v[104:105], v237, 1.0 op_sel:[1,1,0]
	v_pk_fma_f32 v[74:75], v[56:57], v[98:99], v[74:75] op_sel:[1,0,0] op_sel_hi:[1,1,1]
	v_pk_fma_f32 v[76:77], v[56:57], v[100:101], v[76:77] op_sel:[1,0,0] op_sel_hi:[1,1,1]
	v_pk_fma_f32 v[78:79], v[56:57], v[102:103], v[78:79] op_sel:[1,0,0] op_sel_hi:[1,1,1]
	v_pk_fma_f32 v[80:81], v[56:57], v[104:105], v[80:81] op_sel:[1,0,0] op_sel_hi:[1,1,1]
	v_cvt_scalef32_pk_f32_fp4 v[98:99], v238, 1.0
	v_cvt_scalef32_pk_f32_fp4 v[100:101], v238, 1.0 op_sel:[1,0,0]
	v_cvt_scalef32_pk_f32_fp4 v[102:103], v238, 1.0 op_sel:[0,1,0]
	v_cvt_scalef32_pk_f32_fp4 v[104:105], v238, 1.0 op_sel:[1,1,0]
	v_pk_fma_f32 v[82:83], v[56:57], v[98:99], v[82:83] op_sel:[1,0,0] op_sel_hi:[1,1,1]
	v_pk_fma_f32 v[84:85], v[56:57], v[100:101], v[84:85] op_sel:[1,0,0] op_sel_hi:[1,1,1]
	v_pk_fma_f32 v[86:87], v[56:57], v[102:103], v[86:87] op_sel:[1,0,0] op_sel_hi:[1,1,1]
	v_pk_fma_f32 v[88:89], v[56:57], v[104:105], v[88:89] op_sel:[1,0,0] op_sel_hi:[1,1,1]
	v_cvt_scalef32_pk_f32_fp4 v[98:99], v239, 1.0
	v_cvt_scalef32_pk_f32_fp4 v[100:101], v239, 1.0 op_sel:[1,0,0]
	v_cvt_scalef32_pk_f32_fp4 v[102:103], v239, 1.0 op_sel:[0,1,0]
	v_cvt_scalef32_pk_f32_fp4 v[104:105], v239, 1.0 op_sel:[1,1,0]
	v_pk_fma_f32 v[90:91], v[56:57], v[98:99], v[90:91] op_sel:[1,0,0] op_sel_hi:[1,1,1]
	v_pk_fma_f32 v[92:93], v[56:57], v[100:101], v[92:93] op_sel:[1,0,0] op_sel_hi:[1,1,1]
	v_pk_fma_f32 v[94:95], v[56:57], v[102:103], v[94:95] op_sel:[1,0,0] op_sel_hi:[1,1,1]
	v_pk_fma_f32 v[96:97], v[56:57], v[104:105], v[96:97] op_sel:[1,0,0] op_sel_hi:[1,1,1]
	ds_write_b128 v3, v[66:69]
	ds_write_b128 v3, v[70:73] offset:16
	ds_write_b128 v3, v[74:77] offset:32
	ds_write_b128 v3, v[78:81] offset:48
	ds_write_b128 v3, v[82:85] offset:64
	ds_write_b128 v3, v[86:89] offset:80
	ds_write_b128 v3, v[90:93] offset:96
	ds_write_b128 v3, v[94:97] offset:112
	s_waitcnt lgkmcnt(0)
	ds_read_b128 v[66:69], v4
	ds_read_b128 v[70:73], v4 offset:1024
	ds_read_b128 v[74:77], v4 offset:2048
	ds_read_b128 v[78:81], v4 offset:3072
	ds_read_b128 v[82:85], v4 offset:4096
	ds_read_b128 v[86:89], v4 offset:5120
	ds_read_b128 v[90:93], v4 offset:6144
	ds_read_b128 v[94:97], v4 offset:7168
	s_waitcnt lgkmcnt(6)
	v_pk_add_f32 v[66:67], v[66:67], v[70:71]
	v_pk_add_f32 v[68:69], v[68:69], v[72:73]
	s_waitcnt lgkmcnt(5)
	v_pk_add_f32 v[66:67], v[66:67], v[74:75]
	v_pk_add_f32 v[68:69], v[68:69], v[76:77]
	s_waitcnt lgkmcnt(4)
	v_pk_add_f32 v[66:67], v[66:67], v[78:79]
	v_pk_add_f32 v[68:69], v[68:69], v[80:81]
	s_waitcnt lgkmcnt(3)
	v_pk_add_f32 v[66:67], v[66:67], v[82:83]
	v_pk_add_f32 v[68:69], v[68:69], v[84:85]
	s_waitcnt lgkmcnt(2)
	v_pk_add_f32 v[66:67], v[66:67], v[86:87]
	v_pk_add_f32 v[68:69], v[68:69], v[88:89]
	s_waitcnt lgkmcnt(1)
	v_pk_add_f32 v[66:67], v[66:67], v[90:91]
	v_pk_add_f32 v[68:69], v[68:69], v[92:93]
	s_waitcnt lgkmcnt(0)
	v_pk_add_f32 v[66:67], v[66:67], v[94:95]
	v_pk_add_f32 v[68:69], v[68:69], v[96:97]
	v_pk_add_f32 v[62:63], v[62:63], v[66:67]
	v_pk_add_f32 v[64:65], v[64:65], v[68:69]
	global_store_dwordx4 v0, v[62:65], s[46:47]
	v_cvt_pk_bf16_f32 v98, v62, v63
	v_cvt_pk_bf16_f32 v99, v64, v65
	s_lshl_b32 s0, s36, 1
	s_add_u32 s0, s0, s28
	s_lshl_b32 s0, s0, 11
	s_lshl_b32 s1, s14, 9
	s_add_u32 s0, s0, s1
	v_add_u32_e32 v6, s0, v5
	global_store_dwordx2 v6, v[98:99], s[76:77]
	s_mov_b32 s36, s51
	s_cmp_lt_u32 s36, s38
	s_cbranch_scc1 .Lmy_pv0_bodyA
.Lmy_pv0_done:
.LBB0_791:
	s_waitcnt vmcnt(0)
	s_barrier
	s_mov_b64 s[0:1], exec
	v_readlane_b32 s6, v254, 16
	v_readlane_b32 s7, v254, 17
	s_and_b64 s[6:7], s[0:1], s[6:7]
	s_mov_b64 exec, s[6:7]
	s_cbranch_execz .LBB0_828
	s_mov_b64 s[8:9], exec
	v_mbcnt_lo_u32_b32 v0, s8, 0
	v_mbcnt_hi_u32_b32 v0, s9, v0
	v_cmp_eq_u32_e32 vcc, 0, v0
	s_waitcnt vmcnt(0) expcnt(0) lgkmcnt(0)
	s_and_saveexec_b64 s[6:7], vcc
	s_cbranch_execz .LBB0_794
	s_bcnt1_i32_b64 s3, s[8:9]
	v_mov_b32_e32 v1, 0x1000
	v_mov_b32_e32 v2, s3
	global_atomic_add v1, v1, v2, s[78:79] offset:1024 sc0

; __device__ __forceinline__ int tid_opaque() { int t = threadIdx.x; asm volatile("" : "+v"(t)); return t; }
; __device__ __forceinline__ void phase_peer_v(const Params& p, int layer, int xs, int wid0, int wstride, bool last, char* smraw) {
;   const int tid = tid_opaque(), w = tid >> 6, l = tid & 63, g = l >> 3, j = l & 7;
;   const int wid = wid0 + w;
;   const int sl = xs >> 1, par = xs & 1;
;   constexpr int TH = T / 2;
;   float* red = (float*)smraw + w * 2048;
;   const unsigned char* Vq = p.Vq + (size_t)(layer * 4 + sl) * NEXP * 128;
;   const unsigned joff = j * 16;
;   u32x4 ni[4]; f32x4 nc[4];
;   auto load_idx = [&](int tt) {
;     const unsigned o = (unsigned)(2 * tt + par) * 512u + (unsigned)g * 64u;
;     const u32x4* ip = (const u32x4*)((const char*)p.sel_idx + o);
;     const f32x4* cp = (const f32x4*)((const char*)p.coef + o);
; #pragma unroll
;     for (int q4 = 0; q4 < 4; ++q4) { ni[q4] = ip[q4]; nc[q4] = cp[q4]; }
;   };
;   u32x4 qA[8];
;   float acc[32];
;   auto half_fma = [&](const u32x4 (&q)[8], const f32x4& c0, const f32x4& c1) {
; #pragma unroll
;     for (int i = 0; i < 8; ++i) {
;       const float ci = i < 4 ? c0[i & 3] : c1[i & 3];
; #pragma unroll
;       for (int m = 0; m < 4; ++m) {
;         unsigned dw = q[i][m];
;         asm volatile("" : "+v"(dw) : "v"(acc[(8 * m + 31) & 31]));
;         const f32x2 e0 = __builtin_amdgcn_cvt_scalef32_pk_f32_fp4(dw, 1.0f, 0), e1 = __builtin_amdgcn_cvt_scalef32_pk_f32_fp4(dw, 1.0f, 1);
;         const f32x2 e2 = __builtin_amdgcn_cvt_scalef32_pk_f32_fp4(dw, 1.0f, 2), e3 = __builtin_amdgcn_cvt_scalef32_pk_f32_fp4(dw, 1.0f, 3);
;         acc[8 * m + 0] += ci * e0[0]; acc[8 * m + 1] += ci * e0[1]; acc[8 * m + 2] += ci * e1[0]; acc[8 * m + 3] += ci * e1[1];
;         acc[8 * m + 4] += ci * e2[0]; acc[8 * m + 5] += ci * e2[1]; acc[8 * m + 6] += ci * e3[0]; acc[8 * m + 7] += ci * e3[1];
;       }
;     }
;   };
;   int tt = wid;
;   if (tt < TH) load_idx(tt);
;   while (tt < TH) {
;     const int tn = tt + wstride;
;     const int t = 2 * tt + par;
; #pragma unroll
;     for (int i = 0; i < 8; ++i) qA[i] = *(const u32x4*)(Vq + (ni[i >> 2][i & 3] * 128u + joff));
;     float* hq = hrow(p, t) + sl * 256 + 4 * l;
;     f32x4 hv = *(const f32x4*)hq;
;     const f32x4 c0 = nc[0], c1 = nc[1], c2 = nc[2], c3 = nc[3];
.LBB0_1377:
	s_or_b64 exec, exec, s[0:1]
	s_barrier
	v_and_b32_e32 v6, 63, v189
	v_lshrrev_b32_e32 v7, 6, v189
	v_lshlrev_b32_e32 v0, 4, v6
	v_and_b32_e32 v1, 7, v6
	v_lshlrev_b32_e32 v1, 4, v1
	v_lshrrev_b32_e32 v8, 3, v6
	v_readfirstlane_b32 s0, v7
	s_lshl_b32 s1, s28, 9
	v_lshl_add_u32 v2, v8, 6, s1
	v_lshlrev_b32_e32 v3, 13, v7
	v_lshl_add_u32 v4, v6, 4, v3
	v_lshl_add_u32 v3, v8, 10, v3
	v_lshl_add_u32 v3, v1, 3, v3
	v_lshlrev_b32_e32 v5, 3, v6
	s_add_u32 s36, s92, s0
	s_movk_i32 s38, 0x4020
	s_cmp_ge_u32 s36, s38
	s_cbranch_scc1 .Lmy_pv1_done
	s_lshl_b32 s0, s14, 21
	s_add_u32 s0, s0, 0x800000
	s_add_u32 s40, s90, s0
	s_addc_u32 s41, s91, 0
	v_readlane_b32 s42, v254, 6
	v_readlane_b32 s43, v254, 7
	v_readlane_b32 s10, v254, 30
	v_readlane_b32 s11, v254, 31
	v_readlane_b32 s12, v254, 32
	v_readlane_b32 s13, v254, 33
	s_lshl_b32 s39, s14, 10
	s_mov_b32 s49, 0x7fc02
	s_sub_u32 s10, s10, 0x10000
	s_subb_u32 s11, s11, 0
	s_lshl_b32 s0, s36, 10
	v_add_u32_e32 v9, s0, v2
	global_load_dwordx4 v[10:13], v9, s[52:53]
	global_load_dwordx4 v[14:17], v9, s[52:53] offset:16
	global_load_dwordx4 v[18:21], v9, s[52:53] offset:32
	global_load_dwordx4 v[22:25], v9, s[52:53] offset:48
	s_waitcnt vmcnt(0)
	v_lshl_add_u32 v6, v10, 7, v1
	global_load_dwordx4 v[106:109], v6, s[40:41]
	v_lshl_add_u32 v7, v11, 7, v1
	global_load_dwordx4 v[110:113], v7, s[40:41]
	v_lshl_add_u32 v6, v12, 7, v1
	global_load_dwordx4 v[114:117], v6, s[40:41]
	v_lshl_add_u32 v7, v13, 7, v1
	global_load_dwordx4 v[118:121], v7, s[40:41]
	v_lshl_add_u32 v6, v14, 7, v1
	global_load_dwordx4 v[122:125], v6, s[40:41]
	v_lshl_add_u32 v7, v15, 7, v1
	global_load_dwordx4 v[126:129], v7, s[40:41]
	v_lshl_add_u32 v6, v16, 7, v1
	global_load_dwordx4 v[130:133], v6, s[40:41]
	v_lshl_add_u32 v7, v17, 7, v1
	global_load_dwordx4 v[134:137], v7, s[40:41]
	v_lshl_add_u32 v6, v18, 7, v1
	global_load_dwordx4 v[138:141], v6, s[40:41]
	v_lshl_add_u32 v7, v19, 7, v1
	global_load_dwordx4 v[142:145], v7, s[40:41]
	v_lshl_add_u32 v6, v20, 7, v1
	global_load_dwordx4 v[146:149], v6, s[40:41]
	v_lshl_add_u32 v7, v21, 7, v1
	global_load_dwordx4 v[150:153], v7, s[40:41]
	v_lshl_add_u32 v6, v22, 7, v1
	global_load_dwordx4 v[154:157], v6, s[40:41]
	v_lshl_add_u32 v7, v23, 7, v1
	global_load_dwordx4 v[158:161], v7, s[40:41]
	v_lshl_add_u32 v6, v24, 7, v1
	global_load_dwordx4 v[162:165], v6, s[40:41]
	v_lshl_add_u32 v7, v25, 7, v1
	global_load_dwordx4 v[166:169], v7, s[40:41]
	s_lshl_b32 s0, s36, 1
	s_add_u32 s0, s0, s28
	s_mul_hi_u32 s1, s0, s49
	s_mul_i32 s3, s1, 0x2010
	s_sub_u32 s3, s0, s3
	s_lshl_b32 s6, s1, 13
	s_add_u32 s6, s6, s3
	s_lshl_b32 s7, s1, 4
	s_add_u32 s7, s7, s3
	s_cmp_lt_u32 s3, 16
	s_cselect_b32 s6, s7, s6
	s_cselect_b32 s7, s12, s10
	s_cselect_b32 s8, s13, s11
	s_lshl_b32 s6, s6, 12
	s_add_u32 s6, s6, s39
	s_add_u32 s44, s7, s6
	s_addc_u32 s45, s8, 0
	global_load_dwordx4 v[58:61], v0, s[44:45]
	s_lshl_b32 s0, s36, 10
	v_add_u32_e32 v8, s0, v2
	global_load_dwordx4 v[26:29], v8, s[42:43]
	global_load_dwordx4 v[30:33], v8, s[42:43] offset:16
	global_load_dwordx4 v[34:37], v8, s[42:43] offset:32
	global_load_dwordx4 v[38:41], v8, s[42:43] offset:48
	s_add_u32 s51, s36, s33
	s_cmp_ge_u32 s51, s38
	s_cbranch_scc1 .Lmy_pv1_pro1
	s_lshl_b32 s0, s51, 10
	v_add_u32_e32 v9, s0, v2
	global_load_dwordx4 v[10:13], v9, s[52:53]
	global_load_dwordx4 v[14:17], v9, s[52:53] offset:16
	global_load_dwordx4 v[18:21], v9, s[52:53] offset:32
	global_load_dwordx4 v[22:25], v9, s[52:53] offset:48

; __device__ __forceinline__ void phase_peer_v(const Params& p, int layer, int xs, int wid0, int wstride, bool last, char* smraw) {
;     ...
;   auto half_fma = [&](const u32x4 (&q)[8], const f32x4& c0, const f32x4& c1) {
; #pragma unroll
;     for (int i = 0; i < 8; ++i) {
;       const float ci = i < 4 ? c0[i & 3] : c1[i & 3];
; #pragma unroll
;       for (int m = 0; m < 4; ++m) {
;         unsigned dw = q[i][m];
;         asm volatile("" : "+v"(dw) : "v"(acc[(8 * m + 31) & 31]));
;         const f32x2 e0 = __builtin_amdgcn_cvt_scalef32_pk_f32_fp4(dw, 1.0f, 0), e1 = __builtin_amdgcn_cvt_scalef32_pk_f32_fp4(dw, 1.0f, 1);
;         const f32x2 e2 = __builtin_amdgcn_cvt_scalef32_pk_f32_fp4(dw, 1.0f, 2), e3 = __builtin_amdgcn_cvt_scalef32_pk_f32_fp4(dw, 1.0f, 3);
;         acc[8 * m + 0] += ci * e0[0]; acc[8 * m + 1] += ci * e0[1]; acc[8 * m + 2] += ci * e1[0]; acc[8 * m + 3] += ci * e1[1];
;         acc[8 * m + 4] += ci * e2[0]; acc[8 * m + 5] += ci * e2[1]; acc[8 * m + 6] += ci * e3[0]; acc[8 * m + 7] += ci * e3[1];
;       }
;     }
;     ...
;   while (tt < TH) {
;     const int tn = tt + wstride;
;     const int t = 2 * tt + par;
; #pragma unroll
;     for (int i = 0; i < 8; ++i) qA[i] = *(const u32x4*)(Vq + (ni[i >> 2][i & 3] * 128u + joff));
;     float* hq = hrow(p, t) + sl * 256 + 4 * l;
;     f32x4 hv = *(const f32x4*)hq;
;     const f32x4 c0 = nc[0], c1 = nc[1], c2 = nc[2], c3 = nc[3];
; #pragma unroll
;     for (int m = 0; m < 32; ++m) acc[m] = 0.f;
;     half_fma(qA, c0, c1);
; #pragma unroll
;     for (int i = 0; i < 8; ++i) qA[i] = *(const u32x4*)(Vq + (ni[2 + (i >> 2)][i & 3] * 128u + joff));
;     if (tn < TH) load_idx(tn);
.Lmy_pv1_bodyA:
	s_waitcnt vmcnt(1)
	s_add_u32 s51, s36, s33
	s_cmp_ge_u32 s51, s38
	s_cbranch_scc1 .Lmy_pv1_noissueA
	v_lshl_add_u32 v6, v10, 7, v1
	global_load_dwordx4 v[170:173], v6, s[40:41]
	v_lshl_add_u32 v7, v11, 7, v1
	global_load_dwordx4 v[174:177], v7, s[40:41]
	v_lshl_add_u32 v6, v12, 7, v1
	global_load_dwordx4 v[178:181], v6, s[40:41]
	v_lshl_add_u32 v7, v13, 7, v1
	global_load_dwordx4 v[182:185], v7, s[40:41]
	v_lshl_add_u32 v6, v14, 7, v1
	global_load_dwordx4 v[192:195], v6, s[40:41]
	v_lshl_add_u32 v7, v15, 7, v1
	global_load_dwordx4 v[196:199], v7, s[40:41]
	v_lshl_add_u32 v6, v16, 7, v1
	global_load_dwordx4 v[200:203], v6, s[40:41]
	v_lshl_add_u32 v7, v17, 7, v1
	global_load_dwordx4 v[204:207], v7, s[40:41]
	v_lshl_add_u32 v6, v18, 7, v1
	global_load_dwordx4 v[208:211], v6, s[40:41]
	v_lshl_add_u32 v7, v19, 7, v1
	global_load_dwordx4 v[212:215], v7, s[40:41]
	v_lshl_add_u32 v6, v20, 7, v1
	global_load_dwordx4 v[216:219], v6, s[40:41]
	v_lshl_add_u32 v7, v21, 7, v1
	global_load_dwordx4 v[220:223], v7, s[40:41]
	v_lshl_add_u32 v6, v22, 7, v1
	global_load_dwordx4 v[224:227], v6, s[40:41]
	v_lshl_add_u32 v7, v23, 7, v1
	global_load_dwordx4 v[228:231], v7, s[40:41]
	v_lshl_add_u32 v6, v24, 7, v1
	global_load_dwordx4 v[232:235], v6, s[40:41]
	v_lshl_add_u32 v7, v25, 7, v1
	global_load_dwordx4 v[236:239], v7, s[40:41]
	s_lshl_b32 s0, s51, 1
	s_add_u32 s0, s0, s28
	s_mul_hi_u32 s1, s0, s49
	s_mul_i32 s3, s1, 0x2010
	s_sub_u32 s3, s0, s3
	s_lshl_b32 s6, s1, 13
	s_add_u32 s6, s6, s3
	s_lshl_b32 s7, s1, 4
	s_add_u32 s7, s7, s3
	s_cmp_lt_u32 s3, 16
	s_cselect_b32 s6, s7, s6
	s_cselect_b32 s7, s12, s10
	s_cselect_b32 s8, s13, s11
	s_lshl_b32 s6, s6, 12
	s_add_u32 s6, s6, s39
	s_add_u32 s46, s7, s6
	s_addc_u32 s47, s8, 0
	global_load_dwordx4 v[62:65], v0, s[46:47]
	s_lshl_b32 s0, s51, 10
	v_add_u32_e32 v8, s0, v2
	global_load_dwordx4 v[42:45], v8, s[42:43]
	global_load_dwordx4 v[46:49], v8, s[42:43] offset:16
	global_load_dwordx4 v[50:53], v8, s[42:43] offset:32
	global_load_dwordx4 v[54:57], v8, s[42:43] offset:48
	s_add_u32 s9, s51, s33
	s_cmp_ge_u32 s9, s38
	s_cbranch_scc1 .Lmy_pv1_noissueA
	s_lshl_b32 s0, s9, 10
	v_add_u32_e32 v9, s0, v2
	global_load_dwordx4 v[10:13], v9, s[52:53]
	global_load_dwordx4 v[14:17], v9, s[52:53] offset:16
	global_load_dwordx4 v[18:21], v9, s[52:53] offset:32
	global_load_dwordx4 v[22:25], v9, s[52:53] offset:48
.Lmy_pv1_noissueA:
	v_cvt_scalef32_pk_f32_fp4 v[98:99], v106, 1.0
	v_cvt_scalef32_pk_f32_fp4 v[100:101], v106, 1.0 op_sel:[1,0,0]
	v_cvt_scalef32_pk_f32_fp4 v[102:103], v106, 1.0 op_sel:[0,1,0]
	v_cvt_scalef32_pk_f32_fp4 v[104:105], v106, 1.0 op_sel:[1,1,0]
	v_pk_fma_f32 v[66:67], v[26:27], v[98:99], 0 op_sel_hi:[0,1,0]
	v_pk_fma_f32 v[68:69], v[26:27], v[100:101], 0 op_sel_hi:[0,1,0]
	v_pk_fma_f32 v[70:71], v[26:27], v[102:103], 0 op_sel_hi:[0,1,0]
	v_pk_fma_f32 v[72:73], v[26:27], v[104:105], 0 op_sel_hi:[0,1,0]
	v_cvt_scalef32_pk_f32_fp4 v[98:99], v107, 1.0
	v_cvt_scalef32_pk_f32_fp4 v[100:101], v107, 1.0 op_sel:[1,0,0]
	v_cvt_scalef32_pk_f32_fp4 v[102:103], v107, 1.0 op_sel:[0,1,0]
	v_cvt_scalef32_pk_f32_fp4 v[104:105], v107, 1.0 op_sel:[1,1,0]
	v_pk_fma_f32 v[74:75], v[26:27], v[98:99], 0 op_sel_hi:[0,1,0]
	v_pk_fma_f32 v[76:77], v[26:27], v[100:101], 0 op_sel_hi:[0,1,0]
	v_pk_fma_f32 v[78:79], v[26:27], v[102:103], 0 op_sel_hi:[0,1,0]
	v_pk_fma_f32 v[80:81], v[26:27], v[104:105], 0 op_sel_hi:[0,1,0]
	v_cvt_scalef32_pk_f32_fp4 v[98:99], v108, 1.0
	v_cvt_scalef32_pk_f32_fp4 v[100:101], v108, 1.0 op_sel:[1,0,0]
	v_cvt_scalef32_pk_f32_fp4 v[102:103], v108, 1.0 op_sel:[0,1,0]
	v_cvt_scalef32_pk_f32_fp4 v[104:105], v108, 1.0 op_sel:[1,1,0]
	v_pk_fma_f32 v[82:83], v[26:27], v[98:99], 0 op_sel_hi:[0,1,0]
	v_pk_fma_f32 v[84:85], v[26:27], v[100:101], 0 op_sel_hi:[0,1,0]
	v_pk_fma_f32 v[86:87], v[26:27], v[102:103], 0 op_sel_hi:[0,1,0]
	v_pk_fma_f32 v[88:89], v[26:27], v[104:105], 0 op_sel_hi:[0,1,0]
	v_cvt_scalef32_pk_f32_fp4 v[98:99], v109, 1.0
	v_cvt_scalef32_pk_f32_fp4 v[100:101], v109, 1.0 op_sel:[1,0,0]
	v_cvt_scalef32_pk_f32_fp4 v[102:103], v109, 1.0 op_sel:[0,1,0]
	v_cvt_scalef32_pk_f32_fp4 v[104:105], v109, 1.0 op_sel:[1,1,0]
	v_pk_fma_f32 v[90:91], v[26:27], v[98:99], 0 op_sel_hi:[0,1,0]
	v_pk_fma_f32 v[92:93], v[26:27], v[100:101], 0 op_sel_hi:[0,1,0]
	v_pk_fma_f32 v[94:95], v[26:27], v[102:103], 0 op_sel_hi:[0,1,0]
	v_pk_fma_f32 v[96:97], v[26:27], v[104:105], 0 op_sel_hi:[0,1,0]
	v_cvt_scalef32_pk_f32_fp4 v[98:99], v110, 1.0
	v_cvt_scalef32_pk_f32_fp4 v[100:101], v110, 1.0 op_sel:[1,0,0]
	v_cvt_scalef32_pk_f32_fp4 v[102:103], v110, 1.0 op_sel:[0,1,0]
	v_cvt_scalef32_pk_f32_fp4 v[104:105], v110, 1.0 op_sel:[1,1,0]
	v_pk_fma_f32 v[66:67], v[26:27], v[98:99], v[66:67] op_sel:[1,0,0] op_sel_hi:[1,1,1]
	v_pk_fma_f32 v[68:69], v[26:27], v[100:101], v[68:69] op_sel:[1,0,0] op_sel_hi:[1,1,1]
	v_pk_fma_f32 v[70:71], v[26:27], v[102:103], v[70:71] op_sel:[1,0,0] op_sel_hi:[1,1,1]
	v_pk_fma_f32 v[72:73], v[26:27], v[104:105], v[72:73] op_sel:[1,0,0] op_sel_hi:[1,1,1]
	v_cvt_scalef32_pk_f32_fp4 v[98:99], v111, 1.0
	v_cvt_scalef32_pk_f32_fp4 v[100:101], v111, 1.0 op_sel:[1,0,0]
	v_cvt_scalef32_pk_f32_fp4 v[102:103], v111, 1.0 op_sel:[0,1,0]
	v_cvt_scalef32_pk_f32_fp4 v[104:105], v111, 1.0 op_sel:[1,1,0]
	v_pk_fma_f32 v[74:75], v[26:27], v[98:99], v[74:75] op_sel:[1,0,0] op_sel_hi:[1,1,1]
	v_pk_fma_f32 v[76:77], v[26:27], v[100:101], v[76:77] op_sel:[1,0,0] op_sel_hi:[1,1,1]
	v_pk_fma_f32 v[78:79], v[26:27], v[102:103], v[78:79] op_sel:[1,0,0] op_sel_hi:[1,1,1]
	v_pk_fma_f32 v[80:81], v[26:27], v[104:105], v[80:81] op_sel:[1,0,0] op_sel_hi:[1,1,1]
	v_cvt_scalef32_pk_f32_fp4 v[98:99], v112, 1.0
; __device__ __forceinline__ void phase_peer_v(const Params& p, int layer, int xs, int wid0, int wstride, bool last, char* smraw) {
;     ...
;   auto half_fma = [&](const u32x4 (&q)[8], const f32x4& c0, const f32x4& c1) {
; #pragma unroll
;     for (int i = 0; i < 8; ++i) {
;       const float ci = i < 4 ? c0[i & 3] : c1[i & 3];
; #pragma unroll
;       for (int m = 0; m < 4; ++m) {
;         unsigned dw = q[i][m];
;         asm volatile("" : "+v"(dw) : "v"(acc[(8 * m + 31) & 31]));
;         const f32x2 e0 = __builtin_amdgcn_cvt_scalef32_pk_f32_fp4(dw, 1.0f, 0), e1 = __builtin_amdgcn_cvt_scalef32_pk_f32_fp4(dw, 1.0f, 1);
;         const f32x2 e2 = __builtin_amdgcn_cvt_scalef32_pk_f32_fp4(dw, 1.0f, 2), e3 = __builtin_amdgcn_cvt_scalef32_pk_f32_fp4(dw, 1.0f, 3);
;         acc[8 * m + 0] += ci * e0[0]; acc[8 * m + 1] += ci * e0[1]; acc[8 * m + 2] += ci * e1[0]; acc[8 * m + 3] += ci * e1[1];
;         acc[8 * m + 4] += ci * e2[0]; acc[8 * m + 5] += ci * e2[1]; acc[8 * m + 6] += ci * e3[0]; acc[8 * m + 7] += ci * e3[1];
;       }
;     }
	v_cvt_scalef32_pk_f32_fp4 v[100:101], v112, 1.0 op_sel:[1,0,0]
	v_cvt_scalef32_pk_f32_fp4 v[102:103], v112, 1.0 op_sel:[0,1,0]
	v_cvt_scalef32_pk_f32_fp4 v[104:105], v112, 1.0 op_sel:[1,1,0]
	v_pk_fma_f32 v[82:83], v[26:27], v[98:99], v[82:83] op_sel:[1,0,0] op_sel_hi:[1,1,1]
	v_pk_fma_f32 v[84:85], v[26:27], v[100:101], v[84:85] op_sel:[1,0,0] op_sel_hi:[1,1,1]
	v_pk_fma_f32 v[86:87], v[26:27], v[102:103], v[86:87] op_sel:[1,0,0] op_sel_hi:[1,1,1]
	v_pk_fma_f32 v[88:89], v[26:27], v[104:105], v[88:89] op_sel:[1,0,0] op_sel_hi:[1,1,1]
	v_cvt_scalef32_pk_f32_fp4 v[98:99], v113, 1.0
	v_cvt_scalef32_pk_f32_fp4 v[100:101], v113, 1.0 op_sel:[1,0,0]
	v_cvt_scalef32_pk_f32_fp4 v[102:103], v113, 1.0 op_sel:[0,1,0]
	v_cvt_scalef32_pk_f32_fp4 v[104:105], v113, 1.0 op_sel:[1,1,0]
	v_pk_fma_f32 v[90:91], v[26:27], v[98:99], v[90:91] op_sel:[1,0,0] op_sel_hi:[1,1,1]
	v_pk_fma_f32 v[92:93], v[26:27], v[100:101], v[92:93] op_sel:[1,0,0] op_sel_hi:[1,1,1]
	v_pk_fma_f32 v[94:95], v[26:27], v[102:103], v[94:95] op_sel:[1,0,0] op_sel_hi:[1,1,1]
	v_pk_fma_f32 v[96:97], v[26:27], v[104:105], v[96:97] op_sel:[1,0,0] op_sel_hi:[1,1,1]
	v_cvt_scalef32_pk_f32_fp4 v[98:99], v114, 1.0
	v_cvt_scalef32_pk_f32_fp4 v[100:101], v114, 1.0 op_sel:[1,0,0]
	v_cvt_scalef32_pk_f32_fp4 v[102:103], v114, 1.0 op_sel:[0,1,0]
	v_cvt_scalef32_pk_f32_fp4 v[104:105], v114, 1.0 op_sel:[1,1,0]
	v_pk_fma_f32 v[66:67], v[28:29], v[98:99], v[66:67] op_sel_hi:[0,1,1]
	v_pk_fma_f32 v[68:69], v[28:29], v[100:101], v[68:69] op_sel_hi:[0,1,1]
	v_pk_fma_f32 v[70:71], v[28:29], v[102:103], v[70:71] op_sel_hi:[0,1,1]
	v_pk_fma_f32 v[72:73], v[28:29], v[104:105], v[72:73] op_sel_hi:[0,1,1]
	v_cvt_scalef32_pk_f32_fp4 v[98:99], v115, 1.0
	v_cvt_scalef32_pk_f32_fp4 v[100:101], v115, 1.0 op_sel:[1,0,0]
	v_cvt_scalef32_pk_f32_fp4 v[102:103], v115, 1.0 op_sel:[0,1,0]
	v_cvt_scalef32_pk_f32_fp4 v[104:105], v115, 1.0 op_sel:[1,1,0]
	v_pk_fma_f32 v[74:75], v[28:29], v[98:99], v[74:75] op_sel_hi:[0,1,1]
	v_pk_fma_f32 v[76:77], v[28:29], v[100:101], v[76:77] op_sel_hi:[0,1,1]
	v_pk_fma_f32 v[78:79], v[28:29], v[102:103], v[78:79] op_sel_hi:[0,1,1]
	v_pk_fma_f32 v[80:81], v[28:29], v[104:105], v[80:81] op_sel_hi:[0,1,1]
	v_cvt_scalef32_pk_f32_fp4 v[98:99], v116, 1.0
	v_cvt_scalef32_pk_f32_fp4 v[100:101], v116, 1.0 op_sel:[1,0,0]
	v_cvt_scalef32_pk_f32_fp4 v[102:103], v116, 1.0 op_sel:[0,1,0]
	v_cvt_scalef32_pk_f32_fp4 v[104:105], v116, 1.0 op_sel:[1,1,0]
	v_pk_fma_f32 v[82:83], v[28:29], v[98:99], v[82:83] op_sel_hi:[0,1,1]
	v_pk_fma_f32 v[84:85], v[28:29], v[100:101], v[84:85] op_sel_hi:[0,1,1]
	v_pk_fma_f32 v[86:87], v[28:29], v[102:103], v[86:87] op_sel_hi:[0,1,1]
	v_pk_fma_f32 v[88:89], v[28:29], v[104:105], v[88:89] op_sel_hi:[0,1,1]
	v_cvt_scalef32_pk_f32_fp4 v[98:99], v117, 1.0
	v_cvt_scalef32_pk_f32_fp4 v[100:101], v117, 1.0 op_sel:[1,0,0]
	v_cvt_scalef32_pk_f32_fp4 v[102:103], v117, 1.0 op_sel:[0,1,0]
	v_cvt_scalef32_pk_f32_fp4 v[104:105], v117, 1.0 op_sel:[1,1,0]
	v_pk_fma_f32 v[90:91], v[28:29], v[98:99], v[90:91] op_sel_hi:[0,1,1]
	v_pk_fma_f32 v[92:93], v[28:29], v[100:101], v[92:93] op_sel_hi:[0,1,1]
	v_pk_fma_f32 v[94:95], v[28:29], v[102:103], v[94:95] op_sel_hi:[0,1,1]
	v_pk_fma_f32 v[96:97], v[28:29], v[104:105], v[96:97] op_sel_hi:[0,1,1]
	v_cvt_scalef32_pk_f32_fp4 v[98:99], v118, 1.0
	v_cvt_scalef32_pk_f32_fp4 v[100:101], v118, 1.0 op_sel:[1,0,0]
	v_cvt_scalef32_pk_f32_fp4 v[102:103], v118, 1.0 op_sel:[0,1,0]
	v_cvt_scalef32_pk_f32_fp4 v[104:105], v118, 1.0 op_sel:[1,1,0]
	v_pk_fma_f32 v[66:67], v[28:29], v[98:99], v[66:67] op_sel:[1,0,0] op_sel_hi:[1,1,1]
	v_pk_fma_f32 v[68:69], v[28:29], v[100:101], v[68:69] op_sel:[1,0,0] op_sel_hi:[1,1,1]
	v_pk_fma_f32 v[70:71], v[28:29], v[102:103], v[70:71] op_sel:[1,0,0] op_sel_hi:[1,1,1]
	v_pk_fma_f32 v[72:73], v[28:29], v[104:105], v[72:73] op_sel:[1,0,0] op_sel_hi:[1,1,1]
	v_cvt_scalef32_pk_f32_fp4 v[98:99], v119, 1.0
	v_cvt_scalef32_pk_f32_fp4 v[100:101], v119, 1.0 op_sel:[1,0,0]
	v_cvt_scalef32_pk_f32_fp4 v[102:103], v119, 1.0 op_sel:[0,1,0]
	v_cvt_scalef32_pk_f32_fp4 v[104:105], v119, 1.0 op_sel:[1,1,0]
	v_pk_fma_f32 v[74:75], v[28:29], v[98:99], v[74:75] op_sel:[1,0,0] op_sel_hi:[1,1,1]
	v_pk_fma_f32 v[76:77], v[28:29], v[100:101], v[76:77] op_sel:[1,0,0] op_sel_hi:[1,1,1]
	v_pk_fma_f32 v[78:79], v[28:29], v[102:103], v[78:79] op_sel:[1,0,0] op_sel_hi:[1,1,1]
	v_pk_fma_f32 v[80:81], v[28:29], v[104:105], v[80:81] op_sel:[1,0,0] op_sel_hi:[1,1,1]
	v_cvt_scalef32_pk_f32_fp4 v[98:99], v120, 1.0
	v_cvt_scalef32_pk_f32_fp4 v[100:101], v120, 1.0 op_sel:[1,0,0]
	v_cvt_scalef32_pk_f32_fp4 v[102:103], v120, 1.0 op_sel:[0,1,0]
	v_cvt_scalef32_pk_f32_fp4 v[104:105], v120, 1.0 op_sel:[1,1,0]
	v_pk_fma_f32 v[82:83], v[28:29], v[98:99], v[82:83] op_sel:[1,0,0] op_sel_hi:[1,1,1]
	v_pk_fma_f32 v[84:85], v[28:29], v[100:101], v[84:85] op_sel:[1,0,0] op_sel_hi:[1,1,1]
	v_pk_fma_f32 v[86:87], v[28:29], v[102:103], v[86:87] op_sel:[1,0,0] op_sel_hi:[1,1,1]
	v_pk_fma_f32 v[88:89], v[28:29], v[104:105], v[88:89] op_sel:[1,0,0] op_sel_hi:[1,1,1]
	v_cvt_scalef32_pk_f32_fp4 v[98:99], v121, 1.0
	v_cvt_scalef32_pk_f32_fp4 v[100:101], v121, 1.0 op_sel:[1,0,0]
	v_cvt_scalef32_pk_f32_fp4 v[102:103], v121, 1.0 op_sel:[0,1,0]
	v_cvt_scalef32_pk_f32_fp4 v[104:105], v121, 1.0 op_sel:[1,1,0]
	v_pk_fma_f32 v[90:91], v[28:29], v[98:99], v[90:91] op_sel:[1,0,0] op_sel_hi:[1,1,1]
	v_pk_fma_f32 v[92:93], v[28:29], v[100:101], v[92:93] op_sel:[1,0,0] op_sel_hi:[1,1,1]
	v_pk_fma_f32 v[94:95], v[28:29], v[102:103], v[94:95] op_sel:[1,0,0] op_sel_hi:[1,1,1]
	v_pk_fma_f32 v[96:97], v[28:29], v[104:105], v[96:97] op_sel:[1,0,0] op_sel_hi:[1,1,1]
	v_cvt_scalef32_pk_f32_fp4 v[98:99], v122, 1.0
; __device__ __forceinline__ void phase_peer_v(const Params& p, int layer, int xs, int wid0, int wstride, bool last, char* smraw) {
;     ...
;   auto half_fma = [&](const u32x4 (&q)[8], const f32x4& c0, const f32x4& c1) {
; #pragma unroll
;     for (int i = 0; i < 8; ++i) {
;       const float ci = i < 4 ? c0[i & 3] : c1[i & 3];
; #pragma unroll
;       for (int m = 0; m < 4; ++m) {
;         unsigned dw = q[i][m];
;         asm volatile("" : "+v"(dw) : "v"(acc[(8 * m + 31) & 31]));
;         const f32x2 e0 = __builtin_amdgcn_cvt_scalef32_pk_f32_fp4(dw, 1.0f, 0), e1 = __builtin_amdgcn_cvt_scalef32_pk_f32_fp4(dw, 1.0f, 1);
;         const f32x2 e2 = __builtin_amdgcn_cvt_scalef32_pk_f32_fp4(dw, 1.0f, 2), e3 = __builtin_amdgcn_cvt_scalef32_pk_f32_fp4(dw, 1.0f, 3);
;         acc[8 * m + 0] += ci * e0[0]; acc[8 * m + 1] += ci * e0[1]; acc[8 * m + 2] += ci * e1[0]; acc[8 * m + 3] += ci * e1[1];
;         acc[8 * m + 4] += ci * e2[0]; acc[8 * m + 5] += ci * e2[1]; acc[8 * m + 6] += ci * e3[0]; acc[8 * m + 7] += ci * e3[1];
;       }
;     }
	v_cvt_scalef32_pk_f32_fp4 v[100:101], v122, 1.0 op_sel:[1,0,0]
	v_cvt_scalef32_pk_f32_fp4 v[102:103], v122, 1.0 op_sel:[0,1,0]
	v_cvt_scalef32_pk_f32_fp4 v[104:105], v122, 1.0 op_sel:[1,1,0]
	v_pk_fma_f32 v[66:67], v[30:31], v[98:99], v[66:67] op_sel_hi:[0,1,1]
	v_pk_fma_f32 v[68:69], v[30:31], v[100:101], v[68:69] op_sel_hi:[0,1,1]
	v_pk_fma_f32 v[70:71], v[30:31], v[102:103], v[70:71] op_sel_hi:[0,1,1]
	v_pk_fma_f32 v[72:73], v[30:31], v[104:105], v[72:73] op_sel_hi:[0,1,1]
	v_cvt_scalef32_pk_f32_fp4 v[98:99], v123, 1.0
	v_cvt_scalef32_pk_f32_fp4 v[100:101], v123, 1.0 op_sel:[1,0,0]
	v_cvt_scalef32_pk_f32_fp4 v[102:103], v123, 1.0 op_sel:[0,1,0]
	v_cvt_scalef32_pk_f32_fp4 v[104:105], v123, 1.0 op_sel:[1,1,0]
	v_pk_fma_f32 v[74:75], v[30:31], v[98:99], v[74:75] op_sel_hi:[0,1,1]
	v_pk_fma_f32 v[76:77], v[30:31], v[100:101], v[76:77] op_sel_hi:[0,1,1]
	v_pk_fma_f32 v[78:79], v[30:31], v[102:103], v[78:79] op_sel_hi:[0,1,1]
	v_pk_fma_f32 v[80:81], v[30:31], v[104:105], v[80:81] op_sel_hi:[0,1,1]
	v_cvt_scalef32_pk_f32_fp4 v[98:99], v124, 1.0
	v_cvt_scalef32_pk_f32_fp4 v[100:101], v124, 1.0 op_sel:[1,0,0]
	v_cvt_scalef32_pk_f32_fp4 v[102:103], v124, 1.0 op_sel:[0,1,0]
	v_cvt_scalef32_pk_f32_fp4 v[104:105], v124, 1.0 op_sel:[1,1,0]
	v_pk_fma_f32 v[82:83], v[30:31], v[98:99], v[82:83] op_sel_hi:[0,1,1]
	v_pk_fma_f32 v[84:85], v[30:31], v[100:101], v[84:85] op_sel_hi:[0,1,1]
	v_pk_fma_f32 v[86:87], v[30:31], v[102:103], v[86:87] op_sel_hi:[0,1,1]
	v_pk_fma_f32 v[88:89], v[30:31], v[104:105], v[88:89] op_sel_hi:[0,1,1]
	v_cvt_scalef32_pk_f32_fp4 v[98:99], v125, 1.0
	v_cvt_scalef32_pk_f32_fp4 v[100:101], v125, 1.0 op_sel:[1,0,0]
	v_cvt_scalef32_pk_f32_fp4 v[102:103], v125, 1.0 op_sel:[0,1,0]
	v_cvt_scalef32_pk_f32_fp4 v[104:105], v125, 1.0 op_sel:[1,1,0]
	v_pk_fma_f32 v[90:91], v[30:31], v[98:99], v[90:91] op_sel_hi:[0,1,1]
	v_pk_fma_f32 v[92:93], v[30:31], v[100:101], v[92:93] op_sel_hi:[0,1,1]
	v_pk_fma_f32 v[94:95], v[30:31], v[102:103], v[94:95] op_sel_hi:[0,1,1]
	v_pk_fma_f32 v[96:97], v[30:31], v[104:105], v[96:97] op_sel_hi:[0,1,1]
	v_cvt_scalef32_pk_f32_fp4 v[98:99], v126, 1.0
	v_cvt_scalef32_pk_f32_fp4 v[100:101], v126, 1.0 op_sel:[1,0,0]
	v_cvt_scalef32_pk_f32_fp4 v[102:103], v126, 1.0 op_sel:[0,1,0]
	v_cvt_scalef32_pk_f32_fp4 v[104:105], v126, 1.0 op_sel:[1,1,0]
	v_pk_fma_f32 v[66:67], v[30:31], v[98:99], v[66:67] op_sel:[1,0,0] op_sel_hi:[1,1,1]
	v_pk_fma_f32 v[68:69], v[30:31], v[100:101], v[68:69] op_sel:[1,0,0] op_sel_hi:[1,1,1]
	v_pk_fma_f32 v[70:71], v[30:31], v[102:103], v[70:71] op_sel:[1,0,0] op_sel_hi:[1,1,1]
	v_pk_fma_f32 v[72:73], v[30:31], v[104:105], v[72:73] op_sel:[1,0,0] op_sel_hi:[1,1,1]
	v_cvt_scalef32_pk_f32_fp4 v[98:99], v127, 1.0
	v_cvt_scalef32_pk_f32_fp4 v[100:101], v127, 1.0 op_sel:[1,0,0]
	v_cvt_scalef32_pk_f32_fp4 v[102:103], v127, 1.0 op_sel:[0,1,0]
	v_cvt_scalef32_pk_f32_fp4 v[104:105], v127, 1.0 op_sel:[1,1,0]
	v_pk_fma_f32 v[74:75], v[30:31], v[98:99], v[74:75] op_sel:[1,0,0] op_sel_hi:[1,1,1]
	v_pk_fma_f32 v[76:77], v[30:31], v[100:101], v[76:77] op_sel:[1,0,0] op_sel_hi:[1,1,1]
	v_pk_fma_f32 v[78:79], v[30:31], v[102:103], v[78:79] op_sel:[1,0,0] op_sel_hi:[1,1,1]
	v_pk_fma_f32 v[80:81], v[30:31], v[104:105], v[80:81] op_sel:[1,0,0] op_sel_hi:[1,1,1]
	v_cvt_scalef32_pk_f32_fp4 v[98:99], v128, 1.0
	v_cvt_scalef32_pk_f32_fp4 v[100:101], v128, 1.0 op_sel:[1,0,0]
	v_cvt_scalef32_pk_f32_fp4 v[102:103], v128, 1.0 op_sel:[0,1,0]
	v_cvt_scalef32_pk_f32_fp4 v[104:105], v128, 1.0 op_sel:[1,1,0]
	v_pk_fma_f32 v[82:83], v[30:31], v[98:99], v[82:83] op_sel:[1,0,0] op_sel_hi:[1,1,1]
	v_pk_fma_f32 v[84:85], v[30:31], v[100:101], v[84:85] op_sel:[1,0,0] op_sel_hi:[1,1,1]
	v_pk_fma_f32 v[86:87], v[30:31], v[102:103], v[86:87] op_sel:[1,0,0] op_sel_hi:[1,1,1]
	v_pk_fma_f32 v[88:89], v[30:31], v[104:105], v[88:89] op_sel:[1,0,0] op_sel_hi:[1,1,1]
	v_cvt_scalef32_pk_f32_fp4 v[98:99], v129, 1.0
	v_cvt_scalef32_pk_f32_fp4 v[100:101], v129, 1.0 op_sel:[1,0,0]
	v_cvt_scalef32_pk_f32_fp4 v[102:103], v129, 1.0 op_sel:[0,1,0]
	v_cvt_scalef32_pk_f32_fp4 v[104:105], v129, 1.0 op_sel:[1,1,0]
	v_pk_fma_f32 v[90:91], v[30:31], v[98:99], v[90:91] op_sel:[1,0,0] op_sel_hi:[1,1,1]
	v_pk_fma_f32 v[92:93], v[30:31], v[100:101], v[92:93] op_sel:[1,0,0] op_sel_hi:[1,1,1]
	v_pk_fma_f32 v[94:95], v[30:31], v[102:103], v[94:95] op_sel:[1,0,0] op_sel_hi:[1,1,1]
	v_pk_fma_f32 v[96:97], v[30:31], v[104:105], v[96:97] op_sel:[1,0,0] op_sel_hi:[1,1,1]
	v_cvt_scalef32_pk_f32_fp4 v[98:99], v130, 1.0
	v_cvt_scalef32_pk_f32_fp4 v[100:101], v130, 1.0 op_sel:[1,0,0]
	v_cvt_scalef32_pk_f32_fp4 v[102:103], v130, 1.0 op_sel:[0,1,0]
	v_cvt_scalef32_pk_f32_fp4 v[104:105], v130, 1.0 op_sel:[1,1,0]
	v_pk_fma_f32 v[66:67], v[32:33], v[98:99], v[66:67] op_sel_hi:[0,1,1]
	v_pk_fma_f32 v[68:69], v[32:33], v[100:101], v[68:69] op_sel_hi:[0,1,1]
	v_pk_fma_f32 v[70:71], v[32:33], v[102:103], v[70:71] op_sel_hi:[0,1,1]
	v_pk_fma_f32 v[72:73], v[32:33], v[104:105], v[72:73] op_sel_hi:[0,1,1]
	v_cvt_scalef32_pk_f32_fp4 v[98:99], v131, 1.0
	v_cvt_scalef32_pk_f32_fp4 v[100:101], v131, 1.0 op_sel:[1,0,0]
	v_cvt_scalef32_pk_f32_fp4 v[102:103], v131, 1.0 op_sel:[0,1,0]
	v_cvt_scalef32_pk_f32_fp4 v[104:105], v131, 1.0 op_sel:[1,1,0]
	v_pk_fma_f32 v[74:75], v[32:33], v[98:99], v[74:75] op_sel_hi:[0,1,1]
	v_pk_fma_f32 v[76:77], v[32:33], v[100:101], v[76:77] op_sel_hi:[0,1,1]
	v_pk_fma_f32 v[78:79], v[32:33], v[102:103], v[78:79] op_sel_hi:[0,1,1]
	v_pk_fma_f32 v[80:81], v[32:33], v[104:105], v[80:81] op_sel_hi:[0,1,1]
	v_cvt_scalef32_pk_f32_fp4 v[98:99], v132, 1.0
	v_cvt_scalef32_pk_f32_fp4 v[100:101], v132, 1.0 op_sel:[1,0,0]
	v_cvt_scalef32_pk_f32_fp4 v[102:103], v132, 1.0 op_sel:[0,1,0]
; __device__ __forceinline__ void phase_peer_v(const Params& p, int layer, int xs, int wid0, int wstride, bool last, char* smraw) {
;     ...
;   auto half_fma = [&](const u32x4 (&q)[8], const f32x4& c0, const f32x4& c1) {
; #pragma unroll
;     for (int i = 0; i < 8; ++i) {
;       const float ci = i < 4 ? c0[i & 3] : c1[i & 3];
; #pragma unroll
;       for (int m = 0; m < 4; ++m) {
;         unsigned dw = q[i][m];
;         asm volatile("" : "+v"(dw) : "v"(acc[(8 * m + 31) & 31]));
;         const f32x2 e0 = __builtin_amdgcn_cvt_scalef32_pk_f32_fp4(dw, 1.0f, 0), e1 = __builtin_amdgcn_cvt_scalef32_pk_f32_fp4(dw, 1.0f, 1);
;         const f32x2 e2 = __builtin_amdgcn_cvt_scalef32_pk_f32_fp4(dw, 1.0f, 2), e3 = __builtin_amdgcn_cvt_scalef32_pk_f32_fp4(dw, 1.0f, 3);
;         acc[8 * m + 0] += ci * e0[0]; acc[8 * m + 1] += ci * e0[1]; acc[8 * m + 2] += ci * e1[0]; acc[8 * m + 3] += ci * e1[1];
;         acc[8 * m + 4] += ci * e2[0]; acc[8 * m + 5] += ci * e2[1]; acc[8 * m + 6] += ci * e3[0]; acc[8 * m + 7] += ci * e3[1];
;       }
;     }
	v_cvt_scalef32_pk_f32_fp4 v[104:105], v132, 1.0 op_sel:[1,1,0]
	v_pk_fma_f32 v[82:83], v[32:33], v[98:99], v[82:83] op_sel_hi:[0,1,1]
	v_pk_fma_f32 v[84:85], v[32:33], v[100:101], v[84:85] op_sel_hi:[0,1,1]
	v_pk_fma_f32 v[86:87], v[32:33], v[102:103], v[86:87] op_sel_hi:[0,1,1]
	v_pk_fma_f32 v[88:89], v[32:33], v[104:105], v[88:89] op_sel_hi:[0,1,1]
	v_cvt_scalef32_pk_f32_fp4 v[98:99], v133, 1.0
	v_cvt_scalef32_pk_f32_fp4 v[100:101], v133, 1.0 op_sel:[1,0,0]
	v_cvt_scalef32_pk_f32_fp4 v[102:103], v133, 1.0 op_sel:[0,1,0]
	v_cvt_scalef32_pk_f32_fp4 v[104:105], v133, 1.0 op_sel:[1,1,0]
	v_pk_fma_f32 v[90:91], v[32:33], v[98:99], v[90:91] op_sel_hi:[0,1,1]
	v_pk_fma_f32 v[92:93], v[32:33], v[100:101], v[92:93] op_sel_hi:[0,1,1]
	v_pk_fma_f32 v[94:95], v[32:33], v[102:103], v[94:95] op_sel_hi:[0,1,1]
	v_pk_fma_f32 v[96:97], v[32:33], v[104:105], v[96:97] op_sel_hi:[0,1,1]
	v_cvt_scalef32_pk_f32_fp4 v[98:99], v134, 1.0
	v_cvt_scalef32_pk_f32_fp4 v[100:101], v134, 1.0 op_sel:[1,0,0]
	v_cvt_scalef32_pk_f32_fp4 v[102:103], v134, 1.0 op_sel:[0,1,0]
	v_cvt_scalef32_pk_f32_fp4 v[104:105], v134, 1.0 op_sel:[1,1,0]
	v_pk_fma_f32 v[66:67], v[32:33], v[98:99], v[66:67] op_sel:[1,0,0] op_sel_hi:[1,1,1]
	v_pk_fma_f32 v[68:69], v[32:33], v[100:101], v[68:69] op_sel:[1,0,0] op_sel_hi:[1,1,1]
	v_pk_fma_f32 v[70:71], v[32:33], v[102:103], v[70:71] op_sel:[1,0,0] op_sel_hi:[1,1,1]
	v_pk_fma_f32 v[72:73], v[32:33], v[104:105], v[72:73] op_sel:[1,0,0] op_sel_hi:[1,1,1]
	v_cvt_scalef32_pk_f32_fp4 v[98:99], v135, 1.0
	v_cvt_scalef32_pk_f32_fp4 v[100:101], v135, 1.0 op_sel:[1,0,0]
	v_cvt_scalef32_pk_f32_fp4 v[102:103], v135, 1.0 op_sel:[0,1,0]
	v_cvt_scalef32_pk_f32_fp4 v[104:105], v135, 1.0 op_sel:[1,1,0]
	v_pk_fma_f32 v[74:75], v[32:33], v[98:99], v[74:75] op_sel:[1,0,0] op_sel_hi:[1,1,1]
	v_pk_fma_f32 v[76:77], v[32:33], v[100:101], v[76:77] op_sel:[1,0,0] op_sel_hi:[1,1,1]
	v_pk_fma_f32 v[78:79], v[32:33], v[102:103], v[78:79] op_sel:[1,0,0] op_sel_hi:[1,1,1]
	v_pk_fma_f32 v[80:81], v[32:33], v[104:105], v[80:81] op_sel:[1,0,0] op_sel_hi:[1,1,1]
	v_cvt_scalef32_pk_f32_fp4 v[98:99], v136, 1.0
	v_cvt_scalef32_pk_f32_fp4 v[100:101], v136, 1.0 op_sel:[1,0,0]
	v_cvt_scalef32_pk_f32_fp4 v[102:103], v136, 1.0 op_sel:[0,1,0]
	v_cvt_scalef32_pk_f32_fp4 v[104:105], v136, 1.0 op_sel:[1,1,0]
	v_pk_fma_f32 v[82:83], v[32:33], v[98:99], v[82:83] op_sel:[1,0,0] op_sel_hi:[1,1,1]
	v_pk_fma_f32 v[84:85], v[32:33], v[100:101], v[84:85] op_sel:[1,0,0] op_sel_hi:[1,1,1]
	v_pk_fma_f32 v[86:87], v[32:33], v[102:103], v[86:87] op_sel:[1,0,0] op_sel_hi:[1,1,1]
	v_pk_fma_f32 v[88:89], v[32:33], v[104:105], v[88:89] op_sel:[1,0,0] op_sel_hi:[1,1,1]
	v_cvt_scalef32_pk_f32_fp4 v[98:99], v137, 1.0
	v_cvt_scalef32_pk_f32_fp4 v[100:101], v137, 1.0 op_sel:[1,0,0]
	v_cvt_scalef32_pk_f32_fp4 v[102:103], v137, 1.0 op_sel:[0,1,0]
	v_cvt_scalef32_pk_f32_fp4 v[104:105], v137, 1.0 op_sel:[1,1,0]
	v_pk_fma_f32 v[90:91], v[32:33], v[98:99], v[90:91] op_sel:[1,0,0] op_sel_hi:[1,1,1]
	v_pk_fma_f32 v[92:93], v[32:33], v[100:101], v[92:93] op_sel:[1,0,0] op_sel_hi:[1,1,1]
	v_pk_fma_f32 v[94:95], v[32:33], v[102:103], v[94:95] op_sel:[1,0,0] op_sel_hi:[1,1,1]
	v_pk_fma_f32 v[96:97], v[32:33], v[104:105], v[96:97] op_sel:[1,0,0] op_sel_hi:[1,1,1]
	v_cvt_scalef32_pk_f32_fp4 v[98:99], v138, 1.0
	v_cvt_scalef32_pk_f32_fp4 v[100:101], v138, 1.0 op_sel:[1,0,0]
	v_cvt_scalef32_pk_f32_fp4 v[102:103], v138, 1.0 op_sel:[0,1,0]
	v_cvt_scalef32_pk_f32_fp4 v[104:105], v138, 1.0 op_sel:[1,1,0]
	v_pk_fma_f32 v[66:67], v[34:35], v[98:99], v[66:67] op_sel_hi:[0,1,1]
	v_pk_fma_f32 v[68:69], v[34:35], v[100:101], v[68:69] op_sel_hi:[0,1,1]
	v_pk_fma_f32 v[70:71], v[34:35], v[102:103], v[70:71] op_sel_hi:[0,1,1]
	v_pk_fma_f32 v[72:73], v[34:35], v[104:105], v[72:73] op_sel_hi:[0,1,1]
	v_cvt_scalef32_pk_f32_fp4 v[98:99], v139, 1.0
	v_cvt_scalef32_pk_f32_fp4 v[100:101], v139, 1.0 op_sel:[1,0,0]
	v_cvt_scalef32_pk_f32_fp4 v[102:103], v139, 1.0 op_sel:[0,1,0]
	v_cvt_scalef32_pk_f32_fp4 v[104:105], v139, 1.0 op_sel:[1,1,0]
	v_pk_fma_f32 v[74:75], v[34:35], v[98:99], v[74:75] op_sel_hi:[0,1,1]
	v_pk_fma_f32 v[76:77], v[34:35], v[100:101], v[76:77] op_sel_hi:[0,1,1]
	v_pk_fma_f32 v[78:79], v[34:35], v[102:103], v[78:79] op_sel_hi:[0,1,1]
	v_pk_fma_f32 v[80:81], v[34:35], v[104:105], v[80:81] op_sel_hi:[0,1,1]
	v_cvt_scalef32_pk_f32_fp4 v[98:99], v140, 1.0
	v_cvt_scalef32_pk_f32_fp4 v[100:101], v140, 1.0 op_sel:[1,0,0]
	v_cvt_scalef32_pk_f32_fp4 v[102:103], v140, 1.0 op_sel:[0,1,0]
	v_cvt_scalef32_pk_f32_fp4 v[104:105], v140, 1.0 op_sel:[1,1,0]
	v_pk_fma_f32 v[82:83], v[34:35], v[98:99], v[82:83] op_sel_hi:[0,1,1]
	v_pk_fma_f32 v[84:85], v[34:35], v[100:101], v[84:85] op_sel_hi:[0,1,1]
	v_pk_fma_f32 v[86:87], v[34:35], v[102:103], v[86:87] op_sel_hi:[0,1,1]
	v_pk_fma_f32 v[88:89], v[34:35], v[104:105], v[88:89] op_sel_hi:[0,1,1]
	v_cvt_scalef32_pk_f32_fp4 v[98:99], v141, 1.0
	v_cvt_scalef32_pk_f32_fp4 v[100:101], v141, 1.0 op_sel:[1,0,0]
	v_cvt_scalef32_pk_f32_fp4 v[102:103], v141, 1.0 op_sel:[0,1,0]
	v_cvt_scalef32_pk_f32_fp4 v[104:105], v141, 1.0 op_sel:[1,1,0]
	v_pk_fma_f32 v[90:91], v[34:35], v[98:99], v[90:91] op_sel_hi:[0,1,1]
	v_pk_fma_f32 v[92:93], v[34:35], v[100:101], v[92:93] op_sel_hi:[0,1,1]
	v_pk_fma_f32 v[94:95], v[34:35], v[102:103], v[94:95] op_sel_hi:[0,1,1]
	v_pk_fma_f32 v[96:97], v[34:35], v[104:105], v[96:97] op_sel_hi:[0,1,1]
	v_cvt_scalef32_pk_f32_fp4 v[98:99], v142, 1.0
	v_cvt_scalef32_pk_f32_fp4 v[100:101], v142, 1.0 op_sel:[1,0,0]
	v_cvt_scalef32_pk_f32_fp4 v[102:103], v142, 1.0 op_sel:[0,1,0]
	v_cvt_scalef32_pk_f32_fp4 v[104:105], v142, 1.0 op_sel:[1,1,0]
	v_pk_fma_f32 v[66:67], v[34:35], v[98:99], v[66:67] op_sel:[1,0,0] op_sel_hi:[1,1,1]
; __device__ __forceinline__ void phase_peer_v(const Params& p, int layer, int xs, int wid0, int wstride, bool last, char* smraw) {
;     ...
;   auto half_fma = [&](const u32x4 (&q)[8], const f32x4& c0, const f32x4& c1) {
; #pragma unroll
;     for (int i = 0; i < 8; ++i) {
;       const float ci = i < 4 ? c0[i & 3] : c1[i & 3];
; #pragma unroll
;       for (int m = 0; m < 4; ++m) {
;         unsigned dw = q[i][m];
;         asm volatile("" : "+v"(dw) : "v"(acc[(8 * m + 31) & 31]));
;         const f32x2 e0 = __builtin_amdgcn_cvt_scalef32_pk_f32_fp4(dw, 1.0f, 0), e1 = __builtin_amdgcn_cvt_scalef32_pk_f32_fp4(dw, 1.0f, 1);
;         const f32x2 e2 = __builtin_amdgcn_cvt_scalef32_pk_f32_fp4(dw, 1.0f, 2), e3 = __builtin_amdgcn_cvt_scalef32_pk_f32_fp4(dw, 1.0f, 3);
;         acc[8 * m + 0] += ci * e0[0]; acc[8 * m + 1] += ci * e0[1]; acc[8 * m + 2] += ci * e1[0]; acc[8 * m + 3] += ci * e1[1];
;         acc[8 * m + 4] += ci * e2[0]; acc[8 * m + 5] += ci * e2[1]; acc[8 * m + 6] += ci * e3[0]; acc[8 * m + 7] += ci * e3[1];
;       }
;     }
	v_pk_fma_f32 v[68:69], v[34:35], v[100:101], v[68:69] op_sel:[1,0,0] op_sel_hi:[1,1,1]
	v_pk_fma_f32 v[70:71], v[34:35], v[102:103], v[70:71] op_sel:[1,0,0] op_sel_hi:[1,1,1]
	v_pk_fma_f32 v[72:73], v[34:35], v[104:105], v[72:73] op_sel:[1,0,0] op_sel_hi:[1,1,1]
	v_cvt_scalef32_pk_f32_fp4 v[98:99], v143, 1.0
	v_cvt_scalef32_pk_f32_fp4 v[100:101], v143, 1.0 op_sel:[1,0,0]
	v_cvt_scalef32_pk_f32_fp4 v[102:103], v143, 1.0 op_sel:[0,1,0]
	v_cvt_scalef32_pk_f32_fp4 v[104:105], v143, 1.0 op_sel:[1,1,0]
	v_pk_fma_f32 v[74:75], v[34:35], v[98:99], v[74:75] op_sel:[1,0,0] op_sel_hi:[1,1,1]
	v_pk_fma_f32 v[76:77], v[34:35], v[100:101], v[76:77] op_sel:[1,0,0] op_sel_hi:[1,1,1]
	v_pk_fma_f32 v[78:79], v[34:35], v[102:103], v[78:79] op_sel:[1,0,0] op_sel_hi:[1,1,1]
	v_pk_fma_f32 v[80:81], v[34:35], v[104:105], v[80:81] op_sel:[1,0,0] op_sel_hi:[1,1,1]
	v_cvt_scalef32_pk_f32_fp4 v[98:99], v144, 1.0
	v_cvt_scalef32_pk_f32_fp4 v[100:101], v144, 1.0 op_sel:[1,0,0]
	v_cvt_scalef32_pk_f32_fp4 v[102:103], v144, 1.0 op_sel:[0,1,0]
	v_cvt_scalef32_pk_f32_fp4 v[104:105], v144, 1.0 op_sel:[1,1,0]
	v_pk_fma_f32 v[82:83], v[34:35], v[98:99], v[82:83] op_sel:[1,0,0] op_sel_hi:[1,1,1]
	v_pk_fma_f32 v[84:85], v[34:35], v[100:101], v[84:85] op_sel:[1,0,0] op_sel_hi:[1,1,1]
	v_pk_fma_f32 v[86:87], v[34:35], v[102:103], v[86:87] op_sel:[1,0,0] op_sel_hi:[1,1,1]
	v_pk_fma_f32 v[88:89], v[34:35], v[104:105], v[88:89] op_sel:[1,0,0] op_sel_hi:[1,1,1]
	v_cvt_scalef32_pk_f32_fp4 v[98:99], v145, 1.0
	v_cvt_scalef32_pk_f32_fp4 v[100:101], v145, 1.0 op_sel:[1,0,0]
	v_cvt_scalef32_pk_f32_fp4 v[102:103], v145, 1.0 op_sel:[0,1,0]
	v_cvt_scalef32_pk_f32_fp4 v[104:105], v145, 1.0 op_sel:[1,1,0]
	v_pk_fma_f32 v[90:91], v[34:35], v[98:99], v[90:91] op_sel:[1,0,0] op_sel_hi:[1,1,1]
	v_pk_fma_f32 v[92:93], v[34:35], v[100:101], v[92:93] op_sel:[1,0,0] op_sel_hi:[1,1,1]
	v_pk_fma_f32 v[94:95], v[34:35], v[102:103], v[94:95] op_sel:[1,0,0] op_sel_hi:[1,1,1]
	v_pk_fma_f32 v[96:97], v[34:35], v[104:105], v[96:97] op_sel:[1,0,0] op_sel_hi:[1,1,1]
	v_cvt_scalef32_pk_f32_fp4 v[98:99], v146, 1.0
	v_cvt_scalef32_pk_f32_fp4 v[100:101], v146, 1.0 op_sel:[1,0,0]
	v_cvt_scalef32_pk_f32_fp4 v[102:103], v146, 1.0 op_sel:[0,1,0]
	v_cvt_scalef32_pk_f32_fp4 v[104:105], v146, 1.0 op_sel:[1,1,0]
	v_pk_fma_f32 v[66:67], v[36:37], v[98:99], v[66:67] op_sel_hi:[0,1,1]
	v_pk_fma_f32 v[68:69], v[36:37], v[100:101], v[68:69] op_sel_hi:[0,1,1]
	v_pk_fma_f32 v[70:71], v[36:37], v[102:103], v[70:71] op_sel_hi:[0,1,1]
	v_pk_fma_f32 v[72:73], v[36:37], v[104:105], v[72:73] op_sel_hi:[0,1,1]
	v_cvt_scalef32_pk_f32_fp4 v[98:99], v147, 1.0
	v_cvt_scalef32_pk_f32_fp4 v[100:101], v147, 1.0 op_sel:[1,0,0]
	v_cvt_scalef32_pk_f32_fp4 v[102:103], v147, 1.0 op_sel:[0,1,0]
	v_cvt_scalef32_pk_f32_fp4 v[104:105], v147, 1.0 op_sel:[1,1,0]
	v_pk_fma_f32 v[74:75], v[36:37], v[98:99], v[74:75] op_sel_hi:[0,1,1]
	v_pk_fma_f32 v[76:77], v[36:37], v[100:101], v[76:77] op_sel_hi:[0,1,1]
	v_pk_fma_f32 v[78:79], v[36:37], v[102:103], v[78:79] op_sel_hi:[0,1,1]
	v_pk_fma_f32 v[80:81], v[36:37], v[104:105], v[80:81] op_sel_hi:[0,1,1]
	v_cvt_scalef32_pk_f32_fp4 v[98:99], v148, 1.0
	v_cvt_scalef32_pk_f32_fp4 v[100:101], v148, 1.0 op_sel:[1,0,0]
	v_cvt_scalef32_pk_f32_fp4 v[102:103], v148, 1.0 op_sel:[0,1,0]
	v_cvt_scalef32_pk_f32_fp4 v[104:105], v148, 1.0 op_sel:[1,1,0]
	v_pk_fma_f32 v[82:83], v[36:37], v[98:99], v[82:83] op_sel_hi:[0,1,1]
	v_pk_fma_f32 v[84:85], v[36:37], v[100:101], v[84:85] op_sel_hi:[0,1,1]
	v_pk_fma_f32 v[86:87], v[36:37], v[102:103], v[86:87] op_sel_hi:[0,1,1]
	v_pk_fma_f32 v[88:89], v[36:37], v[104:105], v[88:89] op_sel_hi:[0,1,1]
	v_cvt_scalef32_pk_f32_fp4 v[98:99], v149, 1.0
	v_cvt_scalef32_pk_f32_fp4 v[100:101], v149, 1.0 op_sel:[1,0,0]
	v_cvt_scalef32_pk_f32_fp4 v[102:103], v149, 1.0 op_sel:[0,1,0]
	v_cvt_scalef32_pk_f32_fp4 v[104:105], v149, 1.0 op_sel:[1,1,0]
	v_pk_fma_f32 v[90:91], v[36:37], v[98:99], v[90:91] op_sel_hi:[0,1,1]
	v_pk_fma_f32 v[92:93], v[36:37], v[100:101], v[92:93] op_sel_hi:[0,1,1]
	v_pk_fma_f32 v[94:95], v[36:37], v[102:103], v[94:95] op_sel_hi:[0,1,1]
	v_pk_fma_f32 v[96:97], v[36:37], v[104:105], v[96:97] op_sel_hi:[0,1,1]
	v_cvt_scalef32_pk_f32_fp4 v[98:99], v150, 1.0
	v_cvt_scalef32_pk_f32_fp4 v[100:101], v150, 1.0 op_sel:[1,0,0]
	v_cvt_scalef32_pk_f32_fp4 v[102:103], v150, 1.0 op_sel:[0,1,0]
	v_cvt_scalef32_pk_f32_fp4 v[104:105], v150, 1.0 op_sel:[1,1,0]
	v_pk_fma_f32 v[66:67], v[36:37], v[98:99], v[66:67] op_sel:[1,0,0] op_sel_hi:[1,1,1]
	v_pk_fma_f32 v[68:69], v[36:37], v[100:101], v[68:69] op_sel:[1,0,0] op_sel_hi:[1,1,1]
	v_pk_fma_f32 v[70:71], v[36:37], v[102:103], v[70:71] op_sel:[1,0,0] op_sel_hi:[1,1,1]
	v_pk_fma_f32 v[72:73], v[36:37], v[104:105], v[72:73] op_sel:[1,0,0] op_sel_hi:[1,1,1]
	v_cvt_scalef32_pk_f32_fp4 v[98:99], v151, 1.0
	v_cvt_scalef32_pk_f32_fp4 v[100:101], v151, 1.0 op_sel:[1,0,0]
	v_cvt_scalef32_pk_f32_fp4 v[102:103], v151, 1.0 op_sel:[0,1,0]
	v_cvt_scalef32_pk_f32_fp4 v[104:105], v151, 1.0 op_sel:[1,1,0]
	v_pk_fma_f32 v[74:75], v[36:37], v[98:99], v[74:75] op_sel:[1,0,0] op_sel_hi:[1,1,1]
	v_pk_fma_f32 v[76:77], v[36:37], v[100:101], v[76:77] op_sel:[1,0,0] op_sel_hi:[1,1,1]
	v_pk_fma_f32 v[78:79], v[36:37], v[102:103], v[78:79] op_sel:[1,0,0] op_sel_hi:[1,1,1]
	v_pk_fma_f32 v[80:81], v[36:37], v[104:105], v[80:81] op_sel:[1,0,0] op_sel_hi:[1,1,1]
	v_cvt_scalef32_pk_f32_fp4 v[98:99], v152, 1.0
	v_cvt_scalef32_pk_f32_fp4 v[100:101], v152, 1.0 op_sel:[1,0,0]
	v_cvt_scalef32_pk_f32_fp4 v[102:103], v152, 1.0 op_sel:[0,1,0]
	v_cvt_scalef32_pk_f32_fp4 v[104:105], v152, 1.0 op_sel:[1,1,0]
	v_pk_fma_f32 v[82:83], v[36:37], v[98:99], v[82:83] op_sel:[1,0,0] op_sel_hi:[1,1,1]
; __device__ __forceinline__ void phase_peer_v(const Params& p, int layer, int xs, int wid0, int wstride, bool last, char* smraw) {
;     ...
;   auto half_fma = [&](const u32x4 (&q)[8], const f32x4& c0, const f32x4& c1) {
; #pragma unroll
;     for (int i = 0; i < 8; ++i) {
;       const float ci = i < 4 ? c0[i & 3] : c1[i & 3];
; #pragma unroll
;       for (int m = 0; m < 4; ++m) {
;         unsigned dw = q[i][m];
;         asm volatile("" : "+v"(dw) : "v"(acc[(8 * m + 31) & 31]));
;         const f32x2 e0 = __builtin_amdgcn_cvt_scalef32_pk_f32_fp4(dw, 1.0f, 0), e1 = __builtin_amdgcn_cvt_scalef32_pk_f32_fp4(dw, 1.0f, 1);
;         const f32x2 e2 = __builtin_amdgcn_cvt_scalef32_pk_f32_fp4(dw, 1.0f, 2), e3 = __builtin_amdgcn_cvt_scalef32_pk_f32_fp4(dw, 1.0f, 3);
;         acc[8 * m + 0] += ci * e0[0]; acc[8 * m + 1] += ci * e0[1]; acc[8 * m + 2] += ci * e1[0]; acc[8 * m + 3] += ci * e1[1];
;         acc[8 * m + 4] += ci * e2[0]; acc[8 * m + 5] += ci * e2[1]; acc[8 * m + 6] += ci * e3[0]; acc[8 * m + 7] += ci * e3[1];
;       }
;     }
	v_pk_fma_f32 v[84:85], v[36:37], v[100:101], v[84:85] op_sel:[1,0,0] op_sel_hi:[1,1,1]
	v_pk_fma_f32 v[86:87], v[36:37], v[102:103], v[86:87] op_sel:[1,0,0] op_sel_hi:[1,1,1]
	v_pk_fma_f32 v[88:89], v[36:37], v[104:105], v[88:89] op_sel:[1,0,0] op_sel_hi:[1,1,1]
	v_cvt_scalef32_pk_f32_fp4 v[98:99], v153, 1.0
	v_cvt_scalef32_pk_f32_fp4 v[100:101], v153, 1.0 op_sel:[1,0,0]
	v_cvt_scalef32_pk_f32_fp4 v[102:103], v153, 1.0 op_sel:[0,1,0]
	v_cvt_scalef32_pk_f32_fp4 v[104:105], v153, 1.0 op_sel:[1,1,0]
	v_pk_fma_f32 v[90:91], v[36:37], v[98:99], v[90:91] op_sel:[1,0,0] op_sel_hi:[1,1,1]
	v_pk_fma_f32 v[92:93], v[36:37], v[100:101], v[92:93] op_sel:[1,0,0] op_sel_hi:[1,1,1]
	v_pk_fma_f32 v[94:95], v[36:37], v[102:103], v[94:95] op_sel:[1,0,0] op_sel_hi:[1,1,1]
	v_pk_fma_f32 v[96:97], v[36:37], v[104:105], v[96:97] op_sel:[1,0,0] op_sel_hi:[1,1,1]
	v_cvt_scalef32_pk_f32_fp4 v[98:99], v154, 1.0
	v_cvt_scalef32_pk_f32_fp4 v[100:101], v154, 1.0 op_sel:[1,0,0]
	v_cvt_scalef32_pk_f32_fp4 v[102:103], v154, 1.0 op_sel:[0,1,0]
	v_cvt_scalef32_pk_f32_fp4 v[104:105], v154, 1.0 op_sel:[1,1,0]
	v_pk_fma_f32 v[66:67], v[38:39], v[98:99], v[66:67] op_sel_hi:[0,1,1]
	v_pk_fma_f32 v[68:69], v[38:39], v[100:101], v[68:69] op_sel_hi:[0,1,1]
	v_pk_fma_f32 v[70:71], v[38:39], v[102:103], v[70:71] op_sel_hi:[0,1,1]
	v_pk_fma_f32 v[72:73], v[38:39], v[104:105], v[72:73] op_sel_hi:[0,1,1]
	v_cvt_scalef32_pk_f32_fp4 v[98:99], v155, 1.0
	v_cvt_scalef32_pk_f32_fp4 v[100:101], v155, 1.0 op_sel:[1,0,0]
	v_cvt_scalef32_pk_f32_fp4 v[102:103], v155, 1.0 op_sel:[0,1,0]
	v_cvt_scalef32_pk_f32_fp4 v[104:105], v155, 1.0 op_sel:[1,1,0]
	v_pk_fma_f32 v[74:75], v[38:39], v[98:99], v[74:75] op_sel_hi:[0,1,1]
	v_pk_fma_f32 v[76:77], v[38:39], v[100:101], v[76:77] op_sel_hi:[0,1,1]
	v_pk_fma_f32 v[78:79], v[38:39], v[102:103], v[78:79] op_sel_hi:[0,1,1]
	v_pk_fma_f32 v[80:81], v[38:39], v[104:105], v[80:81] op_sel_hi:[0,1,1]
	v_cvt_scalef32_pk_f32_fp4 v[98:99], v156, 1.0
	v_cvt_scalef32_pk_f32_fp4 v[100:101], v156, 1.0 op_sel:[1,0,0]
	v_cvt_scalef32_pk_f32_fp4 v[102:103], v156, 1.0 op_sel:[0,1,0]
	v_cvt_scalef32_pk_f32_fp4 v[104:105], v156, 1.0 op_sel:[1,1,0]
	v_pk_fma_f32 v[82:83], v[38:39], v[98:99], v[82:83] op_sel_hi:[0,1,1]
	v_pk_fma_f32 v[84:85], v[38:39], v[100:101], v[84:85] op_sel_hi:[0,1,1]
	v_pk_fma_f32 v[86:87], v[38:39], v[102:103], v[86:87] op_sel_hi:[0,1,1]
	v_pk_fma_f32 v[88:89], v[38:39], v[104:105], v[88:89] op_sel_hi:[0,1,1]
	v_cvt_scalef32_pk_f32_fp4 v[98:99], v157, 1.0
	v_cvt_scalef32_pk_f32_fp4 v[100:101], v157, 1.0 op_sel:[1,0,0]
	v_cvt_scalef32_pk_f32_fp4 v[102:103], v157, 1.0 op_sel:[0,1,0]
	v_cvt_scalef32_pk_f32_fp4 v[104:105], v157, 1.0 op_sel:[1,1,0]
	v_pk_fma_f32 v[90:91], v[38:39], v[98:99], v[90:91] op_sel_hi:[0,1,1]
	v_pk_fma_f32 v[92:93], v[38:39], v[100:101], v[92:93] op_sel_hi:[0,1,1]
	v_pk_fma_f32 v[94:95], v[38:39], v[102:103], v[94:95] op_sel_hi:[0,1,1]
	v_pk_fma_f32 v[96:97], v[38:39], v[104:105], v[96:97] op_sel_hi:[0,1,1]
	v_cvt_scalef32_pk_f32_fp4 v[98:99], v158, 1.0
	v_cvt_scalef32_pk_f32_fp4 v[100:101], v158, 1.0 op_sel:[1,0,0]
	v_cvt_scalef32_pk_f32_fp4 v[102:103], v158, 1.0 op_sel:[0,1,0]
	v_cvt_scalef32_pk_f32_fp4 v[104:105], v158, 1.0 op_sel:[1,1,0]
	v_pk_fma_f32 v[66:67], v[38:39], v[98:99], v[66:67] op_sel:[1,0,0] op_sel_hi:[1,1,1]
	v_pk_fma_f32 v[68:69], v[38:39], v[100:101], v[68:69] op_sel:[1,0,0] op_sel_hi:[1,1,1]
	v_pk_fma_f32 v[70:71], v[38:39], v[102:103], v[70:71] op_sel:[1,0,0] op_sel_hi:[1,1,1]
	v_pk_fma_f32 v[72:73], v[38:39], v[104:105], v[72:73] op_sel:[1,0,0] op_sel_hi:[1,1,1]
	v_cvt_scalef32_pk_f32_fp4 v[98:99], v159, 1.0
	v_cvt_scalef32_pk_f32_fp4 v[100:101], v159, 1.0 op_sel:[1,0,0]
	v_cvt_scalef32_pk_f32_fp4 v[102:103], v159, 1.0 op_sel:[0,1,0]
	v_cvt_scalef32_pk_f32_fp4 v[104:105], v159, 1.0 op_sel:[1,1,0]
	v_pk_fma_f32 v[74:75], v[38:39], v[98:99], v[74:75] op_sel:[1,0,0] op_sel_hi:[1,1,1]
	v_pk_fma_f32 v[76:77], v[38:39], v[100:101], v[76:77] op_sel:[1,0,0] op_sel_hi:[1,1,1]
	v_pk_fma_f32 v[78:79], v[38:39], v[102:103], v[78:79] op_sel:[1,0,0] op_sel_hi:[1,1,1]
	v_pk_fma_f32 v[80:81], v[38:39], v[104:105], v[80:81] op_sel:[1,0,0] op_sel_hi:[1,1,1]
	v_cvt_scalef32_pk_f32_fp4 v[98:99], v160, 1.0
	v_cvt_scalef32_pk_f32_fp4 v[100:101], v160, 1.0 op_sel:[1,0,0]
	v_cvt_scalef32_pk_f32_fp4 v[102:103], v160, 1.0 op_sel:[0,1,0]
	v_cvt_scalef32_pk_f32_fp4 v[104:105], v160, 1.0 op_sel:[1,1,0]
	v_pk_fma_f32 v[82:83], v[38:39], v[98:99], v[82:83] op_sel:[1,0,0] op_sel_hi:[1,1,1]
	v_pk_fma_f32 v[84:85], v[38:39], v[100:101], v[84:85] op_sel:[1,0,0] op_sel_hi:[1,1,1]
	v_pk_fma_f32 v[86:87], v[38:39], v[102:103], v[86:87] op_sel:[1,0,0] op_sel_hi:[1,1,1]
	v_pk_fma_f32 v[88:89], v[38:39], v[104:105], v[88:89] op_sel:[1,0,0] op_sel_hi:[1,1,1]
	v_cvt_scalef32_pk_f32_fp4 v[98:99], v161, 1.0
	v_cvt_scalef32_pk_f32_fp4 v[100:101], v161, 1.0 op_sel:[1,0,0]
	v_cvt_scalef32_pk_f32_fp4 v[102:103], v161, 1.0 op_sel:[0,1,0]
	v_cvt_scalef32_pk_f32_fp4 v[104:105], v161, 1.0 op_sel:[1,1,0]
	v_pk_fma_f32 v[90:91], v[38:39], v[98:99], v[90:91] op_sel:[1,0,0] op_sel_hi:[1,1,1]
	v_pk_fma_f32 v[92:93], v[38:39], v[100:101], v[92:93] op_sel:[1,0,0] op_sel_hi:[1,1,1]
	v_pk_fma_f32 v[94:95], v[38:39], v[102:103], v[94:95] op_sel:[1,0,0] op_sel_hi:[1,1,1]
	v_pk_fma_f32 v[96:97], v[38:39], v[104:105], v[96:97] op_sel:[1,0,0] op_sel_hi:[1,1,1]
	v_cvt_scalef32_pk_f32_fp4 v[98:99], v162, 1.0
	v_cvt_scalef32_pk_f32_fp4 v[100:101], v162, 1.0 op_sel:[1,0,0]
	v_cvt_scalef32_pk_f32_fp4 v[102:103], v162, 1.0 op_sel:[0,1,0]
	v_cvt_scalef32_pk_f32_fp4 v[104:105], v162, 1.0 op_sel:[1,1,0]
	v_pk_fma_f32 v[66:67], v[40:41], v[98:99], v[66:67] op_sel_hi:[0,1,1]
; __device__ __forceinline__ void phase_peer_v(const Params& p, int layer, int xs, int wid0, int wstride, bool last, char* smraw) {
;     ...
;   auto half_fma = [&](const u32x4 (&q)[8], const f32x4& c0, const f32x4& c1) {
; #pragma unroll
;     for (int i = 0; i < 8; ++i) {
;       const float ci = i < 4 ? c0[i & 3] : c1[i & 3];
; #pragma unroll
;       for (int m = 0; m < 4; ++m) {
;         unsigned dw = q[i][m];
;         asm volatile("" : "+v"(dw) : "v"(acc[(8 * m + 31) & 31]));
;         const f32x2 e0 = __builtin_amdgcn_cvt_scalef32_pk_f32_fp4(dw, 1.0f, 0), e1 = __builtin_amdgcn_cvt_scalef32_pk_f32_fp4(dw, 1.0f, 1);
;         const f32x2 e2 = __builtin_amdgcn_cvt_scalef32_pk_f32_fp4(dw, 1.0f, 2), e3 = __builtin_amdgcn_cvt_scalef32_pk_f32_fp4(dw, 1.0f, 3);
;         acc[8 * m + 0] += ci * e0[0]; acc[8 * m + 1] += ci * e0[1]; acc[8 * m + 2] += ci * e1[0]; acc[8 * m + 3] += ci * e1[1];
;         acc[8 * m + 4] += ci * e2[0]; acc[8 * m + 5] += ci * e2[1]; acc[8 * m + 6] += ci * e3[0]; acc[8 * m + 7] += ci * e3[1];
;       }
;     ...
;     for (int q4 = 0; q4 < 8; ++q4) *(f32x4*)(red + g * 256 + j * 32 + q4 * 4) = f32x4{acc[q4 * 4], acc[q4 * 4 + 1], acc[q4 * 4 + 2], acc[q4 * 4 + 3]};
;     __builtin_amdgcn_fence(__ATOMIC_RELEASE, "wavefront");
;     __builtin_amdgcn_wave_barrier();
;     __builtin_amdgcn_fence(__ATOMIC_ACQUIRE, "wavefront");
;     f32x4 r = {0.f, 0.f, 0.f, 0.f};
; #pragma unroll
;     for (int gg = 0; gg < 8; ++gg) { f32x4 v = *(const f32x4*)(red + gg * 256 + 4 * l); r += v; }
;     asm volatile("" ::: "memory");
;     __builtin_amdgcn_wave_barrier();
;     {
;       hv += r;
;       *(f32x4*)hq = hv;
;       if (!last) { u32x2 o; o[0] = cvtpk(hv[0], hv[1]); o[1] = cvtpk(hv[2], hv[3]); *(u32x2*)((char*)p.hb + ((unsigned)t * 2048u + (unsigned)(sl * 512 + l * 8))) = o; }
;     }
;     tt = tn;
	v_pk_fma_f32 v[68:69], v[40:41], v[100:101], v[68:69] op_sel_hi:[0,1,1]
	v_pk_fma_f32 v[70:71], v[40:41], v[102:103], v[70:71] op_sel_hi:[0,1,1]
	v_pk_fma_f32 v[72:73], v[40:41], v[104:105], v[72:73] op_sel_hi:[0,1,1]
	v_cvt_scalef32_pk_f32_fp4 v[98:99], v163, 1.0
	v_cvt_scalef32_pk_f32_fp4 v[100:101], v163, 1.0 op_sel:[1,0,0]
	v_cvt_scalef32_pk_f32_fp4 v[102:103], v163, 1.0 op_sel:[0,1,0]
	v_cvt_scalef32_pk_f32_fp4 v[104:105], v163, 1.0 op_sel:[1,1,0]
	v_pk_fma_f32 v[74:75], v[40:41], v[98:99], v[74:75] op_sel_hi:[0,1,1]
	v_pk_fma_f32 v[76:77], v[40:41], v[100:101], v[76:77] op_sel_hi:[0,1,1]
	v_pk_fma_f32 v[78:79], v[40:41], v[102:103], v[78:79] op_sel_hi:[0,1,1]
	v_pk_fma_f32 v[80:81], v[40:41], v[104:105], v[80:81] op_sel_hi:[0,1,1]
	v_cvt_scalef32_pk_f32_fp4 v[98:99], v164, 1.0
	v_cvt_scalef32_pk_f32_fp4 v[100:101], v164, 1.0 op_sel:[1,0,0]
	v_cvt_scalef32_pk_f32_fp4 v[102:103], v164, 1.0 op_sel:[0,1,0]
	v_cvt_scalef32_pk_f32_fp4 v[104:105], v164, 1.0 op_sel:[1,1,0]
	v_pk_fma_f32 v[82:83], v[40:41], v[98:99], v[82:83] op_sel_hi:[0,1,1]
	v_pk_fma_f32 v[84:85], v[40:41], v[100:101], v[84:85] op_sel_hi:[0,1,1]
	v_pk_fma_f32 v[86:87], v[40:41], v[102:103], v[86:87] op_sel_hi:[0,1,1]
	v_pk_fma_f32 v[88:89], v[40:41], v[104:105], v[88:89] op_sel_hi:[0,1,1]
	v_cvt_scalef32_pk_f32_fp4 v[98:99], v165, 1.0
	v_cvt_scalef32_pk_f32_fp4 v[100:101], v165, 1.0 op_sel:[1,0,0]
	v_cvt_scalef32_pk_f32_fp4 v[102:103], v165, 1.0 op_sel:[0,1,0]
	v_cvt_scalef32_pk_f32_fp4 v[104:105], v165, 1.0 op_sel:[1,1,0]
	v_pk_fma_f32 v[90:91], v[40:41], v[98:99], v[90:91] op_sel_hi:[0,1,1]
	v_pk_fma_f32 v[92:93], v[40:41], v[100:101], v[92:93] op_sel_hi:[0,1,1]
	v_pk_fma_f32 v[94:95], v[40:41], v[102:103], v[94:95] op_sel_hi:[0,1,1]
	v_pk_fma_f32 v[96:97], v[40:41], v[104:105], v[96:97] op_sel_hi:[0,1,1]
	v_cvt_scalef32_pk_f32_fp4 v[98:99], v166, 1.0
	v_cvt_scalef32_pk_f32_fp4 v[100:101], v166, 1.0 op_sel:[1,0,0]
	v_cvt_scalef32_pk_f32_fp4 v[102:103], v166, 1.0 op_sel:[0,1,0]
	v_cvt_scalef32_pk_f32_fp4 v[104:105], v166, 1.0 op_sel:[1,1,0]
	v_pk_fma_f32 v[66:67], v[40:41], v[98:99], v[66:67] op_sel:[1,0,0] op_sel_hi:[1,1,1]
	v_pk_fma_f32 v[68:69], v[40:41], v[100:101], v[68:69] op_sel:[1,0,0] op_sel_hi:[1,1,1]
	v_pk_fma_f32 v[70:71], v[40:41], v[102:103], v[70:71] op_sel:[1,0,0] op_sel_hi:[1,1,1]
	v_pk_fma_f32 v[72:73], v[40:41], v[104:105], v[72:73] op_sel:[1,0,0] op_sel_hi:[1,1,1]
	v_cvt_scalef32_pk_f32_fp4 v[98:99], v167, 1.0
	v_cvt_scalef32_pk_f32_fp4 v[100:101], v167, 1.0 op_sel:[1,0,0]
	v_cvt_scalef32_pk_f32_fp4 v[102:103], v167, 1.0 op_sel:[0,1,0]
	v_cvt_scalef32_pk_f32_fp4 v[104:105], v167, 1.0 op_sel:[1,1,0]
	v_pk_fma_f32 v[74:75], v[40:41], v[98:99], v[74:75] op_sel:[1,0,0] op_sel_hi:[1,1,1]
	v_pk_fma_f32 v[76:77], v[40:41], v[100:101], v[76:77] op_sel:[1,0,0] op_sel_hi:[1,1,1]
	v_pk_fma_f32 v[78:79], v[40:41], v[102:103], v[78:79] op_sel:[1,0,0] op_sel_hi:[1,1,1]
	v_pk_fma_f32 v[80:81], v[40:41], v[104:105], v[80:81] op_sel:[1,0,0] op_sel_hi:[1,1,1]
	v_cvt_scalef32_pk_f32_fp4 v[98:99], v168, 1.0
	v_cvt_scalef32_pk_f32_fp4 v[100:101], v168, 1.0 op_sel:[1,0,0]
	v_cvt_scalef32_pk_f32_fp4 v[102:103], v168, 1.0 op_sel:[0,1,0]
	v_cvt_scalef32_pk_f32_fp4 v[104:105], v168, 1.0 op_sel:[1,1,0]
	v_pk_fma_f32 v[82:83], v[40:41], v[98:99], v[82:83] op_sel:[1,0,0] op_sel_hi:[1,1,1]
	v_pk_fma_f32 v[84:85], v[40:41], v[100:101], v[84:85] op_sel:[1,0,0] op_sel_hi:[1,1,1]
	v_pk_fma_f32 v[86:87], v[40:41], v[102:103], v[86:87] op_sel:[1,0,0] op_sel_hi:[1,1,1]
	v_pk_fma_f32 v[88:89], v[40:41], v[104:105], v[88:89] op_sel:[1,0,0] op_sel_hi:[1,1,1]
	v_cvt_scalef32_pk_f32_fp4 v[98:99], v169, 1.0
	v_cvt_scalef32_pk_f32_fp4 v[100:101], v169, 1.0 op_sel:[1,0,0]
	v_cvt_scalef32_pk_f32_fp4 v[102:103], v169, 1.0 op_sel:[0,1,0]
	v_cvt_scalef32_pk_f32_fp4 v[104:105], v169, 1.0 op_sel:[1,1,0]
	v_pk_fma_f32 v[90:91], v[40:41], v[98:99], v[90:91] op_sel:[1,0,0] op_sel_hi:[1,1,1]
	v_pk_fma_f32 v[92:93], v[40:41], v[100:101], v[92:93] op_sel:[1,0,0] op_sel_hi:[1,1,1]
	v_pk_fma_f32 v[94:95], v[40:41], v[102:103], v[94:95] op_sel:[1,0,0] op_sel_hi:[1,1,1]
	v_pk_fma_f32 v[96:97], v[40:41], v[104:105], v[96:97] op_sel:[1,0,0] op_sel_hi:[1,1,1]
	ds_write_b128 v3, v[66:69]
	ds_write_b128 v3, v[70:73] offset:16
	ds_write_b128 v3, v[74:77] offset:32
	ds_write_b128 v3, v[78:81] offset:48
	ds_write_b128 v3, v[82:85] offset:64
	ds_write_b128 v3, v[86:89] offset:80
	ds_write_b128 v3, v[90:93] offset:96
	ds_write_b128 v3, v[94:97] offset:112
	s_waitcnt lgkmcnt(0)
	ds_read_b128 v[66:69], v4
	ds_read_b128 v[70:73], v4 offset:1024
	ds_read_b128 v[74:77], v4 offset:2048
	ds_read_b128 v[78:81], v4 offset:3072
	ds_read_b128 v[82:85], v4 offset:4096
	ds_read_b128 v[86:89], v4 offset:5120
	ds_read_b128 v[90:93], v4 offset:6144
	ds_read_b128 v[94:97], v4 offset:7168
	s_waitcnt lgkmcnt(6)
	v_pk_add_f32 v[66:67], v[66:67], v[70:71]
	v_pk_add_f32 v[68:69], v[68:69], v[72:73]
	s_waitcnt lgkmcnt(5)
	v_pk_add_f32 v[66:67], v[66:67], v[74:75]
	v_pk_add_f32 v[68:69], v[68:69], v[76:77]
	s_waitcnt lgkmcnt(4)
	v_pk_add_f32 v[66:67], v[66:67], v[78:79]
	v_pk_add_f32 v[68:69], v[68:69], v[80:81]
	s_waitcnt lgkmcnt(3)
	v_pk_add_f32 v[66:67], v[66:67], v[82:83]
	v_pk_add_f32 v[68:69], v[68:69], v[84:85]
	s_waitcnt lgkmcnt(2)
	v_pk_add_f32 v[66:67], v[66:67], v[86:87]
	v_pk_add_f32 v[68:69], v[68:69], v[88:89]
	s_waitcnt lgkmcnt(1)
	v_pk_add_f32 v[66:67], v[66:67], v[90:91]
	v_pk_add_f32 v[68:69], v[68:69], v[92:93]
	s_waitcnt lgkmcnt(0)
	v_pk_add_f32 v[66:67], v[66:67], v[94:95]
	v_pk_add_f32 v[68:69], v[68:69], v[96:97]
	v_pk_add_f32 v[58:59], v[58:59], v[66:67]
	v_pk_add_f32 v[60:61], v[60:61], v[68:69]
	global_store_dwordx4 v0, v[58:61], s[44:45]
	s_mov_b32 s36, s51
	s_cmp_lt_u32 s36, s38
	s_cbranch_scc0 .Lmy_pv1_done
; __device__ __forceinline__ void phase_peer_v(const Params& p, int layer, int xs, int wid0, int wstride, bool last, char* smraw) {
;     ...
;   auto half_fma = [&](const u32x4 (&q)[8], const f32x4& c0, const f32x4& c1) {
; #pragma unroll
;     for (int i = 0; i < 8; ++i) {
;       const float ci = i < 4 ? c0[i & 3] : c1[i & 3];
; #pragma unroll
;       for (int m = 0; m < 4; ++m) {
;         unsigned dw = q[i][m];
;         asm volatile("" : "+v"(dw) : "v"(acc[(8 * m + 31) & 31]));
;         const f32x2 e0 = __builtin_amdgcn_cvt_scalef32_pk_f32_fp4(dw, 1.0f, 0), e1 = __builtin_amdgcn_cvt_scalef32_pk_f32_fp4(dw, 1.0f, 1);
;         const f32x2 e2 = __builtin_amdgcn_cvt_scalef32_pk_f32_fp4(dw, 1.0f, 2), e3 = __builtin_amdgcn_cvt_scalef32_pk_f32_fp4(dw, 1.0f, 3);
;         acc[8 * m + 0] += ci * e0[0]; acc[8 * m + 1] += ci * e0[1]; acc[8 * m + 2] += ci * e1[0]; acc[8 * m + 3] += ci * e1[1];
;         acc[8 * m + 4] += ci * e2[0]; acc[8 * m + 5] += ci * e2[1]; acc[8 * m + 6] += ci * e3[0]; acc[8 * m + 7] += ci * e3[1];
;       }
;     }
;   };
;   int tt = wid;
;   if (tt < TH) load_idx(tt);
;   while (tt < TH) {
;     const int tn = tt + wstride;
;     const int t = 2 * tt + par;
; #pragma unroll
;     for (int i = 0; i < 8; ++i) qA[i] = *(const u32x4*)(Vq + (ni[i >> 2][i & 3] * 128u + joff));
;     float* hq = hrow(p, t) + sl * 256 + 4 * l;
;     f32x4 hv = *(const f32x4*)hq;
;     const f32x4 c0 = nc[0], c1 = nc[1], c2 = nc[2], c3 = nc[3];
; #pragma unroll
;     for (int m = 0; m < 32; ++m) acc[m] = 0.f;
;     half_fma(qA, c0, c1);
; #pragma unroll
;     for (int i = 0; i < 8; ++i) qA[i] = *(const u32x4*)(Vq + (ni[2 + (i >> 2)][i & 3] * 128u + joff));
;     if (tn < TH) load_idx(tn);
.Lmy_pv1_bodyB:
	s_waitcnt vmcnt(1)
	s_add_u32 s51, s36, s33
	s_cmp_ge_u32 s51, s38
	s_cbranch_scc1 .Lmy_pv1_noissueB
	v_lshl_add_u32 v6, v10, 7, v1
	global_load_dwordx4 v[106:109], v6, s[40:41]
	v_lshl_add_u32 v7, v11, 7, v1
	global_load_dwordx4 v[110:113], v7, s[40:41]
	v_lshl_add_u32 v6, v12, 7, v1
	global_load_dwordx4 v[114:117], v6, s[40:41]
	v_lshl_add_u32 v7, v13, 7, v1
	global_load_dwordx4 v[118:121], v7, s[40:41]
	v_lshl_add_u32 v6, v14, 7, v1
	global_load_dwordx4 v[122:125], v6, s[40:41]
	v_lshl_add_u32 v7, v15, 7, v1
	global_load_dwordx4 v[126:129], v7, s[40:41]
	v_lshl_add_u32 v6, v16, 7, v1
	global_load_dwordx4 v[130:133], v6, s[40:41]
	v_lshl_add_u32 v7, v17, 7, v1
	global_load_dwordx4 v[134:137], v7, s[40:41]
	v_lshl_add_u32 v6, v18, 7, v1
	global_load_dwordx4 v[138:141], v6, s[40:41]
	v_lshl_add_u32 v7, v19, 7, v1
	global_load_dwordx4 v[142:145], v7, s[40:41]
	v_lshl_add_u32 v6, v20, 7, v1
	global_load_dwordx4 v[146:149], v6, s[40:41]
	v_lshl_add_u32 v7, v21, 7, v1
	global_load_dwordx4 v[150:153], v7, s[40:41]
	v_lshl_add_u32 v6, v22, 7, v1
	global_load_dwordx4 v[154:157], v6, s[40:41]
	v_lshl_add_u32 v7, v23, 7, v1
	global_load_dwordx4 v[158:161], v7, s[40:41]
	v_lshl_add_u32 v6, v24, 7, v1
	global_load_dwordx4 v[162:165], v6, s[40:41]
	v_lshl_add_u32 v7, v25, 7, v1
	global_load_dwordx4 v[166:169], v7, s[40:41]
	s_lshl_b32 s0, s51, 1
	s_add_u32 s0, s0, s28
	s_mul_hi_u32 s1, s0, s49
	s_mul_i32 s3, s1, 0x2010
	s_sub_u32 s3, s0, s3
	s_lshl_b32 s6, s1, 13
	s_add_u32 s6, s6, s3
	s_lshl_b32 s7, s1, 4
	s_add_u32 s7, s7, s3
	s_cmp_lt_u32 s3, 16
	s_cselect_b32 s6, s7, s6
	s_cselect_b32 s7, s12, s10
	s_cselect_b32 s8, s13, s11
	s_lshl_b32 s6, s6, 12
	s_add_u32 s6, s6, s39
	s_add_u32 s44, s7, s6
	s_addc_u32 s45, s8, 0
	global_load_dwordx4 v[58:61], v0, s[44:45]
	s_lshl_b32 s0, s51, 10
	v_add_u32_e32 v8, s0, v2
	global_load_dwordx4 v[26:29], v8, s[42:43]
	global_load_dwordx4 v[30:33], v8, s[42:43] offset:16
	global_load_dwordx4 v[34:37], v8, s[42:43] offset:32
	global_load_dwordx4 v[38:41], v8, s[42:43] offset:48
	s_add_u32 s9, s51, s33
	s_cmp_ge_u32 s9, s38
	s_cbranch_scc1 .Lmy_pv1_noissueB
	s_lshl_b32 s0, s9, 10
	v_add_u32_e32 v9, s0, v2
	global_load_dwordx4 v[10:13], v9, s[52:53]
	global_load_dwordx4 v[14:17], v9, s[52:53] offset:16
	global_load_dwordx4 v[18:21], v9, s[52:53] offset:32
	global_load_dwordx4 v[22:25], v9, s[52:53] offset:48
.Lmy_pv1_noissueB:
	v_cvt_scalef32_pk_f32_fp4 v[98:99], v170, 1.0
	v_cvt_scalef32_pk_f32_fp4 v[100:101], v170, 1.0 op_sel:[1,0,0]
	v_cvt_scalef32_pk_f32_fp4 v[102:103], v170, 1.0 op_sel:[0,1,0]
	v_cvt_scalef32_pk_f32_fp4 v[104:105], v170, 1.0 op_sel:[1,1,0]
	v_pk_fma_f32 v[66:67], v[42:43], v[98:99], 0 op_sel_hi:[0,1,0]
	v_pk_fma_f32 v[68:69], v[42:43], v[100:101], 0 op_sel_hi:[0,1,0]
	v_pk_fma_f32 v[70:71], v[42:43], v[102:103], 0 op_sel_hi:[0,1,0]
	v_pk_fma_f32 v[72:73], v[42:43], v[104:105], 0 op_sel_hi:[0,1,0]
	v_cvt_scalef32_pk_f32_fp4 v[98:99], v171, 1.0
	v_cvt_scalef32_pk_f32_fp4 v[100:101], v171, 1.0 op_sel:[1,0,0]
	v_cvt_scalef32_pk_f32_fp4 v[102:103], v171, 1.0 op_sel:[0,1,0]
	v_cvt_scalef32_pk_f32_fp4 v[104:105], v171, 1.0 op_sel:[1,1,0]
	v_pk_fma_f32 v[74:75], v[42:43], v[98:99], 0 op_sel_hi:[0,1,0]
	v_pk_fma_f32 v[76:77], v[42:43], v[100:101], 0 op_sel_hi:[0,1,0]
	v_pk_fma_f32 v[78:79], v[42:43], v[102:103], 0 op_sel_hi:[0,1,0]
	v_pk_fma_f32 v[80:81], v[42:43], v[104:105], 0 op_sel_hi:[0,1,0]
	v_cvt_scalef32_pk_f32_fp4 v[98:99], v172, 1.0
	v_cvt_scalef32_pk_f32_fp4 v[100:101], v172, 1.0 op_sel:[1,0,0]
	v_cvt_scalef32_pk_f32_fp4 v[102:103], v172, 1.0 op_sel:[0,1,0]
	v_cvt_scalef32_pk_f32_fp4 v[104:105], v172, 1.0 op_sel:[1,1,0]
	v_pk_fma_f32 v[82:83], v[42:43], v[98:99], 0 op_sel_hi:[0,1,0]
	v_pk_fma_f32 v[84:85], v[42:43], v[100:101], 0 op_sel_hi:[0,1,0]
	v_pk_fma_f32 v[86:87], v[42:43], v[102:103], 0 op_sel_hi:[0,1,0]
	v_pk_fma_f32 v[88:89], v[42:43], v[104:105], 0 op_sel_hi:[0,1,0]
	v_cvt_scalef32_pk_f32_fp4 v[98:99], v173, 1.0
	v_cvt_scalef32_pk_f32_fp4 v[100:101], v173, 1.0 op_sel:[1,0,0]
	v_cvt_scalef32_pk_f32_fp4 v[102:103], v173, 1.0 op_sel:[0,1,0]
	v_cvt_scalef32_pk_f32_fp4 v[104:105], v173, 1.0 op_sel:[1,1,0]
	v_pk_fma_f32 v[90:91], v[42:43], v[98:99], 0 op_sel_hi:[0,1,0]
	v_pk_fma_f32 v[92:93], v[42:43], v[100:101], 0 op_sel_hi:[0,1,0]
	v_pk_fma_f32 v[94:95], v[42:43], v[102:103], 0 op_sel_hi:[0,1,0]
	v_pk_fma_f32 v[96:97], v[42:43], v[104:105], 0 op_sel_hi:[0,1,0]
	v_cvt_scalef32_pk_f32_fp4 v[98:99], v174, 1.0
	v_cvt_scalef32_pk_f32_fp4 v[100:101], v174, 1.0 op_sel:[1,0,0]
	v_cvt_scalef32_pk_f32_fp4 v[102:103], v174, 1.0 op_sel:[0,1,0]
	v_cvt_scalef32_pk_f32_fp4 v[104:105], v174, 1.0 op_sel:[1,1,0]
	v_pk_fma_f32 v[66:67], v[42:43], v[98:99], v[66:67] op_sel:[1,0,0] op_sel_hi:[1,1,1]
	v_pk_fma_f32 v[68:69], v[42:43], v[100:101], v[68:69] op_sel:[1,0,0] op_sel_hi:[1,1,1]
	v_pk_fma_f32 v[70:71], v[42:43], v[102:103], v[70:71] op_sel:[1,0,0] op_sel_hi:[1,1,1]
	v_pk_fma_f32 v[72:73], v[42:43], v[104:105], v[72:73] op_sel:[1,0,0] op_sel_hi:[1,1,1]
	v_cvt_scalef32_pk_f32_fp4 v[98:99], v175, 1.0
	v_cvt_scalef32_pk_f32_fp4 v[100:101], v175, 1.0 op_sel:[1,0,0]
	v_cvt_scalef32_pk_f32_fp4 v[102:103], v175, 1.0 op_sel:[0,1,0]
	v_cvt_scalef32_pk_f32_fp4 v[104:105], v175, 1.0 op_sel:[1,1,0]
	v_pk_fma_f32 v[74:75], v[42:43], v[98:99], v[74:75] op_sel:[1,0,0] op_sel_hi:[1,1,1]
	v_pk_fma_f32 v[76:77], v[42:43], v[100:101], v[76:77] op_sel:[1,0,0] op_sel_hi:[1,1,1]
	v_pk_fma_f32 v[78:79], v[42:43], v[102:103], v[78:79] op_sel:[1,0,0] op_sel_hi:[1,1,1]
	v_pk_fma_f32 v[80:81], v[42:43], v[104:105], v[80:81] op_sel:[1,0,0] op_sel_hi:[1,1,1]
	v_cvt_scalef32_pk_f32_fp4 v[98:99], v176, 1.0
; __device__ __forceinline__ void phase_peer_v(const Params& p, int layer, int xs, int wid0, int wstride, bool last, char* smraw) {
;     ...
;   auto half_fma = [&](const u32x4 (&q)[8], const f32x4& c0, const f32x4& c1) {
; #pragma unroll
;     for (int i = 0; i < 8; ++i) {
;       const float ci = i < 4 ? c0[i & 3] : c1[i & 3];
; #pragma unroll
;       for (int m = 0; m < 4; ++m) {
;         unsigned dw = q[i][m];
;         asm volatile("" : "+v"(dw) : "v"(acc[(8 * m + 31) & 31]));
;         const f32x2 e0 = __builtin_amdgcn_cvt_scalef32_pk_f32_fp4(dw, 1.0f, 0), e1 = __builtin_amdgcn_cvt_scalef32_pk_f32_fp4(dw, 1.0f, 1);
;         const f32x2 e2 = __builtin_amdgcn_cvt_scalef32_pk_f32_fp4(dw, 1.0f, 2), e3 = __builtin_amdgcn_cvt_scalef32_pk_f32_fp4(dw, 1.0f, 3);
;         acc[8 * m + 0] += ci * e0[0]; acc[8 * m + 1] += ci * e0[1]; acc[8 * m + 2] += ci * e1[0]; acc[8 * m + 3] += ci * e1[1];
;         acc[8 * m + 4] += ci * e2[0]; acc[8 * m + 5] += ci * e2[1]; acc[8 * m + 6] += ci * e3[0]; acc[8 * m + 7] += ci * e3[1];
;       }
;     }
;   };
	v_cvt_scalef32_pk_f32_fp4 v[100:101], v176, 1.0 op_sel:[1,0,0]
	v_cvt_scalef32_pk_f32_fp4 v[102:103], v176, 1.0 op_sel:[0,1,0]
	v_cvt_scalef32_pk_f32_fp4 v[104:105], v176, 1.0 op_sel:[1,1,0]
	v_pk_fma_f32 v[82:83], v[42:43], v[98:99], v[82:83] op_sel:[1,0,0] op_sel_hi:[1,1,1]
	v_pk_fma_f32 v[84:85], v[42:43], v[100:101], v[84:85] op_sel:[1,0,0] op_sel_hi:[1,1,1]
	v_pk_fma_f32 v[86:87], v[42:43], v[102:103], v[86:87] op_sel:[1,0,0] op_sel_hi:[1,1,1]
	v_pk_fma_f32 v[88:89], v[42:43], v[104:105], v[88:89] op_sel:[1,0,0] op_sel_hi:[1,1,1]
	v_cvt_scalef32_pk_f32_fp4 v[98:99], v177, 1.0
	v_cvt_scalef32_pk_f32_fp4 v[100:101], v177, 1.0 op_sel:[1,0,0]
	v_cvt_scalef32_pk_f32_fp4 v[102:103], v177, 1.0 op_sel:[0,1,0]
	v_cvt_scalef32_pk_f32_fp4 v[104:105], v177, 1.0 op_sel:[1,1,0]
	v_pk_fma_f32 v[90:91], v[42:43], v[98:99], v[90:91] op_sel:[1,0,0] op_sel_hi:[1,1,1]
	v_pk_fma_f32 v[92:93], v[42:43], v[100:101], v[92:93] op_sel:[1,0,0] op_sel_hi:[1,1,1]
	v_pk_fma_f32 v[94:95], v[42:43], v[102:103], v[94:95] op_sel:[1,0,0] op_sel_hi:[1,1,1]
	v_pk_fma_f32 v[96:97], v[42:43], v[104:105], v[96:97] op_sel:[1,0,0] op_sel_hi:[1,1,1]
	v_cvt_scalef32_pk_f32_fp4 v[98:99], v178, 1.0
	v_cvt_scalef32_pk_f32_fp4 v[100:101], v178, 1.0 op_sel:[1,0,0]
	v_cvt_scalef32_pk_f32_fp4 v[102:103], v178, 1.0 op_sel:[0,1,0]
	v_cvt_scalef32_pk_f32_fp4 v[104:105], v178, 1.0 op_sel:[1,1,0]
	v_pk_fma_f32 v[66:67], v[44:45], v[98:99], v[66:67] op_sel_hi:[0,1,1]
	v_pk_fma_f32 v[68:69], v[44:45], v[100:101], v[68:69] op_sel_hi:[0,1,1]
	v_pk_fma_f32 v[70:71], v[44:45], v[102:103], v[70:71] op_sel_hi:[0,1,1]
	v_pk_fma_f32 v[72:73], v[44:45], v[104:105], v[72:73] op_sel_hi:[0,1,1]
	v_cvt_scalef32_pk_f32_fp4 v[98:99], v179, 1.0
	v_cvt_scalef32_pk_f32_fp4 v[100:101], v179, 1.0 op_sel:[1,0,0]
	v_cvt_scalef32_pk_f32_fp4 v[102:103], v179, 1.0 op_sel:[0,1,0]
	v_cvt_scalef32_pk_f32_fp4 v[104:105], v179, 1.0 op_sel:[1,1,0]
	v_pk_fma_f32 v[74:75], v[44:45], v[98:99], v[74:75] op_sel_hi:[0,1,1]
	v_pk_fma_f32 v[76:77], v[44:45], v[100:101], v[76:77] op_sel_hi:[0,1,1]
	v_pk_fma_f32 v[78:79], v[44:45], v[102:103], v[78:79] op_sel_hi:[0,1,1]
	v_pk_fma_f32 v[80:81], v[44:45], v[104:105], v[80:81] op_sel_hi:[0,1,1]
	v_cvt_scalef32_pk_f32_fp4 v[98:99], v180, 1.0
	v_cvt_scalef32_pk_f32_fp4 v[100:101], v180, 1.0 op_sel:[1,0,0]
	v_cvt_scalef32_pk_f32_fp4 v[102:103], v180, 1.0 op_sel:[0,1,0]
	v_cvt_scalef32_pk_f32_fp4 v[104:105], v180, 1.0 op_sel:[1,1,0]
	v_pk_fma_f32 v[82:83], v[44:45], v[98:99], v[82:83] op_sel_hi:[0,1,1]
	v_pk_fma_f32 v[84:85], v[44:45], v[100:101], v[84:85] op_sel_hi:[0,1,1]
	v_pk_fma_f32 v[86:87], v[44:45], v[102:103], v[86:87] op_sel_hi:[0,1,1]
	v_pk_fma_f32 v[88:89], v[44:45], v[104:105], v[88:89] op_sel_hi:[0,1,1]
	v_cvt_scalef32_pk_f32_fp4 v[98:99], v181, 1.0
	v_cvt_scalef32_pk_f32_fp4 v[100:101], v181, 1.0 op_sel:[1,0,0]
	v_cvt_scalef32_pk_f32_fp4 v[102:103], v181, 1.0 op_sel:[0,1,0]
	v_cvt_scalef32_pk_f32_fp4 v[104:105], v181, 1.0 op_sel:[1,1,0]
	v_pk_fma_f32 v[90:91], v[44:45], v[98:99], v[90:91] op_sel_hi:[0,1,1]
	v_pk_fma_f32 v[92:93], v[44:45], v[100:101], v[92:93] op_sel_hi:[0,1,1]
	v_pk_fma_f32 v[94:95], v[44:45], v[102:103], v[94:95] op_sel_hi:[0,1,1]
	v_pk_fma_f32 v[96:97], v[44:45], v[104:105], v[96:97] op_sel_hi:[0,1,1]
	v_cvt_scalef32_pk_f32_fp4 v[98:99], v182, 1.0
	v_cvt_scalef32_pk_f32_fp4 v[100:101], v182, 1.0 op_sel:[1,0,0]
	v_cvt_scalef32_pk_f32_fp4 v[102:103], v182, 1.0 op_sel:[0,1,0]
	v_cvt_scalef32_pk_f32_fp4 v[104:105], v182, 1.0 op_sel:[1,1,0]
	v_pk_fma_f32 v[66:67], v[44:45], v[98:99], v[66:67] op_sel:[1,0,0] op_sel_hi:[1,1,1]
	v_pk_fma_f32 v[68:69], v[44:45], v[100:101], v[68:69] op_sel:[1,0,0] op_sel_hi:[1,1,1]
	v_pk_fma_f32 v[70:71], v[44:45], v[102:103], v[70:71] op_sel:[1,0,0] op_sel_hi:[1,1,1]
	v_pk_fma_f32 v[72:73], v[44:45], v[104:105], v[72:73] op_sel:[1,0,0] op_sel_hi:[1,1,1]
	v_cvt_scalef32_pk_f32_fp4 v[98:99], v183, 1.0
	v_cvt_scalef32_pk_f32_fp4 v[100:101], v183, 1.0 op_sel:[1,0,0]
	v_cvt_scalef32_pk_f32_fp4 v[102:103], v183, 1.0 op_sel:[0,1,0]
	v_cvt_scalef32_pk_f32_fp4 v[104:105], v183, 1.0 op_sel:[1,1,0]
	v_pk_fma_f32 v[74:75], v[44:45], v[98:99], v[74:75] op_sel:[1,0,0] op_sel_hi:[1,1,1]
	v_pk_fma_f32 v[76:77], v[44:45], v[100:101], v[76:77] op_sel:[1,0,0] op_sel_hi:[1,1,1]
	v_pk_fma_f32 v[78:79], v[44:45], v[102:103], v[78:79] op_sel:[1,0,0] op_sel_hi:[1,1,1]
	v_pk_fma_f32 v[80:81], v[44:45], v[104:105], v[80:81] op_sel:[1,0,0] op_sel_hi:[1,1,1]
	v_cvt_scalef32_pk_f32_fp4 v[98:99], v184, 1.0
	v_cvt_scalef32_pk_f32_fp4 v[100:101], v184, 1.0 op_sel:[1,0,0]
	v_cvt_scalef32_pk_f32_fp4 v[102:103], v184, 1.0 op_sel:[0,1,0]
	v_cvt_scalef32_pk_f32_fp4 v[104:105], v184, 1.0 op_sel:[1,1,0]
	v_pk_fma_f32 v[82:83], v[44:45], v[98:99], v[82:83] op_sel:[1,0,0] op_sel_hi:[1,1,1]
	v_pk_fma_f32 v[84:85], v[44:45], v[100:101], v[84:85] op_sel:[1,0,0] op_sel_hi:[1,1,1]
	v_pk_fma_f32 v[86:87], v[44:45], v[102:103], v[86:87] op_sel:[1,0,0] op_sel_hi:[1,1,1]
	v_pk_fma_f32 v[88:89], v[44:45], v[104:105], v[88:89] op_sel:[1,0,0] op_sel_hi:[1,1,1]
	v_cvt_scalef32_pk_f32_fp4 v[98:99], v185, 1.0
	v_cvt_scalef32_pk_f32_fp4 v[100:101], v185, 1.0 op_sel:[1,0,0]
	v_cvt_scalef32_pk_f32_fp4 v[102:103], v185, 1.0 op_sel:[0,1,0]
	v_cvt_scalef32_pk_f32_fp4 v[104:105], v185, 1.0 op_sel:[1,1,0]
	v_pk_fma_f32 v[90:91], v[44:45], v[98:99], v[90:91] op_sel:[1,0,0] op_sel_hi:[1,1,1]
	v_pk_fma_f32 v[92:93], v[44:45], v[100:101], v[92:93] op_sel:[1,0,0] op_sel_hi:[1,1,1]
	v_pk_fma_f32 v[94:95], v[44:45], v[102:103], v[94:95] op_sel:[1,0,0] op_sel_hi:[1,1,1]
	v_pk_fma_f32 v[96:97], v[44:45], v[104:105], v[96:97] op_sel:[1,0,0] op_sel_hi:[1,1,1]
	v_cvt_scalef32_pk_f32_fp4 v[98:99], v192, 1.0
; __device__ __forceinline__ void phase_peer_v(const Params& p, int layer, int xs, int wid0, int wstride, bool last, char* smraw) {
;     ...
;   auto half_fma = [&](const u32x4 (&q)[8], const f32x4& c0, const f32x4& c1) {
; #pragma unroll
;     for (int i = 0; i < 8; ++i) {
;       const float ci = i < 4 ? c0[i & 3] : c1[i & 3];
; #pragma unroll
;       for (int m = 0; m < 4; ++m) {
;         unsigned dw = q[i][m];
;         asm volatile("" : "+v"(dw) : "v"(acc[(8 * m + 31) & 31]));
;         const f32x2 e0 = __builtin_amdgcn_cvt_scalef32_pk_f32_fp4(dw, 1.0f, 0), e1 = __builtin_amdgcn_cvt_scalef32_pk_f32_fp4(dw, 1.0f, 1);
;         const f32x2 e2 = __builtin_amdgcn_cvt_scalef32_pk_f32_fp4(dw, 1.0f, 2), e3 = __builtin_amdgcn_cvt_scalef32_pk_f32_fp4(dw, 1.0f, 3);
;         acc[8 * m + 0] += ci * e0[0]; acc[8 * m + 1] += ci * e0[1]; acc[8 * m + 2] += ci * e1[0]; acc[8 * m + 3] += ci * e1[1];
;         acc[8 * m + 4] += ci * e2[0]; acc[8 * m + 5] += ci * e2[1]; acc[8 * m + 6] += ci * e3[0]; acc[8 * m + 7] += ci * e3[1];
;       }
;     }
;   };
	v_cvt_scalef32_pk_f32_fp4 v[100:101], v192, 1.0 op_sel:[1,0,0]
	v_cvt_scalef32_pk_f32_fp4 v[102:103], v192, 1.0 op_sel:[0,1,0]
	v_cvt_scalef32_pk_f32_fp4 v[104:105], v192, 1.0 op_sel:[1,1,0]
	v_pk_fma_f32 v[66:67], v[46:47], v[98:99], v[66:67] op_sel_hi:[0,1,1]
	v_pk_fma_f32 v[68:69], v[46:47], v[100:101], v[68:69] op_sel_hi:[0,1,1]
	v_pk_fma_f32 v[70:71], v[46:47], v[102:103], v[70:71] op_sel_hi:[0,1,1]
	v_pk_fma_f32 v[72:73], v[46:47], v[104:105], v[72:73] op_sel_hi:[0,1,1]
	v_cvt_scalef32_pk_f32_fp4 v[98:99], v193, 1.0
	v_cvt_scalef32_pk_f32_fp4 v[100:101], v193, 1.0 op_sel:[1,0,0]
	v_cvt_scalef32_pk_f32_fp4 v[102:103], v193, 1.0 op_sel:[0,1,0]
	v_cvt_scalef32_pk_f32_fp4 v[104:105], v193, 1.0 op_sel:[1,1,0]
	v_pk_fma_f32 v[74:75], v[46:47], v[98:99], v[74:75] op_sel_hi:[0,1,1]
	v_pk_fma_f32 v[76:77], v[46:47], v[100:101], v[76:77] op_sel_hi:[0,1,1]
	v_pk_fma_f32 v[78:79], v[46:47], v[102:103], v[78:79] op_sel_hi:[0,1,1]
	v_pk_fma_f32 v[80:81], v[46:47], v[104:105], v[80:81] op_sel_hi:[0,1,1]
	v_cvt_scalef32_pk_f32_fp4 v[98:99], v194, 1.0
	v_cvt_scalef32_pk_f32_fp4 v[100:101], v194, 1.0 op_sel:[1,0,0]
	v_cvt_scalef32_pk_f32_fp4 v[102:103], v194, 1.0 op_sel:[0,1,0]
	v_cvt_scalef32_pk_f32_fp4 v[104:105], v194, 1.0 op_sel:[1,1,0]
	v_pk_fma_f32 v[82:83], v[46:47], v[98:99], v[82:83] op_sel_hi:[0,1,1]
	v_pk_fma_f32 v[84:85], v[46:47], v[100:101], v[84:85] op_sel_hi:[0,1,1]
	v_pk_fma_f32 v[86:87], v[46:47], v[102:103], v[86:87] op_sel_hi:[0,1,1]
	v_pk_fma_f32 v[88:89], v[46:47], v[104:105], v[88:89] op_sel_hi:[0,1,1]
	v_cvt_scalef32_pk_f32_fp4 v[98:99], v195, 1.0
	v_cvt_scalef32_pk_f32_fp4 v[100:101], v195, 1.0 op_sel:[1,0,0]
	v_cvt_scalef32_pk_f32_fp4 v[102:103], v195, 1.0 op_sel:[0,1,0]
	v_cvt_scalef32_pk_f32_fp4 v[104:105], v195, 1.0 op_sel:[1,1,0]
	v_pk_fma_f32 v[90:91], v[46:47], v[98:99], v[90:91] op_sel_hi:[0,1,1]
	v_pk_fma_f32 v[92:93], v[46:47], v[100:101], v[92:93] op_sel_hi:[0,1,1]
	v_pk_fma_f32 v[94:95], v[46:47], v[102:103], v[94:95] op_sel_hi:[0,1,1]
	v_pk_fma_f32 v[96:97], v[46:47], v[104:105], v[96:97] op_sel_hi:[0,1,1]
	v_cvt_scalef32_pk_f32_fp4 v[98:99], v196, 1.0
	v_cvt_scalef32_pk_f32_fp4 v[100:101], v196, 1.0 op_sel:[1,0,0]
	v_cvt_scalef32_pk_f32_fp4 v[102:103], v196, 1.0 op_sel:[0,1,0]
	v_cvt_scalef32_pk_f32_fp4 v[104:105], v196, 1.0 op_sel:[1,1,0]
	v_pk_fma_f32 v[66:67], v[46:47], v[98:99], v[66:67] op_sel:[1,0,0] op_sel_hi:[1,1,1]
	v_pk_fma_f32 v[68:69], v[46:47], v[100:101], v[68:69] op_sel:[1,0,0] op_sel_hi:[1,1,1]
	v_pk_fma_f32 v[70:71], v[46:47], v[102:103], v[70:71] op_sel:[1,0,0] op_sel_hi:[1,1,1]
	v_pk_fma_f32 v[72:73], v[46:47], v[104:105], v[72:73] op_sel:[1,0,0] op_sel_hi:[1,1,1]
	v_cvt_scalef32_pk_f32_fp4 v[98:99], v197, 1.0
	v_cvt_scalef32_pk_f32_fp4 v[100:101], v197, 1.0 op_sel:[1,0,0]
	v_cvt_scalef32_pk_f32_fp4 v[102:103], v197, 1.0 op_sel:[0,1,0]
	v_cvt_scalef32_pk_f32_fp4 v[104:105], v197, 1.0 op_sel:[1,1,0]
	v_pk_fma_f32 v[74:75], v[46:47], v[98:99], v[74:75] op_sel:[1,0,0] op_sel_hi:[1,1,1]
	v_pk_fma_f32 v[76:77], v[46:47], v[100:101], v[76:77] op_sel:[1,0,0] op_sel_hi:[1,1,1]
	v_pk_fma_f32 v[78:79], v[46:47], v[102:103], v[78:79] op_sel:[1,0,0] op_sel_hi:[1,1,1]
	v_pk_fma_f32 v[80:81], v[46:47], v[104:105], v[80:81] op_sel:[1,0,0] op_sel_hi:[1,1,1]
	v_cvt_scalef32_pk_f32_fp4 v[98:99], v198, 1.0
	v_cvt_scalef32_pk_f32_fp4 v[100:101], v198, 1.0 op_sel:[1,0,0]
	v_cvt_scalef32_pk_f32_fp4 v[102:103], v198, 1.0 op_sel:[0,1,0]
	v_cvt_scalef32_pk_f32_fp4 v[104:105], v198, 1.0 op_sel:[1,1,0]
	v_pk_fma_f32 v[82:83], v[46:47], v[98:99], v[82:83] op_sel:[1,0,0] op_sel_hi:[1,1,1]
	v_pk_fma_f32 v[84:85], v[46:47], v[100:101], v[84:85] op_sel:[1,0,0] op_sel_hi:[1,1,1]
	v_pk_fma_f32 v[86:87], v[46:47], v[102:103], v[86:87] op_sel:[1,0,0] op_sel_hi:[1,1,1]
	v_pk_fma_f32 v[88:89], v[46:47], v[104:105], v[88:89] op_sel:[1,0,0] op_sel_hi:[1,1,1]
	v_cvt_scalef32_pk_f32_fp4 v[98:99], v199, 1.0
	v_cvt_scalef32_pk_f32_fp4 v[100:101], v199, 1.0 op_sel:[1,0,0]
	v_cvt_scalef32_pk_f32_fp4 v[102:103], v199, 1.0 op_sel:[0,1,0]
	v_cvt_scalef32_pk_f32_fp4 v[104:105], v199, 1.0 op_sel:[1,1,0]
	v_pk_fma_f32 v[90:91], v[46:47], v[98:99], v[90:91] op_sel:[1,0,0] op_sel_hi:[1,1,1]
	v_pk_fma_f32 v[92:93], v[46:47], v[100:101], v[92:93] op_sel:[1,0,0] op_sel_hi:[1,1,1]
	v_pk_fma_f32 v[94:95], v[46:47], v[102:103], v[94:95] op_sel:[1,0,0] op_sel_hi:[1,1,1]
	v_pk_fma_f32 v[96:97], v[46:47], v[104:105], v[96:97] op_sel:[1,0,0] op_sel_hi:[1,1,1]
	v_cvt_scalef32_pk_f32_fp4 v[98:99], v200, 1.0
	v_cvt_scalef32_pk_f32_fp4 v[100:101], v200, 1.0 op_sel:[1,0,0]
	v_cvt_scalef32_pk_f32_fp4 v[102:103], v200, 1.0 op_sel:[0,1,0]
	v_cvt_scalef32_pk_f32_fp4 v[104:105], v200, 1.0 op_sel:[1,1,0]
	v_pk_fma_f32 v[66:67], v[48:49], v[98:99], v[66:67] op_sel_hi:[0,1,1]
	v_pk_fma_f32 v[68:69], v[48:49], v[100:101], v[68:69] op_sel_hi:[0,1,1]
	v_pk_fma_f32 v[70:71], v[48:49], v[102:103], v[70:71] op_sel_hi:[0,1,1]
	v_pk_fma_f32 v[72:73], v[48:49], v[104:105], v[72:73] op_sel_hi:[0,1,1]
	v_cvt_scalef32_pk_f32_fp4 v[98:99], v201, 1.0
	v_cvt_scalef32_pk_f32_fp4 v[100:101], v201, 1.0 op_sel:[1,0,0]
	v_cvt_scalef32_pk_f32_fp4 v[102:103], v201, 1.0 op_sel:[0,1,0]
	v_cvt_scalef32_pk_f32_fp4 v[104:105], v201, 1.0 op_sel:[1,1,0]
	v_pk_fma_f32 v[74:75], v[48:49], v[98:99], v[74:75] op_sel_hi:[0,1,1]
	v_pk_fma_f32 v[76:77], v[48:49], v[100:101], v[76:77] op_sel_hi:[0,1,1]
	v_pk_fma_f32 v[78:79], v[48:49], v[102:103], v[78:79] op_sel_hi:[0,1,1]
	v_pk_fma_f32 v[80:81], v[48:49], v[104:105], v[80:81] op_sel_hi:[0,1,1]
	v_cvt_scalef32_pk_f32_fp4 v[98:99], v202, 1.0
	v_cvt_scalef32_pk_f32_fp4 v[100:101], v202, 1.0 op_sel:[1,0,0]
	v_cvt_scalef32_pk_f32_fp4 v[102:103], v202, 1.0 op_sel:[0,1,0]
; __device__ __forceinline__ void phase_peer_v(const Params& p, int layer, int xs, int wid0, int wstride, bool last, char* smraw) {
;     ...
;   auto half_fma = [&](const u32x4 (&q)[8], const f32x4& c0, const f32x4& c1) {
; #pragma unroll
;     for (int i = 0; i < 8; ++i) {
;       const float ci = i < 4 ? c0[i & 3] : c1[i & 3];
; #pragma unroll
;       for (int m = 0; m < 4; ++m) {
;         unsigned dw = q[i][m];
;         asm volatile("" : "+v"(dw) : "v"(acc[(8 * m + 31) & 31]));
;         const f32x2 e0 = __builtin_amdgcn_cvt_scalef32_pk_f32_fp4(dw, 1.0f, 0), e1 = __builtin_amdgcn_cvt_scalef32_pk_f32_fp4(dw, 1.0f, 1);
;         const f32x2 e2 = __builtin_amdgcn_cvt_scalef32_pk_f32_fp4(dw, 1.0f, 2), e3 = __builtin_amdgcn_cvt_scalef32_pk_f32_fp4(dw, 1.0f, 3);
;         acc[8 * m + 0] += ci * e0[0]; acc[8 * m + 1] += ci * e0[1]; acc[8 * m + 2] += ci * e1[0]; acc[8 * m + 3] += ci * e1[1];
;         acc[8 * m + 4] += ci * e2[0]; acc[8 * m + 5] += ci * e2[1]; acc[8 * m + 6] += ci * e3[0]; acc[8 * m + 7] += ci * e3[1];
;       }
;     }
;   };
	v_cvt_scalef32_pk_f32_fp4 v[104:105], v202, 1.0 op_sel:[1,1,0]
	v_pk_fma_f32 v[82:83], v[48:49], v[98:99], v[82:83] op_sel_hi:[0,1,1]
	v_pk_fma_f32 v[84:85], v[48:49], v[100:101], v[84:85] op_sel_hi:[0,1,1]
	v_pk_fma_f32 v[86:87], v[48:49], v[102:103], v[86:87] op_sel_hi:[0,1,1]
	v_pk_fma_f32 v[88:89], v[48:49], v[104:105], v[88:89] op_sel_hi:[0,1,1]
	v_cvt_scalef32_pk_f32_fp4 v[98:99], v203, 1.0
	v_cvt_scalef32_pk_f32_fp4 v[100:101], v203, 1.0 op_sel:[1,0,0]
	v_cvt_scalef32_pk_f32_fp4 v[102:103], v203, 1.0 op_sel:[0,1,0]
	v_cvt_scalef32_pk_f32_fp4 v[104:105], v203, 1.0 op_sel:[1,1,0]
	v_pk_fma_f32 v[90:91], v[48:49], v[98:99], v[90:91] op_sel_hi:[0,1,1]
	v_pk_fma_f32 v[92:93], v[48:49], v[100:101], v[92:93] op_sel_hi:[0,1,1]
	v_pk_fma_f32 v[94:95], v[48:49], v[102:103], v[94:95] op_sel_hi:[0,1,1]
	v_pk_fma_f32 v[96:97], v[48:49], v[104:105], v[96:97] op_sel_hi:[0,1,1]
	v_cvt_scalef32_pk_f32_fp4 v[98:99], v204, 1.0
	v_cvt_scalef32_pk_f32_fp4 v[100:101], v204, 1.0 op_sel:[1,0,0]
	v_cvt_scalef32_pk_f32_fp4 v[102:103], v204, 1.0 op_sel:[0,1,0]
	v_cvt_scalef32_pk_f32_fp4 v[104:105], v204, 1.0 op_sel:[1,1,0]
	v_pk_fma_f32 v[66:67], v[48:49], v[98:99], v[66:67] op_sel:[1,0,0] op_sel_hi:[1,1,1]
	v_pk_fma_f32 v[68:69], v[48:49], v[100:101], v[68:69] op_sel:[1,0,0] op_sel_hi:[1,1,1]
	v_pk_fma_f32 v[70:71], v[48:49], v[102:103], v[70:71] op_sel:[1,0,0] op_sel_hi:[1,1,1]
	v_pk_fma_f32 v[72:73], v[48:49], v[104:105], v[72:73] op_sel:[1,0,0] op_sel_hi:[1,1,1]
	v_cvt_scalef32_pk_f32_fp4 v[98:99], v205, 1.0
	v_cvt_scalef32_pk_f32_fp4 v[100:101], v205, 1.0 op_sel:[1,0,0]
	v_cvt_scalef32_pk_f32_fp4 v[102:103], v205, 1.0 op_sel:[0,1,0]
	v_cvt_scalef32_pk_f32_fp4 v[104:105], v205, 1.0 op_sel:[1,1,0]
	v_pk_fma_f32 v[74:75], v[48:49], v[98:99], v[74:75] op_sel:[1,0,0] op_sel_hi:[1,1,1]
	v_pk_fma_f32 v[76:77], v[48:49], v[100:101], v[76:77] op_sel:[1,0,0] op_sel_hi:[1,1,1]
	v_pk_fma_f32 v[78:79], v[48:49], v[102:103], v[78:79] op_sel:[1,0,0] op_sel_hi:[1,1,1]
	v_pk_fma_f32 v[80:81], v[48:49], v[104:105], v[80:81] op_sel:[1,0,0] op_sel_hi:[1,1,1]
	v_cvt_scalef32_pk_f32_fp4 v[98:99], v206, 1.0
	v_cvt_scalef32_pk_f32_fp4 v[100:101], v206, 1.0 op_sel:[1,0,0]
	v_cvt_scalef32_pk_f32_fp4 v[102:103], v206, 1.0 op_sel:[0,1,0]
	v_cvt_scalef32_pk_f32_fp4 v[104:105], v206, 1.0 op_sel:[1,1,0]
	v_pk_fma_f32 v[82:83], v[48:49], v[98:99], v[82:83] op_sel:[1,0,0] op_sel_hi:[1,1,1]
	v_pk_fma_f32 v[84:85], v[48:49], v[100:101], v[84:85] op_sel:[1,0,0] op_sel_hi:[1,1,1]
	v_pk_fma_f32 v[86:87], v[48:49], v[102:103], v[86:87] op_sel:[1,0,0] op_sel_hi:[1,1,1]
	v_pk_fma_f32 v[88:89], v[48:49], v[104:105], v[88:89] op_sel:[1,0,0] op_sel_hi:[1,1,1]
	v_cvt_scalef32_pk_f32_fp4 v[98:99], v207, 1.0
	v_cvt_scalef32_pk_f32_fp4 v[100:101], v207, 1.0 op_sel:[1,0,0]
	v_cvt_scalef32_pk_f32_fp4 v[102:103], v207, 1.0 op_sel:[0,1,0]
	v_cvt_scalef32_pk_f32_fp4 v[104:105], v207, 1.0 op_sel:[1,1,0]
	v_pk_fma_f32 v[90:91], v[48:49], v[98:99], v[90:91] op_sel:[1,0,0] op_sel_hi:[1,1,1]
	v_pk_fma_f32 v[92:93], v[48:49], v[100:101], v[92:93] op_sel:[1,0,0] op_sel_hi:[1,1,1]
	v_pk_fma_f32 v[94:95], v[48:49], v[102:103], v[94:95] op_sel:[1,0,0] op_sel_hi:[1,1,1]
	v_pk_fma_f32 v[96:97], v[48:49], v[104:105], v[96:97] op_sel:[1,0,0] op_sel_hi:[1,1,1]
	v_cvt_scalef32_pk_f32_fp4 v[98:99], v208, 1.0
	v_cvt_scalef32_pk_f32_fp4 v[100:101], v208, 1.0 op_sel:[1,0,0]
	v_cvt_scalef32_pk_f32_fp4 v[102:103], v208, 1.0 op_sel:[0,1,0]
	v_cvt_scalef32_pk_f32_fp4 v[104:105], v208, 1.0 op_sel:[1,1,0]
	v_pk_fma_f32 v[66:67], v[50:51], v[98:99], v[66:67] op_sel_hi:[0,1,1]
	v_pk_fma_f32 v[68:69], v[50:51], v[100:101], v[68:69] op_sel_hi:[0,1,1]
	v_pk_fma_f32 v[70:71], v[50:51], v[102:103], v[70:71] op_sel_hi:[0,1,1]
	v_pk_fma_f32 v[72:73], v[50:51], v[104:105], v[72:73] op_sel_hi:[0,1,1]
	v_cvt_scalef32_pk_f32_fp4 v[98:99], v209, 1.0
	v_cvt_scalef32_pk_f32_fp4 v[100:101], v209, 1.0 op_sel:[1,0,0]
	v_cvt_scalef32_pk_f32_fp4 v[102:103], v209, 1.0 op_sel:[0,1,0]
	v_cvt_scalef32_pk_f32_fp4 v[104:105], v209, 1.0 op_sel:[1,1,0]
	v_pk_fma_f32 v[74:75], v[50:51], v[98:99], v[74:75] op_sel_hi:[0,1,1]
	v_pk_fma_f32 v[76:77], v[50:51], v[100:101], v[76:77] op_sel_hi:[0,1,1]
	v_pk_fma_f32 v[78:79], v[50:51], v[102:103], v[78:79] op_sel_hi:[0,1,1]
	v_pk_fma_f32 v[80:81], v[50:51], v[104:105], v[80:81] op_sel_hi:[0,1,1]
	v_cvt_scalef32_pk_f32_fp4 v[98:99], v210, 1.0
	v_cvt_scalef32_pk_f32_fp4 v[100:101], v210, 1.0 op_sel:[1,0,0]
	v_cvt_scalef32_pk_f32_fp4 v[102:103], v210, 1.0 op_sel:[0,1,0]
	v_cvt_scalef32_pk_f32_fp4 v[104:105], v210, 1.0 op_sel:[1,1,0]
	v_pk_fma_f32 v[82:83], v[50:51], v[98:99], v[82:83] op_sel_hi:[0,1,1]
	v_pk_fma_f32 v[84:85], v[50:51], v[100:101], v[84:85] op_sel_hi:[0,1,1]
	v_pk_fma_f32 v[86:87], v[50:51], v[102:103], v[86:87] op_sel_hi:[0,1,1]
	v_pk_fma_f32 v[88:89], v[50:51], v[104:105], v[88:89] op_sel_hi:[0,1,1]
	v_cvt_scalef32_pk_f32_fp4 v[98:99], v211, 1.0
	v_cvt_scalef32_pk_f32_fp4 v[100:101], v211, 1.0 op_sel:[1,0,0]
	v_cvt_scalef32_pk_f32_fp4 v[102:103], v211, 1.0 op_sel:[0,1,0]
	v_cvt_scalef32_pk_f32_fp4 v[104:105], v211, 1.0 op_sel:[1,1,0]
	v_pk_fma_f32 v[90:91], v[50:51], v[98:99], v[90:91] op_sel_hi:[0,1,1]
	v_pk_fma_f32 v[92:93], v[50:51], v[100:101], v[92:93] op_sel_hi:[0,1,1]
	v_pk_fma_f32 v[94:95], v[50:51], v[102:103], v[94:95] op_sel_hi:[0,1,1]
	v_pk_fma_f32 v[96:97], v[50:51], v[104:105], v[96:97] op_sel_hi:[0,1,1]
	v_cvt_scalef32_pk_f32_fp4 v[98:99], v212, 1.0
	v_cvt_scalef32_pk_f32_fp4 v[100:101], v212, 1.0 op_sel:[1,0,0]
	v_cvt_scalef32_pk_f32_fp4 v[102:103], v212, 1.0 op_sel:[0,1,0]
	v_cvt_scalef32_pk_f32_fp4 v[104:105], v212, 1.0 op_sel:[1,1,0]
	v_pk_fma_f32 v[66:67], v[50:51], v[98:99], v[66:67] op_sel:[1,0,0] op_sel_hi:[1,1,1]
; __device__ __forceinline__ void phase_peer_v(const Params& p, int layer, int xs, int wid0, int wstride, bool last, char* smraw) {
;     ...
;   auto half_fma = [&](const u32x4 (&q)[8], const f32x4& c0, const f32x4& c1) {
; #pragma unroll
;     for (int i = 0; i < 8; ++i) {
;       const float ci = i < 4 ? c0[i & 3] : c1[i & 3];
; #pragma unroll
;       for (int m = 0; m < 4; ++m) {
;         unsigned dw = q[i][m];
;         asm volatile("" : "+v"(dw) : "v"(acc[(8 * m + 31) & 31]));
;         const f32x2 e0 = __builtin_amdgcn_cvt_scalef32_pk_f32_fp4(dw, 1.0f, 0), e1 = __builtin_amdgcn_cvt_scalef32_pk_f32_fp4(dw, 1.0f, 1);
;         const f32x2 e2 = __builtin_amdgcn_cvt_scalef32_pk_f32_fp4(dw, 1.0f, 2), e3 = __builtin_amdgcn_cvt_scalef32_pk_f32_fp4(dw, 1.0f, 3);
;         acc[8 * m + 0] += ci * e0[0]; acc[8 * m + 1] += ci * e0[1]; acc[8 * m + 2] += ci * e1[0]; acc[8 * m + 3] += ci * e1[1];
;         acc[8 * m + 4] += ci * e2[0]; acc[8 * m + 5] += ci * e2[1]; acc[8 * m + 6] += ci * e3[0]; acc[8 * m + 7] += ci * e3[1];
;       }
;     }
;   };
	v_pk_fma_f32 v[68:69], v[50:51], v[100:101], v[68:69] op_sel:[1,0,0] op_sel_hi:[1,1,1]
	v_pk_fma_f32 v[70:71], v[50:51], v[102:103], v[70:71] op_sel:[1,0,0] op_sel_hi:[1,1,1]
	v_pk_fma_f32 v[72:73], v[50:51], v[104:105], v[72:73] op_sel:[1,0,0] op_sel_hi:[1,1,1]
	v_cvt_scalef32_pk_f32_fp4 v[98:99], v213, 1.0
	v_cvt_scalef32_pk_f32_fp4 v[100:101], v213, 1.0 op_sel:[1,0,0]
	v_cvt_scalef32_pk_f32_fp4 v[102:103], v213, 1.0 op_sel:[0,1,0]
	v_cvt_scalef32_pk_f32_fp4 v[104:105], v213, 1.0 op_sel:[1,1,0]
	v_pk_fma_f32 v[74:75], v[50:51], v[98:99], v[74:75] op_sel:[1,0,0] op_sel_hi:[1,1,1]
	v_pk_fma_f32 v[76:77], v[50:51], v[100:101], v[76:77] op_sel:[1,0,0] op_sel_hi:[1,1,1]
	v_pk_fma_f32 v[78:79], v[50:51], v[102:103], v[78:79] op_sel:[1,0,0] op_sel_hi:[1,1,1]
	v_pk_fma_f32 v[80:81], v[50:51], v[104:105], v[80:81] op_sel:[1,0,0] op_sel_hi:[1,1,1]
	v_cvt_scalef32_pk_f32_fp4 v[98:99], v214, 1.0
	v_cvt_scalef32_pk_f32_fp4 v[100:101], v214, 1.0 op_sel:[1,0,0]
	v_cvt_scalef32_pk_f32_fp4 v[102:103], v214, 1.0 op_sel:[0,1,0]
	v_cvt_scalef32_pk_f32_fp4 v[104:105], v214, 1.0 op_sel:[1,1,0]
	v_pk_fma_f32 v[82:83], v[50:51], v[98:99], v[82:83] op_sel:[1,0,0] op_sel_hi:[1,1,1]
	v_pk_fma_f32 v[84:85], v[50:51], v[100:101], v[84:85] op_sel:[1,0,0] op_sel_hi:[1,1,1]
	v_pk_fma_f32 v[86:87], v[50:51], v[102:103], v[86:87] op_sel:[1,0,0] op_sel_hi:[1,1,1]
	v_pk_fma_f32 v[88:89], v[50:51], v[104:105], v[88:89] op_sel:[1,0,0] op_sel_hi:[1,1,1]
	v_cvt_scalef32_pk_f32_fp4 v[98:99], v215, 1.0
	v_cvt_scalef32_pk_f32_fp4 v[100:101], v215, 1.0 op_sel:[1,0,0]
	v_cvt_scalef32_pk_f32_fp4 v[102:103], v215, 1.0 op_sel:[0,1,0]
	v_cvt_scalef32_pk_f32_fp4 v[104:105], v215, 1.0 op_sel:[1,1,0]
	v_pk_fma_f32 v[90:91], v[50:51], v[98:99], v[90:91] op_sel:[1,0,0] op_sel_hi:[1,1,1]
	v_pk_fma_f32 v[92:93], v[50:51], v[100:101], v[92:93] op_sel:[1,0,0] op_sel_hi:[1,1,1]
	v_pk_fma_f32 v[94:95], v[50:51], v[102:103], v[94:95] op_sel:[1,0,0] op_sel_hi:[1,1,1]
	v_pk_fma_f32 v[96:97], v[50:51], v[104:105], v[96:97] op_sel:[1,0,0] op_sel_hi:[1,1,1]
	v_cvt_scalef32_pk_f32_fp4 v[98:99], v216, 1.0
	v_cvt_scalef32_pk_f32_fp4 v[100:101], v216, 1.0 op_sel:[1,0,0]
	v_cvt_scalef32_pk_f32_fp4 v[102:103], v216, 1.0 op_sel:[0,1,0]
	v_cvt_scalef32_pk_f32_fp4 v[104:105], v216, 1.0 op_sel:[1,1,0]
	v_pk_fma_f32 v[66:67], v[52:53], v[98:99], v[66:67] op_sel_hi:[0,1,1]
	v_pk_fma_f32 v[68:69], v[52:53], v[100:101], v[68:69] op_sel_hi:[0,1,1]
	v_pk_fma_f32 v[70:71], v[52:53], v[102:103], v[70:71] op_sel_hi:[0,1,1]
	v_pk_fma_f32 v[72:73], v[52:53], v[104:105], v[72:73] op_sel_hi:[0,1,1]
	v_cvt_scalef32_pk_f32_fp4 v[98:99], v217, 1.0
	v_cvt_scalef32_pk_f32_fp4 v[100:101], v217, 1.0 op_sel:[1,0,0]
	v_cvt_scalef32_pk_f32_fp4 v[102:103], v217, 1.0 op_sel:[0,1,0]
	v_cvt_scalef32_pk_f32_fp4 v[104:105], v217, 1.0 op_sel:[1,1,0]
	v_pk_fma_f32 v[74:75], v[52:53], v[98:99], v[74:75] op_sel_hi:[0,1,1]
	v_pk_fma_f32 v[76:77], v[52:53], v[100:101], v[76:77] op_sel_hi:[0,1,1]
	v_pk_fma_f32 v[78:79], v[52:53], v[102:103], v[78:79] op_sel_hi:[0,1,1]
	v_pk_fma_f32 v[80:81], v[52:53], v[104:105], v[80:81] op_sel_hi:[0,1,1]
	v_cvt_scalef32_pk_f32_fp4 v[98:99], v218, 1.0
	v_cvt_scalef32_pk_f32_fp4 v[100:101], v218, 1.0 op_sel:[1,0,0]
	v_cvt_scalef32_pk_f32_fp4 v[102:103], v218, 1.0 op_sel:[0,1,0]
	v_cvt_scalef32_pk_f32_fp4 v[104:105], v218, 1.0 op_sel:[1,1,0]
	v_pk_fma_f32 v[82:83], v[52:53], v[98:99], v[82:83] op_sel_hi:[0,1,1]
	v_pk_fma_f32 v[84:85], v[52:53], v[100:101], v[84:85] op_sel_hi:[0,1,1]
	v_pk_fma_f32 v[86:87], v[52:53], v[102:103], v[86:87] op_sel_hi:[0,1,1]
	v_pk_fma_f32 v[88:89], v[52:53], v[104:105], v[88:89] op_sel_hi:[0,1,1]
	v_cvt_scalef32_pk_f32_fp4 v[98:99], v219, 1.0
	v_cvt_scalef32_pk_f32_fp4 v[100:101], v219, 1.0 op_sel:[1,0,0]
	v_cvt_scalef32_pk_f32_fp4 v[102:103], v219, 1.0 op_sel:[0,1,0]
	v_cvt_scalef32_pk_f32_fp4 v[104:105], v219, 1.0 op_sel:[1,1,0]
	v_pk_fma_f32 v[90:91], v[52:53], v[98:99], v[90:91] op_sel_hi:[0,1,1]
	v_pk_fma_f32 v[92:93], v[52:53], v[100:101], v[92:93] op_sel_hi:[0,1,1]
	v_pk_fma_f32 v[94:95], v[52:53], v[102:103], v[94:95] op_sel_hi:[0,1,1]
	v_pk_fma_f32 v[96:97], v[52:53], v[104:105], v[96:97] op_sel_hi:[0,1,1]
	v_cvt_scalef32_pk_f32_fp4 v[98:99], v220, 1.0
	v_cvt_scalef32_pk_f32_fp4 v[100:101], v220, 1.0 op_sel:[1,0,0]
	v_cvt_scalef32_pk_f32_fp4 v[102:103], v220, 1.0 op_sel:[0,1,0]
	v_cvt_scalef32_pk_f32_fp4 v[104:105], v220, 1.0 op_sel:[1,1,0]
	v_pk_fma_f32 v[66:67], v[52:53], v[98:99], v[66:67] op_sel:[1,0,0] op_sel_hi:[1,1,1]
	v_pk_fma_f32 v[68:69], v[52:53], v[100:101], v[68:69] op_sel:[1,0,0] op_sel_hi:[1,1,1]
	v_pk_fma_f32 v[70:71], v[52:53], v[102:103], v[70:71] op_sel:[1,0,0] op_sel_hi:[1,1,1]
	v_pk_fma_f32 v[72:73], v[52:53], v[104:105], v[72:73] op_sel:[1,0,0] op_sel_hi:[1,1,1]
	v_cvt_scalef32_pk_f32_fp4 v[98:99], v221, 1.0
	v_cvt_scalef32_pk_f32_fp4 v[100:101], v221, 1.0 op_sel:[1,0,0]
	v_cvt_scalef32_pk_f32_fp4 v[102:103], v221, 1.0 op_sel:[0,1,0]
	v_cvt_scalef32_pk_f32_fp4 v[104:105], v221, 1.0 op_sel:[1,1,0]
	v_pk_fma_f32 v[74:75], v[52:53], v[98:99], v[74:75] op_sel:[1,0,0] op_sel_hi:[1,1,1]
	v_pk_fma_f32 v[76:77], v[52:53], v[100:101], v[76:77] op_sel:[1,0,0] op_sel_hi:[1,1,1]
	v_pk_fma_f32 v[78:79], v[52:53], v[102:103], v[78:79] op_sel:[1,0,0] op_sel_hi:[1,1,1]
	v_pk_fma_f32 v[80:81], v[52:53], v[104:105], v[80:81] op_sel:[1,0,0] op_sel_hi:[1,1,1]
	v_cvt_scalef32_pk_f32_fp4 v[98:99], v222, 1.0
	v_cvt_scalef32_pk_f32_fp4 v[100:101], v222, 1.0 op_sel:[1,0,0]
	v_cvt_scalef32_pk_f32_fp4 v[102:103], v222, 1.0 op_sel:[0,1,0]
	v_cvt_scalef32_pk_f32_fp4 v[104:105], v222, 1.0 op_sel:[1,1,0]
	v_pk_fma_f32 v[82:83], v[52:53], v[98:99], v[82:83] op_sel:[1,0,0] op_sel_hi:[1,1,1]
; __device__ __forceinline__ void phase_peer_v(const Params& p, int layer, int xs, int wid0, int wstride, bool last, char* smraw) {
;     ...
;   auto half_fma = [&](const u32x4 (&q)[8], const f32x4& c0, const f32x4& c1) {
; #pragma unroll
;     for (int i = 0; i < 8; ++i) {
;       const float ci = i < 4 ? c0[i & 3] : c1[i & 3];
; #pragma unroll
;       for (int m = 0; m < 4; ++m) {
;         unsigned dw = q[i][m];
;         asm volatile("" : "+v"(dw) : "v"(acc[(8 * m + 31) & 31]));
;         const f32x2 e0 = __builtin_amdgcn_cvt_scalef32_pk_f32_fp4(dw, 1.0f, 0), e1 = __builtin_amdgcn_cvt_scalef32_pk_f32_fp4(dw, 1.0f, 1);
;         const f32x2 e2 = __builtin_amdgcn_cvt_scalef32_pk_f32_fp4(dw, 1.0f, 2), e3 = __builtin_amdgcn_cvt_scalef32_pk_f32_fp4(dw, 1.0f, 3);
;         acc[8 * m + 0] += ci * e0[0]; acc[8 * m + 1] += ci * e0[1]; acc[8 * m + 2] += ci * e1[0]; acc[8 * m + 3] += ci * e1[1];
;         acc[8 * m + 4] += ci * e2[0]; acc[8 * m + 5] += ci * e2[1]; acc[8 * m + 6] += ci * e3[0]; acc[8 * m + 7] += ci * e3[1];
;       }
;     }
;   };
	v_pk_fma_f32 v[84:85], v[52:53], v[100:101], v[84:85] op_sel:[1,0,0] op_sel_hi:[1,1,1]
	v_pk_fma_f32 v[86:87], v[52:53], v[102:103], v[86:87] op_sel:[1,0,0] op_sel_hi:[1,1,1]
	v_pk_fma_f32 v[88:89], v[52:53], v[104:105], v[88:89] op_sel:[1,0,0] op_sel_hi:[1,1,1]
	v_cvt_scalef32_pk_f32_fp4 v[98:99], v223, 1.0
	v_cvt_scalef32_pk_f32_fp4 v[100:101], v223, 1.0 op_sel:[1,0,0]
	v_cvt_scalef32_pk_f32_fp4 v[102:103], v223, 1.0 op_sel:[0,1,0]
	v_cvt_scalef32_pk_f32_fp4 v[104:105], v223, 1.0 op_sel:[1,1,0]
	v_pk_fma_f32 v[90:91], v[52:53], v[98:99], v[90:91] op_sel:[1,0,0] op_sel_hi:[1,1,1]
	v_pk_fma_f32 v[92:93], v[52:53], v[100:101], v[92:93] op_sel:[1,0,0] op_sel_hi:[1,1,1]
	v_pk_fma_f32 v[94:95], v[52:53], v[102:103], v[94:95] op_sel:[1,0,0] op_sel_hi:[1,1,1]
	v_pk_fma_f32 v[96:97], v[52:53], v[104:105], v[96:97] op_sel:[1,0,0] op_sel_hi:[1,1,1]
	v_cvt_scalef32_pk_f32_fp4 v[98:99], v224, 1.0
	v_cvt_scalef32_pk_f32_fp4 v[100:101], v224, 1.0 op_sel:[1,0,0]
	v_cvt_scalef32_pk_f32_fp4 v[102:103], v224, 1.0 op_sel:[0,1,0]
	v_cvt_scalef32_pk_f32_fp4 v[104:105], v224, 1.0 op_sel:[1,1,0]
	v_pk_fma_f32 v[66:67], v[54:55], v[98:99], v[66:67] op_sel_hi:[0,1,1]
	v_pk_fma_f32 v[68:69], v[54:55], v[100:101], v[68:69] op_sel_hi:[0,1,1]
	v_pk_fma_f32 v[70:71], v[54:55], v[102:103], v[70:71] op_sel_hi:[0,1,1]
	v_pk_fma_f32 v[72:73], v[54:55], v[104:105], v[72:73] op_sel_hi:[0,1,1]
	v_cvt_scalef32_pk_f32_fp4 v[98:99], v225, 1.0
	v_cvt_scalef32_pk_f32_fp4 v[100:101], v225, 1.0 op_sel:[1,0,0]
	v_cvt_scalef32_pk_f32_fp4 v[102:103], v225, 1.0 op_sel:[0,1,0]
	v_cvt_scalef32_pk_f32_fp4 v[104:105], v225, 1.0 op_sel:[1,1,0]
	v_pk_fma_f32 v[74:75], v[54:55], v[98:99], v[74:75] op_sel_hi:[0,1,1]
	v_pk_fma_f32 v[76:77], v[54:55], v[100:101], v[76:77] op_sel_hi:[0,1,1]
	v_pk_fma_f32 v[78:79], v[54:55], v[102:103], v[78:79] op_sel_hi:[0,1,1]
	v_pk_fma_f32 v[80:81], v[54:55], v[104:105], v[80:81] op_sel_hi:[0,1,1]
	v_cvt_scalef32_pk_f32_fp4 v[98:99], v226, 1.0
	v_cvt_scalef32_pk_f32_fp4 v[100:101], v226, 1.0 op_sel:[1,0,0]
	v_cvt_scalef32_pk_f32_fp4 v[102:103], v226, 1.0 op_sel:[0,1,0]
	v_cvt_scalef32_pk_f32_fp4 v[104:105], v226, 1.0 op_sel:[1,1,0]
	v_pk_fma_f32 v[82:83], v[54:55], v[98:99], v[82:83] op_sel_hi:[0,1,1]
	v_pk_fma_f32 v[84:85], v[54:55], v[100:101], v[84:85] op_sel_hi:[0,1,1]
	v_pk_fma_f32 v[86:87], v[54:55], v[102:103], v[86:87] op_sel_hi:[0,1,1]
	v_pk_fma_f32 v[88:89], v[54:55], v[104:105], v[88:89] op_sel_hi:[0,1,1]
	v_cvt_scalef32_pk_f32_fp4 v[98:99], v227, 1.0
	v_cvt_scalef32_pk_f32_fp4 v[100:101], v227, 1.0 op_sel:[1,0,0]
	v_cvt_scalef32_pk_f32_fp4 v[102:103], v227, 1.0 op_sel:[0,1,0]
	v_cvt_scalef32_pk_f32_fp4 v[104:105], v227, 1.0 op_sel:[1,1,0]
	v_pk_fma_f32 v[90:91], v[54:55], v[98:99], v[90:91] op_sel_hi:[0,1,1]
	v_pk_fma_f32 v[92:93], v[54:55], v[100:101], v[92:93] op_sel_hi:[0,1,1]
	v_pk_fma_f32 v[94:95], v[54:55], v[102:103], v[94:95] op_sel_hi:[0,1,1]
	v_pk_fma_f32 v[96:97], v[54:55], v[104:105], v[96:97] op_sel_hi:[0,1,1]
	v_cvt_scalef32_pk_f32_fp4 v[98:99], v228, 1.0
	v_cvt_scalef32_pk_f32_fp4 v[100:101], v228, 1.0 op_sel:[1,0,0]
	v_cvt_scalef32_pk_f32_fp4 v[102:103], v228, 1.0 op_sel:[0,1,0]
	v_cvt_scalef32_pk_f32_fp4 v[104:105], v228, 1.0 op_sel:[1,1,0]
	v_pk_fma_f32 v[66:67], v[54:55], v[98:99], v[66:67] op_sel:[1,0,0] op_sel_hi:[1,1,1]
	v_pk_fma_f32 v[68:69], v[54:55], v[100:101], v[68:69] op_sel:[1,0,0] op_sel_hi:[1,1,1]
	v_pk_fma_f32 v[70:71], v[54:55], v[102:103], v[70:71] op_sel:[1,0,0] op_sel_hi:[1,1,1]
	v_pk_fma_f32 v[72:73], v[54:55], v[104:105], v[72:73] op_sel:[1,0,0] op_sel_hi:[1,1,1]
	v_cvt_scalef32_pk_f32_fp4 v[98:99], v229, 1.0
	v_cvt_scalef32_pk_f32_fp4 v[100:101], v229, 1.0 op_sel:[1,0,0]
	v_cvt_scalef32_pk_f32_fp4 v[102:103], v229, 1.0 op_sel:[0,1,0]
	v_cvt_scalef32_pk_f32_fp4 v[104:105], v229, 1.0 op_sel:[1,1,0]
	v_pk_fma_f32 v[74:75], v[54:55], v[98:99], v[74:75] op_sel:[1,0,0] op_sel_hi:[1,1,1]
	v_pk_fma_f32 v[76:77], v[54:55], v[100:101], v[76:77] op_sel:[1,0,0] op_sel_hi:[1,1,1]
	v_pk_fma_f32 v[78:79], v[54:55], v[102:103], v[78:79] op_sel:[1,0,0] op_sel_hi:[1,1,1]
	v_pk_fma_f32 v[80:81], v[54:55], v[104:105], v[80:81] op_sel:[1,0,0] op_sel_hi:[1,1,1]
	v_cvt_scalef32_pk_f32_fp4 v[98:99], v230, 1.0
	v_cvt_scalef32_pk_f32_fp4 v[100:101], v230, 1.0 op_sel:[1,0,0]
	v_cvt_scalef32_pk_f32_fp4 v[102:103], v230, 1.0 op_sel:[0,1,0]
	v_cvt_scalef32_pk_f32_fp4 v[104:105], v230, 1.0 op_sel:[1,1,0]
	v_pk_fma_f32 v[82:83], v[54:55], v[98:99], v[82:83] op_sel:[1,0,0] op_sel_hi:[1,1,1]
	v_pk_fma_f32 v[84:85], v[54:55], v[100:101], v[84:85] op_sel:[1,0,0] op_sel_hi:[1,1,1]
	v_pk_fma_f32 v[86:87], v[54:55], v[102:103], v[86:87] op_sel:[1,0,0] op_sel_hi:[1,1,1]
	v_pk_fma_f32 v[88:89], v[54:55], v[104:105], v[88:89] op_sel:[1,0,0] op_sel_hi:[1,1,1]
	v_cvt_scalef32_pk_f32_fp4 v[98:99], v231, 1.0
	v_cvt_scalef32_pk_f32_fp4 v[100:101], v231, 1.0 op_sel:[1,0,0]
	v_cvt_scalef32_pk_f32_fp4 v[102:103], v231, 1.0 op_sel:[0,1,0]
	v_cvt_scalef32_pk_f32_fp4 v[104:105], v231, 1.0 op_sel:[1,1,0]
	v_pk_fma_f32 v[90:91], v[54:55], v[98:99], v[90:91] op_sel:[1,0,0] op_sel_hi:[1,1,1]
	v_pk_fma_f32 v[92:93], v[54:55], v[100:101], v[92:93] op_sel:[1,0,0] op_sel_hi:[1,1,1]
	v_pk_fma_f32 v[94:95], v[54:55], v[102:103], v[94:95] op_sel:[1,0,0] op_sel_hi:[1,1,1]
	v_pk_fma_f32 v[96:97], v[54:55], v[104:105], v[96:97] op_sel:[1,0,0] op_sel_hi:[1,1,1]
	v_cvt_scalef32_pk_f32_fp4 v[98:99], v232, 1.0
	v_cvt_scalef32_pk_f32_fp4 v[100:101], v232, 1.0 op_sel:[1,0,0]
	v_cvt_scalef32_pk_f32_fp4 v[102:103], v232, 1.0 op_sel:[0,1,0]
	v_cvt_scalef32_pk_f32_fp4 v[104:105], v232, 1.0 op_sel:[1,1,0]
	v_pk_fma_f32 v[66:67], v[56:57], v[98:99], v[66:67] op_sel_hi:[0,1,1]
; __device__ __forceinline__ void phase_peer_v(const Params& p, int layer, int xs, int wid0, int wstride, bool last, char* smraw) {
;     ...
;   auto half_fma = [&](const u32x4 (&q)[8], const f32x4& c0, const f32x4& c1) {
; #pragma unroll
;     for (int i = 0; i < 8; ++i) {
;       const float ci = i < 4 ? c0[i & 3] : c1[i & 3];
; #pragma unroll
;       for (int m = 0; m < 4; ++m) {
;         unsigned dw = q[i][m];
;         asm volatile("" : "+v"(dw) : "v"(acc[(8 * m + 31) & 31]));
;         const f32x2 e0 = __builtin_amdgcn_cvt_scalef32_pk_f32_fp4(dw, 1.0f, 0), e1 = __builtin_amdgcn_cvt_scalef32_pk_f32_fp4(dw, 1.0f, 1);
;         const f32x2 e2 = __builtin_amdgcn_cvt_scalef32_pk_f32_fp4(dw, 1.0f, 2), e3 = __builtin_amdgcn_cvt_scalef32_pk_f32_fp4(dw, 1.0f, 3);
;         acc[8 * m + 0] += ci * e0[0]; acc[8 * m + 1] += ci * e0[1]; acc[8 * m + 2] += ci * e1[0]; acc[8 * m + 3] += ci * e1[1];
;         acc[8 * m + 4] += ci * e2[0]; acc[8 * m + 5] += ci * e2[1]; acc[8 * m + 6] += ci * e3[0]; acc[8 * m + 7] += ci * e3[1];
;       }
;     }
;   };
;     ...
;     half_fma(qA, c2, c3);
; #pragma unroll
;     for (int q4 = 0; q4 < 8; ++q4) *(f32x4*)(red + g * 256 + j * 32 + q4 * 4) = f32x4{acc[q4 * 4], acc[q4 * 4 + 1], acc[q4 * 4 + 2], acc[q4 * 4 + 3]};
;     __builtin_amdgcn_fence(__ATOMIC_RELEASE, "wavefront");
;     __builtin_amdgcn_wave_barrier();
;     __builtin_amdgcn_fence(__ATOMIC_ACQUIRE, "wavefront");
;     f32x4 r = {0.f, 0.f, 0.f, 0.f};
; #pragma unroll
;     for (int gg = 0; gg < 8; ++gg) { f32x4 v = *(const f32x4*)(red + gg * 256 + 4 * l); r += v; }
;     asm volatile("" ::: "memory");
;     __builtin_amdgcn_wave_barrier();
;     {
;       hv += r;
;       *(f32x4*)hq = hv;
;       if (!last) { u32x2 o; o[0] = cvtpk(hv[0], hv[1]); o[1] = cvtpk(hv[2], hv[3]); *(u32x2*)((char*)p.hb + ((unsigned)t * 2048u + (unsigned)(sl * 512 + l * 8))) = o; }
;     }
;     tt = tn;
;   }
	v_pk_fma_f32 v[68:69], v[56:57], v[100:101], v[68:69] op_sel_hi:[0,1,1]
	v_pk_fma_f32 v[70:71], v[56:57], v[102:103], v[70:71] op_sel_hi:[0,1,1]
	v_pk_fma_f32 v[72:73], v[56:57], v[104:105], v[72:73] op_sel_hi:[0,1,1]
	v_cvt_scalef32_pk_f32_fp4 v[98:99], v233, 1.0
	v_cvt_scalef32_pk_f32_fp4 v[100:101], v233, 1.0 op_sel:[1,0,0]
	v_cvt_scalef32_pk_f32_fp4 v[102:103], v233, 1.0 op_sel:[0,1,0]
	v_cvt_scalef32_pk_f32_fp4 v[104:105], v233, 1.0 op_sel:[1,1,0]
	v_pk_fma_f32 v[74:75], v[56:57], v[98:99], v[74:75] op_sel_hi:[0,1,1]
	v_pk_fma_f32 v[76:77], v[56:57], v[100:101], v[76:77] op_sel_hi:[0,1,1]
	v_pk_fma_f32 v[78:79], v[56:57], v[102:103], v[78:79] op_sel_hi:[0,1,1]
	v_pk_fma_f32 v[80:81], v[56:57], v[104:105], v[80:81] op_sel_hi:[0,1,1]
	v_cvt_scalef32_pk_f32_fp4 v[98:99], v234, 1.0
	v_cvt_scalef32_pk_f32_fp4 v[100:101], v234, 1.0 op_sel:[1,0,0]
	v_cvt_scalef32_pk_f32_fp4 v[102:103], v234, 1.0 op_sel:[0,1,0]
	v_cvt_scalef32_pk_f32_fp4 v[104:105], v234, 1.0 op_sel:[1,1,0]
	v_pk_fma_f32 v[82:83], v[56:57], v[98:99], v[82:83] op_sel_hi:[0,1,1]
	v_pk_fma_f32 v[84:85], v[56:57], v[100:101], v[84:85] op_sel_hi:[0,1,1]
	v_pk_fma_f32 v[86:87], v[56:57], v[102:103], v[86:87] op_sel_hi:[0,1,1]
	v_pk_fma_f32 v[88:89], v[56:57], v[104:105], v[88:89] op_sel_hi:[0,1,1]
	v_cvt_scalef32_pk_f32_fp4 v[98:99], v235, 1.0
	v_cvt_scalef32_pk_f32_fp4 v[100:101], v235, 1.0 op_sel:[1,0,0]
	v_cvt_scalef32_pk_f32_fp4 v[102:103], v235, 1.0 op_sel:[0,1,0]
	v_cvt_scalef32_pk_f32_fp4 v[104:105], v235, 1.0 op_sel:[1,1,0]
	v_pk_fma_f32 v[90:91], v[56:57], v[98:99], v[90:91] op_sel_hi:[0,1,1]
	v_pk_fma_f32 v[92:93], v[56:57], v[100:101], v[92:93] op_sel_hi:[0,1,1]
	v_pk_fma_f32 v[94:95], v[56:57], v[102:103], v[94:95] op_sel_hi:[0,1,1]
	v_pk_fma_f32 v[96:97], v[56:57], v[104:105], v[96:97] op_sel_hi:[0,1,1]
	v_cvt_scalef32_pk_f32_fp4 v[98:99], v236, 1.0
	v_cvt_scalef32_pk_f32_fp4 v[100:101], v236, 1.0 op_sel:[1,0,0]
	v_cvt_scalef32_pk_f32_fp4 v[102:103], v236, 1.0 op_sel:[0,1,0]
	v_cvt_scalef32_pk_f32_fp4 v[104:105], v236, 1.0 op_sel:[1,1,0]
	v_pk_fma_f32 v[66:67], v[56:57], v[98:99], v[66:67] op_sel:[1,0,0] op_sel_hi:[1,1,1]
	v_pk_fma_f32 v[68:69], v[56:57], v[100:101], v[68:69] op_sel:[1,0,0] op_sel_hi:[1,1,1]
	v_pk_fma_f32 v[70:71], v[56:57], v[102:103], v[70:71] op_sel:[1,0,0] op_sel_hi:[1,1,1]
	v_pk_fma_f32 v[72:73], v[56:57], v[104:105], v[72:73] op_sel:[1,0,0] op_sel_hi:[1,1,1]
	v_cvt_scalef32_pk_f32_fp4 v[98:99], v237, 1.0
	v_cvt_scalef32_pk_f32_fp4 v[100:101], v237, 1.0 op_sel:[1,0,0]
	v_cvt_scalef32_pk_f32_fp4 v[102:103], v237, 1.0 op_sel:[0,1,0]
	v_cvt_scalef32_pk_f32_fp4 v[104:105], v237, 1.0 op_sel:[1,1,0]
	v_pk_fma_f32 v[74:75], v[56:57], v[98:99], v[74:75] op_sel:[1,0,0] op_sel_hi:[1,1,1]
	v_pk_fma_f32 v[76:77], v[56:57], v[100:101], v[76:77] op_sel:[1,0,0] op_sel_hi:[1,1,1]
	v_pk_fma_f32 v[78:79], v[56:57], v[102:103], v[78:79] op_sel:[1,0,0] op_sel_hi:[1,1,1]
	v_pk_fma_f32 v[80:81], v[56:57], v[104:105], v[80:81] op_sel:[1,0,0] op_sel_hi:[1,1,1]
	v_cvt_scalef32_pk_f32_fp4 v[98:99], v238, 1.0
	v_cvt_scalef32_pk_f32_fp4 v[100:101], v238, 1.0 op_sel:[1,0,0]
	v_cvt_scalef32_pk_f32_fp4 v[102:103], v238, 1.0 op_sel:[0,1,0]
	v_cvt_scalef32_pk_f32_fp4 v[104:105], v238, 1.0 op_sel:[1,1,0]
	v_pk_fma_f32 v[82:83], v[56:57], v[98:99], v[82:83] op_sel:[1,0,0] op_sel_hi:[1,1,1]
	v_pk_fma_f32 v[84:85], v[56:57], v[100:101], v[84:85] op_sel:[1,0,0] op_sel_hi:[1,1,1]
	v_pk_fma_f32 v[86:87], v[56:57], v[102:103], v[86:87] op_sel:[1,0,0] op_sel_hi:[1,1,1]
	v_pk_fma_f32 v[88:89], v[56:57], v[104:105], v[88:89] op_sel:[1,0,0] op_sel_hi:[1,1,1]
	v_cvt_scalef32_pk_f32_fp4 v[98:99], v239, 1.0
	v_cvt_scalef32_pk_f32_fp4 v[100:101], v239, 1.0 op_sel:[1,0,0]
	v_cvt_scalef32_pk_f32_fp4 v[102:103], v239, 1.0 op_sel:[0,1,0]
	v_cvt_scalef32_pk_f32_fp4 v[104:105], v239, 1.0 op_sel:[1,1,0]
	v_pk_fma_f32 v[90:91], v[56:57], v[98:99], v[90:91] op_sel:[1,0,0] op_sel_hi:[1,1,1]
	v_pk_fma_f32 v[92:93], v[56:57], v[100:101], v[92:93] op_sel:[1,0,0] op_sel_hi:[1,1,1]
	v_pk_fma_f32 v[94:95], v[56:57], v[102:103], v[94:95] op_sel:[1,0,0] op_sel_hi:[1,1,1]
	v_pk_fma_f32 v[96:97], v[56:57], v[104:105], v[96:97] op_sel:[1,0,0] op_sel_hi:[1,1,1]
	ds_write_b128 v3, v[66:69]
	ds_write_b128 v3, v[70:73] offset:16
	ds_write_b128 v3, v[74:77] offset:32
	ds_write_b128 v3, v[78:81] offset:48
	ds_write_b128 v3, v[82:85] offset:64
	ds_write_b128 v3, v[86:89] offset:80
	ds_write_b128 v3, v[90:93] offset:96
	ds_write_b128 v3, v[94:97] offset:112
	s_waitcnt lgkmcnt(0)
	ds_read_b128 v[66:69], v4
	ds_read_b128 v[70:73], v4 offset:1024
	ds_read_b128 v[74:77], v4 offset:2048
	ds_read_b128 v[78:81], v4 offset:3072
	ds_read_b128 v[82:85], v4 offset:4096
	ds_read_b128 v[86:89], v4 offset:5120
	ds_read_b128 v[90:93], v4 offset:6144
	ds_read_b128 v[94:97], v4 offset:7168
	s_waitcnt lgkmcnt(6)
	v_pk_add_f32 v[66:67], v[66:67], v[70:71]
	v_pk_add_f32 v[68:69], v[68:69], v[72:73]
	s_waitcnt lgkmcnt(5)
	v_pk_add_f32 v[66:67], v[66:67], v[74:75]
	v_pk_add_f32 v[68:69], v[68:69], v[76:77]
	s_waitcnt lgkmcnt(4)
	v_pk_add_f32 v[66:67], v[66:67], v[78:79]
	v_pk_add_f32 v[68:69], v[68:69], v[80:81]
	s_waitcnt lgkmcnt(3)
	v_pk_add_f32 v[66:67], v[66:67], v[82:83]
	v_pk_add_f32 v[68:69], v[68:69], v[84:85]
	s_waitcnt lgkmcnt(2)
	v_pk_add_f32 v[66:67], v[66:67], v[86:87]
	v_pk_add_f32 v[68:69], v[68:69], v[88:89]
	s_waitcnt lgkmcnt(1)
	v_pk_add_f32 v[66:67], v[66:67], v[90:91]
	v_pk_add_f32 v[68:69], v[68:69], v[92:93]
	s_waitcnt lgkmcnt(0)
	v_pk_add_f32 v[66:67], v[66:67], v[94:95]
	v_pk_add_f32 v[68:69], v[68:69], v[96:97]
	v_pk_add_f32 v[62:63], v[62:63], v[66:67]
	v_pk_add_f32 v[64:65], v[64:65], v[68:69]
	global_store_dwordx4 v0, v[62:65], s[46:47]
	s_mov_b32 s36, s51
	s_cmp_lt_u32 s36, s38
	s_cbranch_scc1 .Lmy_pv1_bodyA
.Lmy_pv1_done:
.LBB0_1386:
	s_endpgm
